# v21 plus: context-row split-K partial loads issued up front in the FFN adaLN phase, phase-0 modulation-table k-loop unrolled x2 with the next group's loads in flight, LDS-DMA m0 write moved ahead of t
# speedup vs baseline: 1.0194x; 1.0006x over previous
.LBB0_39:
	s_mul_hi_i32 s2, s29, 0x38e38e39
	s_lshr_b32 s3, s2, 31
	s_ashr_i32 s11, s2, 5
	s_add_i32 s11, s11, s3
	s_mul_i32 s2, s11, 0x90
	s_sub_i32 s2, s29, s2
	s_lshl_b32 s10, s2, 6
	s_add_i32 s2, s29, 0x8f
	s_cmpk_lt_u32 s2, 0x11f
	s_cselect_b32 s2, 32, 0xa8
	s_cselect_b32 s9, 40, 0xb0
	s_add_u32 s2, s12, s2
	s_addc_u32 s3, s13, 0
	s_load_dwordx2 s[2:3], s[2:3], 0x0
	s_add_u32 s16, s12, s9
	s_addc_u32 s17, s13, 0
	s_load_dwordx2 s[16:17], s[16:17], 0x0
	v_or_b32_e32 v8, s10, v28
	s_waitcnt lgkmcnt(0)
	s_add_u32 s2, s2, s22
	v_ashrrev_i32_e32 v9, 31, v8
	s_addc_u32 s3, s3, s24
	v_lshl_add_u64 v[10:11], v[8:9], 2, s[2:3]
	s_mov_b32 s18, 0
	v_mov_b32_e32 v2, 0
	v_mov_b32_e32 v12, 0
	v_mov_b32_e32 v13, v3
	v_mov_b32_e32 v14, 0
	v_mov_b32_e32 v15, v3
	v_mov_b32_e32 v16, 0
	v_mov_b32_e32 v17, v3
	v_mov_b32_e32 v18, 0
	v_mov_b32_e32 v19, v3
	v_mov_b32_e32 v20, 0
	v_mov_b32_e32 v21, v3
	v_mov_b32_e32 v22, 0
	v_mov_b32_e32 v23, v3
	v_mov_b32_e32 v24, 0
	v_mov_b32_e32 v25, v3
	v_mov_b32_e32 v26, 0
	v_mov_b32_e32 v27, v3
	v_add_co_u32_e64 v30, s[2:3], s27, v10
	global_load_dword v102, v[10:11], off
	s_nop 0
	v_addc_co_u32_e64 v31, s[2:3], 0, v11, s[2:3]
	v_add_co_u32_e64 v34, s[2:3], s23, v10
	s_add_i32 s9, s25, s18
	s_nop 0
	v_addc_co_u32_e64 v35, s[2:3], 0, v11, s[2:3]
	v_add_co_u32_e64 v36, s[2:3], s26, v10
	v_mov_b32_e32 v29, s9
	s_nop 0
	v_addc_co_u32_e64 v37, s[2:3], 0, v11, s[2:3]
	global_load_dword v104, v[34:35], off
	global_load_dword v106, v[30:31], off
	global_load_dword v108, v[36:37], off
	v_lshl_add_u64 v[10:11], v[10:11], 0, s[4:5]
.LBB0_40:
	v_add_co_u32_e64 v30, s[2:3], s27, v10
	global_load_dword v110, v[10:11], off
	s_nop 0
	v_addc_co_u32_e64 v31, s[2:3], 0, v11, s[2:3]
	v_add_co_u32_e64 v34, s[2:3], s23, v10
	s_add_i32 s9, s25, s18
	s_nop 0
	v_addc_co_u32_e64 v35, s[2:3], 0, v11, s[2:3]
	v_add_co_u32_e64 v36, s[2:3], s26, v10
	v_mov_b32_e32 v29, s9
	s_nop 0
	v_addc_co_u32_e64 v37, s[2:3], 0, v11, s[2:3]
	global_load_dword v112, v[34:35], off
	global_load_dword v114, v[30:31], off
	global_load_dword v116, v[36:37], off
	v_lshl_add_u64 v[10:11], v[10:11], 0, s[4:5]
	s_add_i32 s2, s9, 0x10000
	ds_read_b128 v[34:37], v29
	ds_read_b128 v[38:41], v29 offset:4096
	ds_read_b128 v[42:45], v29 offset:8192
	ds_read_b128 v[46:49], v29 offset:12288
	ds_read_b128 v[50:53], v29 offset:16384
	ds_read_b128 v[54:57], v29 offset:20480
	ds_read_b128 v[58:61], v29 offset:24576
	ds_read_b128 v[62:65], v29 offset:28672
	ds_read_b128 v[66:69], v29 offset:32768
	ds_read_b128 v[70:73], v29 offset:36864
	ds_read_b128 v[74:77], v29 offset:40960
	ds_read_b128 v[78:81], v29 offset:45056
	ds_read_b128 v[82:85], v29 offset:49152
	ds_read_b128 v[86:89], v29 offset:53248
	ds_read_b128 v[90:93], v29 offset:57344
	ds_read_b128 v[94:97], v29 offset:61440
	v_mov_b32_e32 v29, s2
	ds_read_b128 v[98:101], v29
	s_waitcnt lgkmcnt(14)
	v_mov_b32_e32 v30, v42
	v_mov_b32_e32 v31, v38
	v_mov_b32_e32 v38, v43
	v_mov_b32_e32 v42, v44
	v_mov_b32_e32 v43, v40
	v_mov_b32_e32 v40, v45
	v_mov_b32_e32 v44, v34
	s_waitcnt lgkmcnt(13)
	v_mov_b32_e32 v45, v46
	v_mov_b32_e32 v46, v35
	v_mov_b32_e32 v34, v36
	v_mov_b32_e32 v35, v48
	v_mov_b32_e32 v48, v37
	s_waitcnt lgkmcnt(12)
	v_mov_b32_e32 v36, v50
	s_waitcnt lgkmcnt(11)
	v_mov_b32_e32 v37, v54
	v_mov_b32_e32 v54, v51
	v_mov_b32_e32 v50, v52
	v_mov_b32_e32 v51, v56
	v_mov_b32_e32 v56, v53
	s_waitcnt lgkmcnt(10)
	v_mov_b32_e32 v52, v58
	s_waitcnt lgkmcnt(9)
	v_mov_b32_e32 v53, v62
	v_mov_b32_e32 v62, v59
	v_mov_b32_e32 v58, v60
	v_mov_b32_e32 v59, v64
	v_mov_b32_e32 v64, v61
	s_waitcnt lgkmcnt(8)
	v_mov_b32_e32 v60, v66
	s_waitcnt lgkmcnt(7)
	v_mov_b32_e32 v61, v70
	v_mov_b32_e32 v70, v67
	v_mov_b32_e32 v66, v68
	v_mov_b32_e32 v67, v72
	v_mov_b32_e32 v72, v69
	s_waitcnt lgkmcnt(6)
	v_mov_b32_e32 v68, v74
	s_waitcnt lgkmcnt(5)
	v_mov_b32_e32 v69, v78
	v_mov_b32_e32 v78, v75
	v_mov_b32_e32 v74, v76
	v_mov_b32_e32 v75, v80
	v_mov_b32_e32 v80, v77
	s_waitcnt lgkmcnt(4)
	v_mov_b32_e32 v76, v82
	s_waitcnt lgkmcnt(3)
	v_mov_b32_e32 v77, v86
	v_mov_b32_e32 v86, v83
	v_mov_b32_e32 v82, v84
	v_mov_b32_e32 v83, v88
	v_mov_b32_e32 v88, v85
	s_waitcnt lgkmcnt(2)
	v_mov_b32_e32 v84, v90
	s_waitcnt lgkmcnt(1)
	v_mov_b32_e32 v85, v94
	v_mov_b32_e32 v94, v91
	v_mov_b32_e32 v90, v92
	v_mov_b32_e32 v91, v96
	s_add_i32 s18, s18, 16
	v_mov_b32_e32 v96, v93
	s_waitcnt vmcnt(7)
	v_pk_fma_f32 v[12:13], v[102:103], v[30:31], v[12:13] op_sel_hi:[0,1,1]
	v_pk_fma_f32 v[14:15], v[102:103], v[44:45], v[14:15] op_sel_hi:[0,1,1]
	v_pk_fma_f32 v[16:17], v[102:103], v[36:37], v[16:17] op_sel_hi:[0,1,1]
	v_pk_fma_f32 v[18:19], v[102:103], v[52:53], v[18:19] op_sel_hi:[0,1,1]
	v_pk_fma_f32 v[20:21], v[102:103], v[60:61], v[20:21] op_sel_hi:[0,1,1]
	v_pk_fma_f32 v[22:23], v[102:103], v[68:69], v[22:23] op_sel_hi:[0,1,1]
	v_pk_fma_f32 v[24:25], v[102:103], v[76:77], v[24:25] op_sel_hi:[0,1,1]
	v_pk_fma_f32 v[26:27], v[102:103], v[84:85], v[26:27] op_sel_hi:[0,1,1]
	s_waitcnt lgkmcnt(0)
	v_fmac_f32_e32 v2, v102, v98
	s_waitcnt vmcnt(6)
	v_pk_fma_f32 v[12:13], v[104:105], v[38:39], v[12:13] op_sel_hi:[0,1,1]
	v_pk_fma_f32 v[14:15], v[104:105], v[46:47], v[14:15] op_sel_hi:[0,1,1]
	v_pk_fma_f32 v[16:17], v[104:105], v[54:55], v[16:17] op_sel_hi:[0,1,1]
	v_pk_fma_f32 v[18:19], v[104:105], v[62:63], v[18:19] op_sel_hi:[0,1,1]
	v_pk_fma_f32 v[20:21], v[104:105], v[70:71], v[20:21] op_sel_hi:[0,1,1]
	v_pk_fma_f32 v[22:23], v[104:105], v[78:79], v[22:23] op_sel_hi:[0,1,1]
	v_pk_fma_f32 v[24:25], v[104:105], v[86:87], v[24:25] op_sel_hi:[0,1,1]
	v_pk_fma_f32 v[26:27], v[104:105], v[94:95], v[26:27] op_sel_hi:[0,1,1]
	v_fmac_f32_e32 v2, v104, v99
	s_waitcnt vmcnt(4)
	v_pk_fma_f32 v[12:13], v[108:109], v[42:43], v[12:13] op_sel_hi:[0,1,1]
	v_pk_fma_f32 v[14:15], v[108:109], v[34:35], v[14:15] op_sel_hi:[0,1,1]
	v_pk_fma_f32 v[16:17], v[108:109], v[50:51], v[16:17] op_sel_hi:[0,1,1]
	v_pk_fma_f32 v[18:19], v[108:109], v[58:59], v[18:19] op_sel_hi:[0,1,1]
	v_pk_fma_f32 v[20:21], v[108:109], v[66:67], v[20:21] op_sel_hi:[0,1,1]
	v_pk_fma_f32 v[22:23], v[108:109], v[74:75], v[22:23] op_sel_hi:[0,1,1]
	v_pk_fma_f32 v[24:25], v[108:109], v[82:83], v[24:25] op_sel_hi:[0,1,1]
	v_pk_fma_f32 v[26:27], v[108:109], v[90:91], v[26:27] op_sel_hi:[0,1,1]
	v_fmac_f32_e32 v2, v108, v100
	v_pk_fma_f32 v[12:13], v[106:107], v[40:41], v[12:13] op_sel_hi:[0,1,1]
	v_pk_fma_f32 v[14:15], v[106:107], v[48:49], v[14:15] op_sel_hi:[0,1,1]
	v_pk_fma_f32 v[16:17], v[106:107], v[56:57], v[16:17] op_sel_hi:[0,1,1]
	v_pk_fma_f32 v[18:19], v[106:107], v[64:65], v[18:19] op_sel_hi:[0,1,1]
	v_pk_fma_f32 v[20:21], v[106:107], v[72:73], v[20:21] op_sel_hi:[0,1,1]
	v_pk_fma_f32 v[22:23], v[106:107], v[80:81], v[22:23] op_sel_hi:[0,1,1]
	v_pk_fma_f32 v[24:25], v[106:107], v[88:89], v[24:25] op_sel_hi:[0,1,1]
	v_pk_fma_f32 v[26:27], v[106:107], v[96:97], v[26:27] op_sel_hi:[0,1,1]
	v_fmac_f32_e32 v2, v106, v101
	s_cmpk_eq_i32 s18, 0x1f0
	s_cselect_b32 s98, 0xfffdc000, 0
	s_cselect_b32 s99, -1, 0
	v_lshl_add_u64 v[10:11], v[10:11], 0, s[98:99]
	v_add_co_u32_e64 v30, s[2:3], s27, v10
	global_load_dword v102, v[10:11], off
	s_nop 0
	v_addc_co_u32_e64 v31, s[2:3], 0, v11, s[2:3]
	v_add_co_u32_e64 v34, s[2:3], s23, v10
	s_add_i32 s9, s25, s18
	s_nop 0
	v_addc_co_u32_e64 v35, s[2:3], 0, v11, s[2:3]
	v_add_co_u32_e64 v36, s[2:3], s26, v10
	v_mov_b32_e32 v29, s9
	s_nop 0
	v_addc_co_u32_e64 v37, s[2:3], 0, v11, s[2:3]
	global_load_dword v104, v[34:35], off
	global_load_dword v106, v[30:31], off
	global_load_dword v108, v[36:37], off
	v_lshl_add_u64 v[10:11], v[10:11], 0, s[4:5]
	s_add_i32 s2, s9, 0x10000
	ds_read_b128 v[34:37], v29
	ds_read_b128 v[38:41], v29 offset:4096
	ds_read_b128 v[42:45], v29 offset:8192
	ds_read_b128 v[46:49], v29 offset:12288
	ds_read_b128 v[50:53], v29 offset:16384
	ds_read_b128 v[54:57], v29 offset:20480
	ds_read_b128 v[58:61], v29 offset:24576
	ds_read_b128 v[62:65], v29 offset:28672
	ds_read_b128 v[66:69], v29 offset:32768
	ds_read_b128 v[70:73], v29 offset:36864
	ds_read_b128 v[74:77], v29 offset:40960
	ds_read_b128 v[78:81], v29 offset:45056
	ds_read_b128 v[82:85], v29 offset:49152
	ds_read_b128 v[86:89], v29 offset:53248
	ds_read_b128 v[90:93], v29 offset:57344
	ds_read_b128 v[94:97], v29 offset:61440
	v_mov_b32_e32 v29, s2
	ds_read_b128 v[98:101], v29
	s_waitcnt lgkmcnt(14)
	v_mov_b32_e32 v30, v42
	v_mov_b32_e32 v31, v38
	v_mov_b32_e32 v38, v43
	v_mov_b32_e32 v42, v44
	v_mov_b32_e32 v43, v40
	v_mov_b32_e32 v40, v45
	v_mov_b32_e32 v44, v34
	s_waitcnt lgkmcnt(13)
	v_mov_b32_e32 v45, v46
	v_mov_b32_e32 v46, v35
	v_mov_b32_e32 v34, v36
	v_mov_b32_e32 v35, v48
	v_mov_b32_e32 v48, v37
	s_waitcnt lgkmcnt(12)
	v_mov_b32_e32 v36, v50
	s_waitcnt lgkmcnt(11)
	v_mov_b32_e32 v37, v54
	v_mov_b32_e32 v54, v51
	v_mov_b32_e32 v50, v52
	v_mov_b32_e32 v51, v56
	v_mov_b32_e32 v56, v53
	s_waitcnt lgkmcnt(10)
	v_mov_b32_e32 v52, v58
	s_waitcnt lgkmcnt(9)
	v_mov_b32_e32 v53, v62
	v_mov_b32_e32 v62, v59
	v_mov_b32_e32 v58, v60
	v_mov_b32_e32 v59, v64
	v_mov_b32_e32 v64, v61
	s_waitcnt lgkmcnt(8)
	v_mov_b32_e32 v60, v66
	s_waitcnt lgkmcnt(7)
	v_mov_b32_e32 v61, v70
	v_mov_b32_e32 v70, v67
	v_mov_b32_e32 v66, v68
	v_mov_b32_e32 v67, v72
	v_mov_b32_e32 v72, v69
	s_waitcnt lgkmcnt(6)
	v_mov_b32_e32 v68, v74
	s_waitcnt lgkmcnt(5)
	v_mov_b32_e32 v69, v78
	v_mov_b32_e32 v78, v75
	v_mov_b32_e32 v74, v76
	v_mov_b32_e32 v75, v80
	v_mov_b32_e32 v80, v77
	s_waitcnt lgkmcnt(4)
	v_mov_b32_e32 v76, v82
	s_waitcnt lgkmcnt(3)
	v_mov_b32_e32 v77, v86
	v_mov_b32_e32 v86, v83
	v_mov_b32_e32 v82, v84
	v_mov_b32_e32 v83, v88
	v_mov_b32_e32 v88, v85
	s_waitcnt lgkmcnt(2)
	v_mov_b32_e32 v84, v90
	s_waitcnt lgkmcnt(1)
	v_mov_b32_e32 v85, v94
	v_mov_b32_e32 v94, v91
	v_mov_b32_e32 v90, v92
	v_mov_b32_e32 v91, v96
	s_add_i32 s18, s18, 16
	v_mov_b32_e32 v96, v93
	s_cmpk_lg_i32 s18, 0x200
	s_waitcnt vmcnt(7)
	v_pk_fma_f32 v[12:13], v[110:111], v[30:31], v[12:13] op_sel_hi:[0,1,1]
	v_pk_fma_f32 v[14:15], v[110:111], v[44:45], v[14:15] op_sel_hi:[0,1,1]
	v_pk_fma_f32 v[16:17], v[110:111], v[36:37], v[16:17] op_sel_hi:[0,1,1]
	v_pk_fma_f32 v[18:19], v[110:111], v[52:53], v[18:19] op_sel_hi:[0,1,1]
	v_pk_fma_f32 v[20:21], v[110:111], v[60:61], v[20:21] op_sel_hi:[0,1,1]
	v_pk_fma_f32 v[22:23], v[110:111], v[68:69], v[22:23] op_sel_hi:[0,1,1]
	v_pk_fma_f32 v[24:25], v[110:111], v[76:77], v[24:25] op_sel_hi:[0,1,1]
	v_pk_fma_f32 v[26:27], v[110:111], v[84:85], v[26:27] op_sel_hi:[0,1,1]
	s_waitcnt lgkmcnt(0)
	v_fmac_f32_e32 v2, v110, v98
	s_waitcnt vmcnt(6)
	v_pk_fma_f32 v[12:13], v[112:113], v[38:39], v[12:13] op_sel_hi:[0,1,1]
	v_pk_fma_f32 v[14:15], v[112:113], v[46:47], v[14:15] op_sel_hi:[0,1,1]
	v_pk_fma_f32 v[16:17], v[112:113], v[54:55], v[16:17] op_sel_hi:[0,1,1]
	v_pk_fma_f32 v[18:19], v[112:113], v[62:63], v[18:19] op_sel_hi:[0,1,1]
	v_pk_fma_f32 v[20:21], v[112:113], v[70:71], v[20:21] op_sel_hi:[0,1,1]
	v_pk_fma_f32 v[22:23], v[112:113], v[78:79], v[22:23] op_sel_hi:[0,1,1]
	v_pk_fma_f32 v[24:25], v[112:113], v[86:87], v[24:25] op_sel_hi:[0,1,1]
	v_pk_fma_f32 v[26:27], v[112:113], v[94:95], v[26:27] op_sel_hi:[0,1,1]
	v_fmac_f32_e32 v2, v112, v99
	s_waitcnt vmcnt(4)
	v_pk_fma_f32 v[12:13], v[116:117], v[42:43], v[12:13] op_sel_hi:[0,1,1]
	v_pk_fma_f32 v[14:15], v[116:117], v[34:35], v[14:15] op_sel_hi:[0,1,1]
	v_pk_fma_f32 v[16:17], v[116:117], v[50:51], v[16:17] op_sel_hi:[0,1,1]
	v_pk_fma_f32 v[18:19], v[116:117], v[58:59], v[18:19] op_sel_hi:[0,1,1]
	v_pk_fma_f32 v[20:21], v[116:117], v[66:67], v[20:21] op_sel_hi:[0,1,1]
	v_pk_fma_f32 v[22:23], v[116:117], v[74:75], v[22:23] op_sel_hi:[0,1,1]
	v_pk_fma_f32 v[24:25], v[116:117], v[82:83], v[24:25] op_sel_hi:[0,1,1]
	v_pk_fma_f32 v[26:27], v[116:117], v[90:91], v[26:27] op_sel_hi:[0,1,1]
	v_fmac_f32_e32 v2, v116, v100
	v_pk_fma_f32 v[12:13], v[114:115], v[40:41], v[12:13] op_sel_hi:[0,1,1]
	v_pk_fma_f32 v[14:15], v[114:115], v[48:49], v[14:15] op_sel_hi:[0,1,1]
	v_pk_fma_f32 v[16:17], v[114:115], v[56:57], v[16:17] op_sel_hi:[0,1,1]
	v_pk_fma_f32 v[18:19], v[114:115], v[64:65], v[18:19] op_sel_hi:[0,1,1]
	v_pk_fma_f32 v[20:21], v[114:115], v[72:73], v[20:21] op_sel_hi:[0,1,1]
	v_pk_fma_f32 v[22:23], v[114:115], v[80:81], v[22:23] op_sel_hi:[0,1,1]
	v_pk_fma_f32 v[24:25], v[114:115], v[88:89], v[24:25] op_sel_hi:[0,1,1]
	v_pk_fma_f32 v[26:27], v[114:115], v[96:97], v[26:27] op_sel_hi:[0,1,1]
	v_fmac_f32_e32 v2, v114, v101
	s_cbranch_scc1 .LBB0_40
	v_add_u32_e32 v10, s21, v7
	ds_write2st64_b32 v10, v14, v13 offset1:1
	ds_write2st64_b32 v10, v12, v15 offset0:2 offset1:3
	ds_write2st64_b32 v10, v16, v17 offset0:4 offset1:5
	ds_write2st64_b32 v10, v18, v19 offset0:6 offset1:7
	ds_write2st64_b32 v10, v20, v21 offset0:8 offset1:9
	ds_write2st64_b32 v10, v22, v23 offset0:10 offset1:11
	ds_write2st64_b32 v10, v24, v25 offset0:12 offset1:13
	ds_write2st64_b32 v10, v26, v27 offset0:14 offset1:15
	ds_write_b32 v10, v2 offset:4096
	s_waitcnt lgkmcnt(0)
	s_barrier
	s_and_saveexec_b64 s[18:19], vcc
	s_cbranch_execz .LBB0_38
	s_mul_i32 s9, s11, 17
	s_ashr_i32 s11, s10, 31
	v_lshl_add_u64 v[8:9], v[8:9], 2, s[16:17]
	v_lshl_add_u64 v[10:11], s[10:11], 2, v[4:5]
	s_mov_b64 s[10:11], 0
	v_mov_b32_e32 v2, v6

.LBB0_182:
	s_add_u32 s6, s4, 0xfffc0080
	s_addc_u32 s7, s5, -1
	s_add_i32 s9, 0, 0x10000
	s_cmp_eq_u32 s53, 12
	s_cselect_b32 s27, s39, s7
	s_cselect_b32 s26, s49, s6
	v_add_u32_e32 v0, s9, v189
	s_cselect_b32 s7, s15, s52
	s_cselect_b32 s6, s50, s51
	s_add_i32 s83, 0, 0x14000
	ds_read_b128 v[130:133], v0
	ds_read_b128 v[134:137], v0 offset:1024
	ds_read_b128 v[162:165], v0 offset:2048
	ds_read_b128 v[166:169], v0 offset:3072
	v_add_u32_e32 v0, s83, v189
	ds_read_b128 v[170:173], v0
	ds_read_b128 v[174:177], v0 offset:1024
	ds_read_b128 v[178:181], v0 offset:2048
	ds_read_b128 v[182:185], v0 offset:3072
	v_lshl_add_u64 v[148:149], s[4:5], 0, v[158:159]
	s_add_i32 m0, s40, 0xc000
	ds_read_b128 v[196:199], v193
	ds_read_b128 v[200:203], v193 offset:1024
	ds_read_b128 v[204:207], v193 offset:2048
	ds_read_b128 v[208:211], v193 offset:3072
	ds_read_b128 v[212:215], v193 offset:4096
	ds_read_b128 v[216:219], v193 offset:5120
	ds_read_b128 v[220:223], v193 offset:6144
	ds_read_b128 v[224:227], v193 offset:7168
	global_load_lds_dwordx4 v[148:149], off
	s_add_i32 m0, s40, 0xe000
	v_lshl_add_u64 v[148:149], s[4:5], 0, v[160:161]
	global_load_lds_dwordx4 v[148:149], off
	s_waitcnt vmcnt(8)
	s_waitcnt lgkmcnt(0)
	s_barrier
	s_setprio 1
	v_mfma_f32_16x16x32_bf16 v[126:129], v[130:133], v[196:199], v[126:129]
	v_mfma_f32_16x16x32_bf16 v[122:125], v[162:165], v[196:199], v[122:125]
	v_mfma_f32_16x16x32_bf16 v[118:121], v[130:133], v[204:207], v[118:121]
	v_mfma_f32_16x16x32_bf16 v[114:117], v[162:165], v[204:207], v[114:117]
	v_mfma_f32_16x16x32_bf16 v[102:105], v[130:133], v[212:215], v[102:105]
	v_mfma_f32_16x16x32_bf16 v[98:101], v[162:165], v[212:215], v[98:101]
	v_mfma_f32_16x16x32_bf16 v[86:89], v[130:133], v[220:223], v[86:89]
	v_mfma_f32_16x16x32_bf16 v[82:85], v[162:165], v[220:223], v[82:85]
	v_mfma_f32_16x16x32_bf16 v[126:129], v[134:137], v[200:203], v[126:129]
	v_mfma_f32_16x16x32_bf16 v[122:125], v[166:169], v[200:203], v[122:125]
	v_mfma_f32_16x16x32_bf16 v[118:121], v[134:137], v[208:211], v[118:121]
	v_mfma_f32_16x16x32_bf16 v[114:117], v[166:169], v[208:211], v[114:117]
	v_mfma_f32_16x16x32_bf16 v[102:105], v[134:137], v[216:219], v[102:105]
	v_mfma_f32_16x16x32_bf16 v[98:101], v[166:169], v[216:219], v[98:101]
	v_mfma_f32_16x16x32_bf16 v[86:89], v[134:137], v[224:227], v[86:89]
	v_mfma_f32_16x16x32_bf16 v[82:85], v[166:169], v[224:227], v[82:85]
	v_mfma_f32_16x16x32_bf16 v[110:113], v[170:173], v[196:199], v[110:113]
	v_mfma_f32_16x16x32_bf16 v[106:109], v[178:181], v[196:199], v[106:109]
	v_mfma_f32_16x16x32_bf16 v[94:97], v[170:173], v[204:207], v[94:97]
	v_mfma_f32_16x16x32_bf16 v[90:93], v[178:181], v[204:207], v[90:93]
	v_mfma_f32_16x16x32_bf16 v[78:81], v[170:173], v[212:215], v[78:81]
	v_mfma_f32_16x16x32_bf16 v[74:77], v[178:181], v[212:215], v[74:77]
	v_mfma_f32_16x16x32_bf16 v[70:73], v[170:173], v[220:223], v[70:73]
	v_mfma_f32_16x16x32_bf16 v[66:69], v[178:181], v[220:223], v[66:69]
	v_mfma_f32_16x16x32_bf16 v[110:113], v[174:177], v[200:203], v[110:113]
	v_mfma_f32_16x16x32_bf16 v[106:109], v[182:185], v[200:203], v[106:109]
	v_mfma_f32_16x16x32_bf16 v[94:97], v[174:177], v[208:211], v[94:97]
	v_mfma_f32_16x16x32_bf16 v[90:93], v[182:185], v[208:211], v[90:93]
	v_mfma_f32_16x16x32_bf16 v[78:81], v[174:177], v[216:219], v[78:81]
	v_mfma_f32_16x16x32_bf16 v[74:77], v[182:185], v[216:219], v[74:77]
	v_mfma_f32_16x16x32_bf16 v[70:73], v[174:177], v[224:227], v[70:73]
	v_mfma_f32_16x16x32_bf16 v[66:69], v[182:185], v[224:227], v[66:69]
	s_setprio 0
	s_barrier
	s_add_i32 s9, s9, s29
	v_lshl_add_u64 v[148:149], s[6:7], 0, v[142:143]
	s_mov_b32 m0, s9
	ds_read_b128 v[196:199], v193 offset:16384
	ds_read_b128 v[200:203], v193 offset:17408
	ds_read_b128 v[204:207], v193 offset:18432
	ds_read_b128 v[208:211], v193 offset:19456
	ds_read_b128 v[212:215], v193 offset:20480
	ds_read_b128 v[216:219], v193 offset:21504
	ds_read_b128 v[220:223], v193 offset:22528
	ds_read_b128 v[224:227], v193 offset:23552
	global_load_lds_dwordx4 v[148:149], off
	s_add_i32 m0, s9, 0x2000
	s_add_u32 s78, s6, 0x40000
	v_lshl_add_u64 v[150:151], s[6:7], 0, v[138:139]
	s_addc_u32 s79, s7, 0
	s_add_i32 s9, s83, s29
	global_load_lds_dwordx4 v[150:151], off
	v_lshl_add_u64 v[186:187], s[78:79], 0, v[142:143]
	s_mov_b32 m0, s9
	v_lshl_add_u64 v[228:229], s[26:27], 0, v[140:141]
	global_load_lds_dwordx4 v[186:187], off
	s_add_i32 m0, s9, 0x2000
	v_lshl_add_u64 v[186:187], s[78:79], 0, v[138:139]
	global_load_lds_dwordx4 v[186:187], off
	s_mov_b32 m0, s40
	v_lshl_add_u64 v[186:187], s[26:27], 0, v[144:145]
	global_load_lds_dwordx4 v[186:187], off
	s_mov_b32 m0, s41
	s_nop 0
	global_load_lds_dwordx4 v[228:229], off
	s_waitcnt vmcnt(8)
	s_waitcnt lgkmcnt(0)
	s_barrier
	s_setprio 1
	v_mfma_f32_16x16x32_bf16 v[62:65], v[130:133], v[196:199], v[62:65]
	v_mfma_f32_16x16x32_bf16 v[58:61], v[162:165], v[196:199], v[58:61]
	v_mfma_f32_16x16x32_bf16 v[54:57], v[130:133], v[204:207], v[54:57]
	v_mfma_f32_16x16x32_bf16 v[50:53], v[162:165], v[204:207], v[50:53]
	v_mfma_f32_16x16x32_bf16 v[38:41], v[130:133], v[212:215], v[38:41]
	v_mfma_f32_16x16x32_bf16 v[34:37], v[162:165], v[212:215], v[34:37]
	v_mfma_f32_16x16x32_bf16 v[22:25], v[130:133], v[220:223], v[22:25]
	v_mfma_f32_16x16x32_bf16 v[18:21], v[162:165], v[220:223], v[18:21]
	v_mfma_f32_16x16x32_bf16 v[62:65], v[134:137], v[200:203], v[62:65]
	v_mfma_f32_16x16x32_bf16 v[58:61], v[166:169], v[200:203], v[58:61]
	v_mfma_f32_16x16x32_bf16 v[54:57], v[134:137], v[208:211], v[54:57]
	v_mfma_f32_16x16x32_bf16 v[50:53], v[166:169], v[208:211], v[50:53]
	v_mfma_f32_16x16x32_bf16 v[38:41], v[134:137], v[216:219], v[38:41]
	v_mfma_f32_16x16x32_bf16 v[34:37], v[166:169], v[216:219], v[34:37]
	v_mfma_f32_16x16x32_bf16 v[22:25], v[134:137], v[224:227], v[22:25]
	v_mfma_f32_16x16x32_bf16 v[18:21], v[166:169], v[224:227], v[18:21]
	v_mfma_f32_16x16x32_bf16 v[46:49], v[170:173], v[196:199], v[46:49]
	v_mfma_f32_16x16x32_bf16 v[42:45], v[178:181], v[196:199], v[42:45]
	v_mfma_f32_16x16x32_bf16 v[30:33], v[170:173], v[204:207], v[30:33]
	v_mfma_f32_16x16x32_bf16 v[26:29], v[178:181], v[204:207], v[26:29]
	v_mfma_f32_16x16x32_bf16 v[14:17], v[170:173], v[212:215], v[14:17]
	v_mfma_f32_16x16x32_bf16 v[10:13], v[178:181], v[212:215], v[10:13]
	v_mfma_f32_16x16x32_bf16 v[6:9], v[170:173], v[220:223], v[6:9]
	v_mfma_f32_16x16x32_bf16 v[2:5], v[178:181], v[220:223], v[2:5]
	v_mfma_f32_16x16x32_bf16 v[46:49], v[174:177], v[200:203], v[46:49]
	v_mfma_f32_16x16x32_bf16 v[42:45], v[182:185], v[200:203], v[42:45]
	v_mfma_f32_16x16x32_bf16 v[30:33], v[174:177], v[208:211], v[30:33]
	v_mfma_f32_16x16x32_bf16 v[26:29], v[182:185], v[208:211], v[26:29]
	v_mfma_f32_16x16x32_bf16 v[14:17], v[174:177], v[216:219], v[14:17]
	v_mfma_f32_16x16x32_bf16 v[10:13], v[182:185], v[216:219], v[10:13]
	v_mfma_f32_16x16x32_bf16 v[6:9], v[174:177], v[224:227], v[6:9]
	v_mfma_f32_16x16x32_bf16 v[2:5], v[182:185], v[224:227], v[2:5]
	s_setprio 0
	s_barrier
	s_add_i32 s9, 0, 0x18000
	v_add_u32_e32 v0, s9, v189
	s_add_i32 s78, 0, 0x1c000
	ds_read_b128 v[130:133], v0
	ds_read_b128 v[134:137], v0 offset:1024
	ds_read_b128 v[162:165], v0 offset:2048
	ds_read_b128 v[166:169], v0 offset:3072
	v_add_u32_e32 v0, s78, v189
	ds_read_b128 v[170:173], v0
	ds_read_b128 v[174:177], v0 offset:1024
	ds_read_b128 v[178:181], v0 offset:2048
	ds_read_b128 v[182:185], v0 offset:3072
	s_add_u32 s26, s26, 0x40000
	s_addc_u32 s27, s27, 0
	s_mov_b32 m0, s42
	v_lshl_add_u64 v[230:231], s[26:27], 0, v[144:145]
	ds_read_b128 v[196:199], v193 offset:32768
	ds_read_b128 v[200:203], v193 offset:33792
	ds_read_b128 v[204:207], v193 offset:34816
	ds_read_b128 v[208:211], v193 offset:35840
	ds_read_b128 v[212:215], v193 offset:36864
	ds_read_b128 v[216:219], v193 offset:37888
	ds_read_b128 v[220:223], v193 offset:38912
	ds_read_b128 v[224:227], v193 offset:39936
	global_load_lds_dwordx4 v[230:231], off
	s_mov_b32 m0, s43
	v_lshl_add_u64 v[230:231], s[26:27], 0, v[140:141]
	global_load_lds_dwordx4 v[230:231], off
	s_waitcnt vmcnt(8)
	s_waitcnt lgkmcnt(0)
	s_barrier
	s_setprio 1
	v_mfma_f32_16x16x32_bf16 v[126:129], v[130:133], v[196:199], v[126:129]
	v_mfma_f32_16x16x32_bf16 v[122:125], v[162:165], v[196:199], v[122:125]
	v_mfma_f32_16x16x32_bf16 v[118:121], v[130:133], v[204:207], v[118:121]
	v_mfma_f32_16x16x32_bf16 v[114:117], v[162:165], v[204:207], v[114:117]
	v_mfma_f32_16x16x32_bf16 v[102:105], v[130:133], v[212:215], v[102:105]
	v_mfma_f32_16x16x32_bf16 v[98:101], v[162:165], v[212:215], v[98:101]
	v_mfma_f32_16x16x32_bf16 v[86:89], v[130:133], v[220:223], v[86:89]
	v_mfma_f32_16x16x32_bf16 v[82:85], v[162:165], v[220:223], v[82:85]
	v_mfma_f32_16x16x32_bf16 v[126:129], v[134:137], v[200:203], v[126:129]
	v_mfma_f32_16x16x32_bf16 v[122:125], v[166:169], v[200:203], v[122:125]
	v_mfma_f32_16x16x32_bf16 v[118:121], v[134:137], v[208:211], v[118:121]
	v_mfma_f32_16x16x32_bf16 v[114:117], v[166:169], v[208:211], v[114:117]
	v_mfma_f32_16x16x32_bf16 v[102:105], v[134:137], v[216:219], v[102:105]
	v_mfma_f32_16x16x32_bf16 v[98:101], v[166:169], v[216:219], v[98:101]
	v_mfma_f32_16x16x32_bf16 v[86:89], v[134:137], v[224:227], v[86:89]
	v_mfma_f32_16x16x32_bf16 v[82:85], v[166:169], v[224:227], v[82:85]
	v_mfma_f32_16x16x32_bf16 v[110:113], v[170:173], v[196:199], v[110:113]
	v_mfma_f32_16x16x32_bf16 v[106:109], v[178:181], v[196:199], v[106:109]
	v_mfma_f32_16x16x32_bf16 v[94:97], v[170:173], v[204:207], v[94:97]
	v_mfma_f32_16x16x32_bf16 v[90:93], v[178:181], v[204:207], v[90:93]
	v_mfma_f32_16x16x32_bf16 v[78:81], v[170:173], v[212:215], v[78:81]
	v_mfma_f32_16x16x32_bf16 v[74:77], v[178:181], v[212:215], v[74:77]
	v_mfma_f32_16x16x32_bf16 v[70:73], v[170:173], v[220:223], v[70:73]
	v_mfma_f32_16x16x32_bf16 v[66:69], v[178:181], v[220:223], v[66:69]
	v_mfma_f32_16x16x32_bf16 v[110:113], v[174:177], v[200:203], v[110:113]
	v_mfma_f32_16x16x32_bf16 v[106:109], v[182:185], v[200:203], v[106:109]
	v_mfma_f32_16x16x32_bf16 v[94:97], v[174:177], v[208:211], v[94:97]
	v_mfma_f32_16x16x32_bf16 v[90:93], v[182:185], v[208:211], v[90:93]
	v_mfma_f32_16x16x32_bf16 v[78:81], v[174:177], v[216:219], v[78:81]
	v_mfma_f32_16x16x32_bf16 v[74:77], v[182:185], v[216:219], v[74:77]
	v_mfma_f32_16x16x32_bf16 v[70:73], v[174:177], v[224:227], v[70:73]
	v_mfma_f32_16x16x32_bf16 v[66:69], v[182:185], v[224:227], v[66:69]
	s_setprio 0
	s_barrier
	s_add_i32 s9, s9, s29
	v_lshl_add_u64 v[148:149], v[148:149], 0, s[70:71]
	s_mov_b32 m0, s9
	ds_read_b128 v[196:199], v193 offset:49152
	ds_read_b128 v[200:203], v193 offset:50176
	ds_read_b128 v[204:207], v193 offset:51200
	ds_read_b128 v[208:211], v193 offset:52224
	ds_read_b128 v[212:215], v193 offset:53248
	ds_read_b128 v[216:219], v193 offset:54272
	ds_read_b128 v[220:223], v193 offset:55296
	ds_read_b128 v[224:227], v193 offset:56320
	global_load_lds_dwordx4 v[148:149], off
	s_add_i32 m0, s9, 0x2000
	s_add_u32 s6, s6, 0x40080
	v_lshl_add_u64 v[148:149], v[150:151], 0, s[70:71]
	s_addc_u32 s7, s7, 0
	s_add_i32 s9, s78, s29
	global_load_lds_dwordx4 v[148:149], off
	s_mov_b32 m0, s9
	v_lshl_add_u64 v[148:149], s[6:7], 0, v[142:143]
	global_load_lds_dwordx4 v[148:149], off
	s_add_i32 m0, s9, 0x2000
	v_lshl_add_u64 v[148:149], s[6:7], 0, v[138:139]
	global_load_lds_dwordx4 v[148:149], off
	s_mov_b32 m0, s44
	v_lshl_add_u64 v[148:149], v[186:187], 0, s[70:71]
	global_load_lds_dwordx4 v[148:149], off
	s_mov_b32 m0, s45
	v_lshl_add_u64 v[148:149], v[228:229], 0, s[70:71]
	global_load_lds_dwordx4 v[148:149], off
	s_waitcnt vmcnt(8)
	s_waitcnt lgkmcnt(0)
	s_barrier
	s_setprio 1
	v_mfma_f32_16x16x32_bf16 v[62:65], v[130:133], v[196:199], v[62:65]
	v_mfma_f32_16x16x32_bf16 v[58:61], v[162:165], v[196:199], v[58:61]
	v_mfma_f32_16x16x32_bf16 v[54:57], v[130:133], v[204:207], v[54:57]
	v_mfma_f32_16x16x32_bf16 v[50:53], v[162:165], v[204:207], v[50:53]
	v_mfma_f32_16x16x32_bf16 v[38:41], v[130:133], v[212:215], v[38:41]
	v_mfma_f32_16x16x32_bf16 v[34:37], v[162:165], v[212:215], v[34:37]
	v_mfma_f32_16x16x32_bf16 v[22:25], v[130:133], v[220:223], v[22:25]
	v_mfma_f32_16x16x32_bf16 v[18:21], v[162:165], v[220:223], v[18:21]
	v_mfma_f32_16x16x32_bf16 v[62:65], v[134:137], v[200:203], v[62:65]
	v_mfma_f32_16x16x32_bf16 v[58:61], v[166:169], v[200:203], v[58:61]
	v_mfma_f32_16x16x32_bf16 v[54:57], v[134:137], v[208:211], v[54:57]
	v_mfma_f32_16x16x32_bf16 v[50:53], v[166:169], v[208:211], v[50:53]
	v_mfma_f32_16x16x32_bf16 v[38:41], v[134:137], v[216:219], v[38:41]
	v_mfma_f32_16x16x32_bf16 v[34:37], v[166:169], v[216:219], v[34:37]
	v_mfma_f32_16x16x32_bf16 v[22:25], v[134:137], v[224:227], v[22:25]
	v_mfma_f32_16x16x32_bf16 v[18:21], v[166:169], v[224:227], v[18:21]
	v_mfma_f32_16x16x32_bf16 v[46:49], v[170:173], v[196:199], v[46:49]
	v_mfma_f32_16x16x32_bf16 v[42:45], v[178:181], v[196:199], v[42:45]
	v_mfma_f32_16x16x32_bf16 v[30:33], v[170:173], v[204:207], v[30:33]
	v_mfma_f32_16x16x32_bf16 v[26:29], v[178:181], v[204:207], v[26:29]
	v_mfma_f32_16x16x32_bf16 v[14:17], v[170:173], v[212:215], v[14:17]
	v_mfma_f32_16x16x32_bf16 v[10:13], v[178:181], v[212:215], v[10:13]
	v_mfma_f32_16x16x32_bf16 v[6:9], v[170:173], v[220:223], v[6:9]
	v_mfma_f32_16x16x32_bf16 v[2:5], v[178:181], v[220:223], v[2:5]
	v_mfma_f32_16x16x32_bf16 v[46:49], v[174:177], v[200:203], v[46:49]
	v_mfma_f32_16x16x32_bf16 v[42:45], v[182:185], v[200:203], v[42:45]
	v_mfma_f32_16x16x32_bf16 v[30:33], v[174:177], v[208:211], v[30:33]
	v_mfma_f32_16x16x32_bf16 v[26:29], v[182:185], v[208:211], v[26:29]
	v_mfma_f32_16x16x32_bf16 v[14:17], v[174:177], v[216:219], v[14:17]
	v_mfma_f32_16x16x32_bf16 v[10:13], v[182:185], v[216:219], v[10:13]
	v_mfma_f32_16x16x32_bf16 v[6:9], v[174:177], v[224:227], v[6:9]
	v_mfma_f32_16x16x32_bf16 v[2:5], v[182:185], v[224:227], v[2:5]
	s_setprio 0
	s_barrier
	s_add_i32 s53, s53, 2
	s_add_u32 s4, s4, 0x100
	s_addc_u32 s5, s5, 0
	s_add_u32 s51, s51, 0x100
	s_addc_u32 s52, s52, 0
	s_cmp_gt_u32 s53, 13
	s_cbranch_scc0 .LBB0_182
	s_and_b64 vcc, exec, s[36:37]
	s_cbranch_vccz .LBB0_185
	s_barrier

.LBB0_220:
	s_add_u32 s9, s36, 0xfffc0080
	s_addc_u32 s26, s37, -1
	s_add_i32 s60, 0, 0x10000
	s_cmp_eq_u32 s53, 12
	s_cselect_b32 s39, s19, s26
	s_cselect_b32 s38, s49, s9
	v_add_u32_e32 v148, s60, v141
	s_cselect_b32 s27, s17, s52
	s_cselect_b32 s26, s50, s51
	s_add_i32 s9, 0, 0x14000
	ds_read_b128 v[144:147], v148
	ds_read_b128 v[156:159], v148 offset:1024
	ds_read_b128 v[160:163], v148 offset:2048
	ds_read_b128 v[164:167], v148 offset:3072
	v_add_u32_e32 v148, s9, v141
	ds_read_b128 v[168:171], v148
	ds_read_b128 v[172:175], v148 offset:1024
	ds_read_b128 v[176:179], v148 offset:2048
	ds_read_b128 v[180:183], v148 offset:3072
	v_lshl_add_u64 v[148:149], s[36:37], 0, v[136:137]
	s_add_i32 m0, s40, 0xc000
	ds_read_b128 v[184:187], v143
	ds_read_b128 v[188:191], v143 offset:1024
	ds_read_b128 v[192:195], v143 offset:2048
	ds_read_b128 v[196:199], v143 offset:3072
	ds_read_b128 v[200:203], v143 offset:4096
	ds_read_b128 v[204:207], v143 offset:5120
	ds_read_b128 v[208:211], v143 offset:6144
	ds_read_b128 v[212:215], v143 offset:7168
	global_load_lds_dwordx4 v[148:149], off
	s_add_i32 m0, s40, 0xe000
	v_lshl_add_u64 v[148:149], s[36:37], 0, v[138:139]
	global_load_lds_dwordx4 v[148:149], off
	s_waitcnt vmcnt(8)
	s_waitcnt lgkmcnt(0)
	s_barrier
	s_setprio 1
	v_mfma_f32_16x16x32_bf16 v[126:129], v[144:147], v[184:187], v[126:129]
	v_mfma_f32_16x16x32_bf16 v[122:125], v[160:163], v[184:187], v[122:125]
	v_mfma_f32_16x16x32_bf16 v[118:121], v[144:147], v[192:195], v[118:121]
	v_mfma_f32_16x16x32_bf16 v[114:117], v[160:163], v[192:195], v[114:117]
	v_mfma_f32_16x16x32_bf16 v[102:105], v[144:147], v[200:203], v[102:105]
	v_mfma_f32_16x16x32_bf16 v[98:101], v[160:163], v[200:203], v[98:101]
	v_mfma_f32_16x16x32_bf16 v[86:89], v[144:147], v[208:211], v[86:89]
	v_mfma_f32_16x16x32_bf16 v[82:85], v[160:163], v[208:211], v[82:85]
	v_mfma_f32_16x16x32_bf16 v[126:129], v[156:159], v[188:191], v[126:129]
	v_mfma_f32_16x16x32_bf16 v[122:125], v[164:167], v[188:191], v[122:125]
	v_mfma_f32_16x16x32_bf16 v[118:121], v[156:159], v[196:199], v[118:121]
	v_mfma_f32_16x16x32_bf16 v[114:117], v[164:167], v[196:199], v[114:117]
	v_mfma_f32_16x16x32_bf16 v[102:105], v[156:159], v[204:207], v[102:105]
	v_mfma_f32_16x16x32_bf16 v[98:101], v[164:167], v[204:207], v[98:101]
	v_mfma_f32_16x16x32_bf16 v[86:89], v[156:159], v[212:215], v[86:89]
	v_mfma_f32_16x16x32_bf16 v[82:85], v[164:167], v[212:215], v[82:85]
	v_mfma_f32_16x16x32_bf16 v[110:113], v[168:171], v[184:187], v[110:113]
	v_mfma_f32_16x16x32_bf16 v[106:109], v[176:179], v[184:187], v[106:109]
	v_mfma_f32_16x16x32_bf16 v[94:97], v[168:171], v[192:195], v[94:97]
	v_mfma_f32_16x16x32_bf16 v[90:93], v[176:179], v[192:195], v[90:93]
	v_mfma_f32_16x16x32_bf16 v[78:81], v[168:171], v[200:203], v[78:81]
	v_mfma_f32_16x16x32_bf16 v[74:77], v[176:179], v[200:203], v[74:77]
	v_mfma_f32_16x16x32_bf16 v[70:73], v[168:171], v[208:211], v[70:73]
	v_mfma_f32_16x16x32_bf16 v[66:69], v[176:179], v[208:211], v[66:69]
	v_mfma_f32_16x16x32_bf16 v[110:113], v[172:175], v[188:191], v[110:113]
	v_mfma_f32_16x16x32_bf16 v[106:109], v[180:183], v[188:191], v[106:109]
	v_mfma_f32_16x16x32_bf16 v[94:97], v[172:175], v[196:199], v[94:97]
	v_mfma_f32_16x16x32_bf16 v[90:93], v[180:183], v[196:199], v[90:93]
	v_mfma_f32_16x16x32_bf16 v[78:81], v[172:175], v[204:207], v[78:81]
	v_mfma_f32_16x16x32_bf16 v[74:77], v[180:183], v[204:207], v[74:77]
	v_mfma_f32_16x16x32_bf16 v[70:73], v[172:175], v[212:215], v[70:73]
	v_mfma_f32_16x16x32_bf16 v[66:69], v[180:183], v[212:215], v[66:69]
	s_setprio 0
	s_barrier
	s_add_i32 s60, s60, s29
	v_lshl_add_u64 v[148:149], s[26:27], 0, v[0:1]
	s_mov_b32 m0, s60
	ds_read_b128 v[184:187], v143 offset:16384
	ds_read_b128 v[188:191], v143 offset:17408
	ds_read_b128 v[192:195], v143 offset:18432
	ds_read_b128 v[196:199], v143 offset:19456
	ds_read_b128 v[200:203], v143 offset:20480
	ds_read_b128 v[204:207], v143 offset:21504
	ds_read_b128 v[208:211], v143 offset:22528
	ds_read_b128 v[212:215], v143 offset:23552
	global_load_lds_dwordx4 v[148:149], off
	s_add_i32 m0, s60, 0x2000
	s_add_u32 s60, s26, 0x40000
	v_lshl_add_u64 v[150:151], s[26:27], 0, v[130:131]
	s_addc_u32 s61, s27, 0
	s_add_i32 s9, s9, s29
	global_load_lds_dwordx4 v[150:151], off
	v_lshl_add_u64 v[216:217], s[60:61], 0, v[0:1]
	s_mov_b32 m0, s9
	v_lshl_add_u64 v[218:219], s[38:39], 0, v[132:133]
	global_load_lds_dwordx4 v[216:217], off
	s_add_i32 m0, s9, 0x2000
	v_lshl_add_u64 v[216:217], s[60:61], 0, v[130:131]
	global_load_lds_dwordx4 v[216:217], off
	s_mov_b32 m0, s40
	v_lshl_add_u64 v[216:217], s[38:39], 0, v[134:135]
	global_load_lds_dwordx4 v[216:217], off
	s_mov_b32 m0, s41
	s_nop 0
	global_load_lds_dwordx4 v[218:219], off
	s_waitcnt vmcnt(8)
	s_waitcnt lgkmcnt(0)
	s_barrier
	s_setprio 1
	v_mfma_f32_16x16x32_bf16 v[62:65], v[144:147], v[184:187], v[62:65]
	v_mfma_f32_16x16x32_bf16 v[58:61], v[160:163], v[184:187], v[58:61]
	v_mfma_f32_16x16x32_bf16 v[54:57], v[144:147], v[192:195], v[54:57]
	v_mfma_f32_16x16x32_bf16 v[50:53], v[160:163], v[192:195], v[50:53]
	v_mfma_f32_16x16x32_bf16 v[38:41], v[144:147], v[200:203], v[38:41]
	v_mfma_f32_16x16x32_bf16 v[34:37], v[160:163], v[200:203], v[34:37]
	v_mfma_f32_16x16x32_bf16 v[22:25], v[144:147], v[208:211], v[22:25]
	v_mfma_f32_16x16x32_bf16 v[18:21], v[160:163], v[208:211], v[18:21]
	v_mfma_f32_16x16x32_bf16 v[62:65], v[156:159], v[188:191], v[62:65]
	v_mfma_f32_16x16x32_bf16 v[58:61], v[164:167], v[188:191], v[58:61]
	v_mfma_f32_16x16x32_bf16 v[54:57], v[156:159], v[196:199], v[54:57]
	v_mfma_f32_16x16x32_bf16 v[50:53], v[164:167], v[196:199], v[50:53]
	v_mfma_f32_16x16x32_bf16 v[38:41], v[156:159], v[204:207], v[38:41]
	v_mfma_f32_16x16x32_bf16 v[34:37], v[164:167], v[204:207], v[34:37]
	v_mfma_f32_16x16x32_bf16 v[22:25], v[156:159], v[212:215], v[22:25]
	v_mfma_f32_16x16x32_bf16 v[18:21], v[164:167], v[212:215], v[18:21]
	v_mfma_f32_16x16x32_bf16 v[46:49], v[168:171], v[184:187], v[46:49]
	v_mfma_f32_16x16x32_bf16 v[42:45], v[176:179], v[184:187], v[42:45]
	v_mfma_f32_16x16x32_bf16 v[30:33], v[168:171], v[192:195], v[30:33]
	v_mfma_f32_16x16x32_bf16 v[26:29], v[176:179], v[192:195], v[26:29]
	v_mfma_f32_16x16x32_bf16 v[14:17], v[168:171], v[200:203], v[14:17]
	v_mfma_f32_16x16x32_bf16 v[10:13], v[176:179], v[200:203], v[10:13]
	v_mfma_f32_16x16x32_bf16 v[6:9], v[168:171], v[208:211], v[6:9]
	v_mfma_f32_16x16x32_bf16 v[2:5], v[176:179], v[208:211], v[2:5]
	v_mfma_f32_16x16x32_bf16 v[46:49], v[172:175], v[188:191], v[46:49]
	v_mfma_f32_16x16x32_bf16 v[42:45], v[180:183], v[188:191], v[42:45]
	v_mfma_f32_16x16x32_bf16 v[30:33], v[172:175], v[196:199], v[30:33]
	v_mfma_f32_16x16x32_bf16 v[26:29], v[180:183], v[196:199], v[26:29]
	v_mfma_f32_16x16x32_bf16 v[14:17], v[172:175], v[204:207], v[14:17]
	v_mfma_f32_16x16x32_bf16 v[10:13], v[180:183], v[204:207], v[10:13]
	v_mfma_f32_16x16x32_bf16 v[6:9], v[172:175], v[212:215], v[6:9]
	v_mfma_f32_16x16x32_bf16 v[2:5], v[180:183], v[212:215], v[2:5]
	s_setprio 0
	s_barrier
	s_add_i32 s9, 0, 0x18000
	s_add_i32 s60, 0, 0x1c000
	v_add_u32_e32 v164, s9, v141
	v_add_u32_e32 v180, s60, v141
	ds_read_b128 v[144:147], v164
	ds_read_b128 v[156:159], v164 offset:1024
	ds_read_b128 v[160:163], v164 offset:2048
	ds_read_b128 v[164:167], v164 offset:3072
	ds_read_b128 v[168:171], v180
	ds_read_b128 v[172:175], v180 offset:1024
	ds_read_b128 v[176:179], v180 offset:2048
	ds_read_b128 v[180:183], v180 offset:3072
	s_add_u32 s38, s38, 0x40000
	s_addc_u32 s39, s39, 0
	s_mov_b32 m0, s42
	v_lshl_add_u64 v[220:221], s[38:39], 0, v[134:135]
	ds_read_b128 v[184:187], v143 offset:32768
	ds_read_b128 v[188:191], v143 offset:33792
	ds_read_b128 v[192:195], v143 offset:34816
	ds_read_b128 v[196:199], v143 offset:35840
	ds_read_b128 v[200:203], v143 offset:36864
	ds_read_b128 v[204:207], v143 offset:37888
	ds_read_b128 v[208:211], v143 offset:38912
	ds_read_b128 v[212:215], v143 offset:39936
	global_load_lds_dwordx4 v[220:221], off
	s_mov_b32 m0, s43
	v_lshl_add_u64 v[220:221], s[38:39], 0, v[132:133]
	global_load_lds_dwordx4 v[220:221], off
	s_waitcnt vmcnt(8)
	s_waitcnt lgkmcnt(0)
	s_barrier
	s_setprio 1
	v_mfma_f32_16x16x32_bf16 v[126:129], v[144:147], v[184:187], v[126:129]
	v_mfma_f32_16x16x32_bf16 v[122:125], v[160:163], v[184:187], v[122:125]
	v_mfma_f32_16x16x32_bf16 v[118:121], v[144:147], v[192:195], v[118:121]
	v_mfma_f32_16x16x32_bf16 v[114:117], v[160:163], v[192:195], v[114:117]
	v_mfma_f32_16x16x32_bf16 v[102:105], v[144:147], v[200:203], v[102:105]
	v_mfma_f32_16x16x32_bf16 v[98:101], v[160:163], v[200:203], v[98:101]
	v_mfma_f32_16x16x32_bf16 v[86:89], v[144:147], v[208:211], v[86:89]
	v_mfma_f32_16x16x32_bf16 v[82:85], v[160:163], v[208:211], v[82:85]
	v_mfma_f32_16x16x32_bf16 v[126:129], v[156:159], v[188:191], v[126:129]
	v_mfma_f32_16x16x32_bf16 v[122:125], v[164:167], v[188:191], v[122:125]
	v_mfma_f32_16x16x32_bf16 v[118:121], v[156:159], v[196:199], v[118:121]
	v_mfma_f32_16x16x32_bf16 v[114:117], v[164:167], v[196:199], v[114:117]
	v_mfma_f32_16x16x32_bf16 v[102:105], v[156:159], v[204:207], v[102:105]
	v_mfma_f32_16x16x32_bf16 v[98:101], v[164:167], v[204:207], v[98:101]
	v_mfma_f32_16x16x32_bf16 v[86:89], v[156:159], v[212:215], v[86:89]
	v_mfma_f32_16x16x32_bf16 v[82:85], v[164:167], v[212:215], v[82:85]
	v_mfma_f32_16x16x32_bf16 v[110:113], v[168:171], v[184:187], v[110:113]
	v_mfma_f32_16x16x32_bf16 v[106:109], v[176:179], v[184:187], v[106:109]
	v_mfma_f32_16x16x32_bf16 v[94:97], v[168:171], v[192:195], v[94:97]
	v_mfma_f32_16x16x32_bf16 v[90:93], v[176:179], v[192:195], v[90:93]
	v_mfma_f32_16x16x32_bf16 v[78:81], v[168:171], v[200:203], v[78:81]
	v_mfma_f32_16x16x32_bf16 v[74:77], v[176:179], v[200:203], v[74:77]
	v_mfma_f32_16x16x32_bf16 v[70:73], v[168:171], v[208:211], v[70:73]
	v_mfma_f32_16x16x32_bf16 v[66:69], v[176:179], v[208:211], v[66:69]
	v_mfma_f32_16x16x32_bf16 v[110:113], v[172:175], v[188:191], v[110:113]
	v_mfma_f32_16x16x32_bf16 v[106:109], v[180:183], v[188:191], v[106:109]
	v_mfma_f32_16x16x32_bf16 v[94:97], v[172:175], v[196:199], v[94:97]
	v_mfma_f32_16x16x32_bf16 v[90:93], v[180:183], v[196:199], v[90:93]
	v_mfma_f32_16x16x32_bf16 v[78:81], v[172:175], v[204:207], v[78:81]
	v_mfma_f32_16x16x32_bf16 v[74:77], v[180:183], v[204:207], v[74:77]
	v_mfma_f32_16x16x32_bf16 v[70:73], v[172:175], v[212:215], v[70:73]
	v_mfma_f32_16x16x32_bf16 v[66:69], v[180:183], v[212:215], v[66:69]
	s_setprio 0
	s_barrier
	s_add_i32 s9, s9, s29
	v_lshl_add_u64 v[148:149], v[148:149], 0, s[70:71]
	s_mov_b32 m0, s9
	ds_read_b128 v[184:187], v143 offset:49152
	ds_read_b128 v[188:191], v143 offset:50176
	ds_read_b128 v[192:195], v143 offset:51200
	ds_read_b128 v[196:199], v143 offset:52224
	ds_read_b128 v[200:203], v143 offset:53248
	ds_read_b128 v[204:207], v143 offset:54272
	ds_read_b128 v[208:211], v143 offset:55296
	ds_read_b128 v[212:215], v143 offset:56320
	global_load_lds_dwordx4 v[148:149], off
	s_add_i32 m0, s9, 0x2000
	s_add_u32 s26, s26, 0x40080
	v_lshl_add_u64 v[148:149], v[150:151], 0, s[70:71]
	s_addc_u32 s27, s27, 0
	s_add_i32 s9, s60, s29
	global_load_lds_dwordx4 v[148:149], off
	s_mov_b32 m0, s9
	v_lshl_add_u64 v[148:149], s[26:27], 0, v[0:1]
	global_load_lds_dwordx4 v[148:149], off
	s_add_i32 m0, s9, 0x2000
	v_lshl_add_u64 v[148:149], s[26:27], 0, v[130:131]
	global_load_lds_dwordx4 v[148:149], off
	s_mov_b32 m0, s44
	v_lshl_add_u64 v[148:149], v[216:217], 0, s[70:71]
	global_load_lds_dwordx4 v[148:149], off
	s_mov_b32 m0, s45
	v_lshl_add_u64 v[148:149], v[218:219], 0, s[70:71]
	global_load_lds_dwordx4 v[148:149], off
	s_waitcnt vmcnt(8)
	s_waitcnt lgkmcnt(0)
	s_barrier
	s_setprio 1
	v_mfma_f32_16x16x32_bf16 v[62:65], v[144:147], v[184:187], v[62:65]
	v_mfma_f32_16x16x32_bf16 v[58:61], v[160:163], v[184:187], v[58:61]
	v_mfma_f32_16x16x32_bf16 v[54:57], v[144:147], v[192:195], v[54:57]
	v_mfma_f32_16x16x32_bf16 v[50:53], v[160:163], v[192:195], v[50:53]
	v_mfma_f32_16x16x32_bf16 v[38:41], v[144:147], v[200:203], v[38:41]
	v_mfma_f32_16x16x32_bf16 v[34:37], v[160:163], v[200:203], v[34:37]
	v_mfma_f32_16x16x32_bf16 v[22:25], v[144:147], v[208:211], v[22:25]
	v_mfma_f32_16x16x32_bf16 v[18:21], v[160:163], v[208:211], v[18:21]
	v_mfma_f32_16x16x32_bf16 v[62:65], v[156:159], v[188:191], v[62:65]
	v_mfma_f32_16x16x32_bf16 v[58:61], v[164:167], v[188:191], v[58:61]
	v_mfma_f32_16x16x32_bf16 v[54:57], v[156:159], v[196:199], v[54:57]
	v_mfma_f32_16x16x32_bf16 v[50:53], v[164:167], v[196:199], v[50:53]
	v_mfma_f32_16x16x32_bf16 v[38:41], v[156:159], v[204:207], v[38:41]
	v_mfma_f32_16x16x32_bf16 v[34:37], v[164:167], v[204:207], v[34:37]
	v_mfma_f32_16x16x32_bf16 v[22:25], v[156:159], v[212:215], v[22:25]
	v_mfma_f32_16x16x32_bf16 v[18:21], v[164:167], v[212:215], v[18:21]
	v_mfma_f32_16x16x32_bf16 v[46:49], v[168:171], v[184:187], v[46:49]
	v_mfma_f32_16x16x32_bf16 v[42:45], v[176:179], v[184:187], v[42:45]
	v_mfma_f32_16x16x32_bf16 v[30:33], v[168:171], v[192:195], v[30:33]
	v_mfma_f32_16x16x32_bf16 v[26:29], v[176:179], v[192:195], v[26:29]
	v_mfma_f32_16x16x32_bf16 v[14:17], v[168:171], v[200:203], v[14:17]
	v_mfma_f32_16x16x32_bf16 v[10:13], v[176:179], v[200:203], v[10:13]
	v_mfma_f32_16x16x32_bf16 v[6:9], v[168:171], v[208:211], v[6:9]
	v_mfma_f32_16x16x32_bf16 v[2:5], v[176:179], v[208:211], v[2:5]
	v_mfma_f32_16x16x32_bf16 v[46:49], v[172:175], v[188:191], v[46:49]
	v_mfma_f32_16x16x32_bf16 v[42:45], v[180:183], v[188:191], v[42:45]
	v_mfma_f32_16x16x32_bf16 v[30:33], v[172:175], v[196:199], v[30:33]
	v_mfma_f32_16x16x32_bf16 v[26:29], v[180:183], v[196:199], v[26:29]
	v_mfma_f32_16x16x32_bf16 v[14:17], v[172:175], v[204:207], v[14:17]
	v_mfma_f32_16x16x32_bf16 v[10:13], v[180:183], v[204:207], v[10:13]
	v_mfma_f32_16x16x32_bf16 v[6:9], v[172:175], v[212:215], v[6:9]
	v_mfma_f32_16x16x32_bf16 v[2:5], v[180:183], v[212:215], v[2:5]
	s_setprio 0
	s_barrier
	s_add_i32 s53, s53, 2
	s_add_u32 s36, s36, 0x100
	s_addc_u32 s37, s37, 0
	s_add_u32 s51, s51, 0x100
	s_addc_u32 s52, s52, 0
	s_cmp_gt_u32 s53, 13
	s_cbranch_scc0 .LBB0_220
	s_and_b64 vcc, exec, s[14:15]
	s_cbranch_vccz .LBB0_223
	s_barrier

.LBB0_376:
	s_add_u32 s53, s18, s9
	s_addc_u32 s74, s19, 0
	s_add_u32 s60, s53, 0x100
	s_addc_u32 s61, s74, 0
	s_and_b64 s[26:27], s[38:39], exec
	s_cselect_b32 s61, s25, s61
	s_cselect_b32 s60, s24, s60
	s_add_u32 s9, s16, s9
	s_addc_u32 s26, s17, 0
	s_add_u32 s9, s9, 0x100
	s_addc_u32 s72, s26, 0
	s_add_i32 s92, 0, 0x10000
	s_and_b64 s[26:27], s[38:39], exec
	s_cselect_b32 s73, s23, s72
	s_cselect_b32 s72, s52, s9
	s_add_i32 s39, 0, 0x14000
	s_add_u32 vcc_lo, s53, 0x58080
	s_addc_u32 vcc_hi, s74, 0
	s_add_i32 s78, s92, s41
	s_add_i32 m0, s42, 0xc000
	s_add_i32 s93, s42, 0xe000
	s_add_i32 s91, s78, 0x2000
	v_add_u32_e32 v148, s92, v137
	s_add_u32 s74, s72, 0x10000
	ds_read_b128 v[140:143], v148
	ds_read_b128 v[144:147], v148 offset:1024
	ds_read_b128 v[156:159], v148 offset:2048
	ds_read_b128 v[160:163], v148 offset:3072
	v_add_u32_e32 v148, s39, v137
	s_addc_u32 s75, s73, 0
	s_add_i32 s79, s39, s41
	ds_read_b128 v[164:167], v148
	ds_read_b128 v[168:171], v148 offset:1024
	ds_read_b128 v[172:175], v148 offset:2048
	ds_read_b128 v[176:179], v148 offset:3072
	s_add_i32 s90, s79, 0x2000
	s_add_i32 s97, 0, 0x18000
	s_add_i32 s83, 0, 0x1c000
	s_add_u32 s26, s60, 0x58000
	s_addc_u32 s27, s61, 0
	s_add_i32 s53, s97, s41
	s_add_i32 s9, s53, 0x2000
	s_add_u32 s38, s72, 0x10080
	s_addc_u32 s39, s73, 0
	s_add_i32 s96, s83, s41
	s_add_i32 s92, s96, 0x2000
	v_lshl_add_u64 v[148:149], vcc, 0, v[134:135]
	ds_read_b128 v[180:183], v139
	ds_read_b128 v[184:187], v139 offset:1024
	ds_read_b128 v[188:191], v139 offset:2048
	ds_read_b128 v[192:195], v139 offset:3072
	ds_read_b128 v[196:199], v139 offset:4096
	ds_read_b128 v[200:203], v139 offset:5120
	ds_read_b128 v[204:207], v139 offset:6144
	ds_read_b128 v[208:211], v139 offset:7168
	global_load_lds_dwordx4 v[148:149], off
	s_mov_b32 m0, s93
	v_lshl_add_u64 v[148:149], vcc, 0, v[132:133]
	global_load_lds_dwordx4 v[148:149], off
	s_waitcnt vmcnt(8)
	s_waitcnt lgkmcnt(0)
	s_barrier
	s_setprio 1
	v_mfma_f32_16x16x32_bf16 v[126:129], v[140:143], v[180:183], v[126:129]
	v_mfma_f32_16x16x32_bf16 v[122:125], v[156:159], v[180:183], v[122:125]
	v_mfma_f32_16x16x32_bf16 v[118:121], v[140:143], v[188:191], v[118:121]
	v_mfma_f32_16x16x32_bf16 v[114:117], v[156:159], v[188:191], v[114:117]
	v_mfma_f32_16x16x32_bf16 v[102:105], v[140:143], v[196:199], v[102:105]
	v_mfma_f32_16x16x32_bf16 v[98:101], v[156:159], v[196:199], v[98:101]
	v_mfma_f32_16x16x32_bf16 v[86:89], v[140:143], v[204:207], v[86:89]
	v_mfma_f32_16x16x32_bf16 v[82:85], v[156:159], v[204:207], v[82:85]
	v_mfma_f32_16x16x32_bf16 v[126:129], v[144:147], v[184:187], v[126:129]
	v_mfma_f32_16x16x32_bf16 v[122:125], v[160:163], v[184:187], v[122:125]
	v_mfma_f32_16x16x32_bf16 v[118:121], v[144:147], v[192:195], v[118:121]
	v_mfma_f32_16x16x32_bf16 v[114:117], v[160:163], v[192:195], v[114:117]
	v_mfma_f32_16x16x32_bf16 v[102:105], v[144:147], v[200:203], v[102:105]
	v_mfma_f32_16x16x32_bf16 v[98:101], v[160:163], v[200:203], v[98:101]
	v_mfma_f32_16x16x32_bf16 v[86:89], v[144:147], v[208:211], v[86:89]
	v_mfma_f32_16x16x32_bf16 v[82:85], v[160:163], v[208:211], v[82:85]
	v_mfma_f32_16x16x32_bf16 v[110:113], v[164:167], v[180:183], v[110:113]
	v_mfma_f32_16x16x32_bf16 v[106:109], v[172:175], v[180:183], v[106:109]
	v_mfma_f32_16x16x32_bf16 v[94:97], v[164:167], v[188:191], v[94:97]
	v_mfma_f32_16x16x32_bf16 v[90:93], v[172:175], v[188:191], v[90:93]
	v_mfma_f32_16x16x32_bf16 v[78:81], v[164:167], v[196:199], v[78:81]
	v_mfma_f32_16x16x32_bf16 v[74:77], v[172:175], v[196:199], v[74:77]
	v_mfma_f32_16x16x32_bf16 v[70:73], v[164:167], v[204:207], v[70:73]
	v_mfma_f32_16x16x32_bf16 v[66:69], v[172:175], v[204:207], v[66:69]
	v_mfma_f32_16x16x32_bf16 v[110:113], v[168:171], v[184:187], v[110:113]
	v_mfma_f32_16x16x32_bf16 v[106:109], v[176:179], v[184:187], v[106:109]
	v_mfma_f32_16x16x32_bf16 v[94:97], v[168:171], v[192:195], v[94:97]
	v_mfma_f32_16x16x32_bf16 v[90:93], v[176:179], v[192:195], v[90:93]
	v_mfma_f32_16x16x32_bf16 v[78:81], v[168:171], v[200:203], v[78:81]
	v_mfma_f32_16x16x32_bf16 v[74:77], v[176:179], v[200:203], v[74:77]
	v_mfma_f32_16x16x32_bf16 v[70:73], v[168:171], v[208:211], v[70:73]
	v_mfma_f32_16x16x32_bf16 v[66:69], v[176:179], v[208:211], v[66:69]
	s_setprio 0
	s_barrier
	s_mov_b32 m0, s78
	v_lshl_add_u64 v[148:149], s[72:73], 0, v[0:1]
	ds_read_b128 v[180:183], v139 offset:16384
	ds_read_b128 v[184:187], v139 offset:17408
	ds_read_b128 v[188:191], v139 offset:18432
	ds_read_b128 v[192:195], v139 offset:19456
	ds_read_b128 v[196:199], v139 offset:20480
	ds_read_b128 v[200:203], v139 offset:21504
	ds_read_b128 v[204:207], v139 offset:22528
	ds_read_b128 v[208:211], v139 offset:23552
	global_load_lds_dwordx4 v[148:149], off
	v_lshl_add_u64 v[150:151], s[72:73], 0, v[130:131]
	s_mov_b32 m0, s91
	v_lshl_add_u64 v[212:213], s[74:75], 0, v[0:1]
	global_load_lds_dwordx4 v[150:151], off
	s_mov_b32 m0, s79
	v_lshl_add_u64 v[214:215], s[60:61], 0, v[132:133]
	global_load_lds_dwordx4 v[212:213], off
	s_mov_b32 m0, s90
	v_lshl_add_u64 v[212:213], s[74:75], 0, v[130:131]
	global_load_lds_dwordx4 v[212:213], off
	s_mov_b32 m0, s42
	v_lshl_add_u64 v[212:213], s[60:61], 0, v[134:135]
	global_load_lds_dwordx4 v[212:213], off
	s_mov_b32 m0, s43
	s_nop 0
	global_load_lds_dwordx4 v[214:215], off
	s_waitcnt vmcnt(8)
	s_waitcnt lgkmcnt(0)
	s_barrier
	s_setprio 1
	v_mfma_f32_16x16x32_bf16 v[62:65], v[140:143], v[180:183], v[62:65]
	v_mfma_f32_16x16x32_bf16 v[58:61], v[156:159], v[180:183], v[58:61]
	v_mfma_f32_16x16x32_bf16 v[54:57], v[140:143], v[188:191], v[54:57]
	v_mfma_f32_16x16x32_bf16 v[50:53], v[156:159], v[188:191], v[50:53]
	v_mfma_f32_16x16x32_bf16 v[38:41], v[140:143], v[196:199], v[38:41]
	v_mfma_f32_16x16x32_bf16 v[34:37], v[156:159], v[196:199], v[34:37]
	v_mfma_f32_16x16x32_bf16 v[22:25], v[140:143], v[204:207], v[22:25]
	v_mfma_f32_16x16x32_bf16 v[18:21], v[156:159], v[204:207], v[18:21]
	v_mfma_f32_16x16x32_bf16 v[62:65], v[144:147], v[184:187], v[62:65]
	v_mfma_f32_16x16x32_bf16 v[58:61], v[160:163], v[184:187], v[58:61]
	v_mfma_f32_16x16x32_bf16 v[54:57], v[144:147], v[192:195], v[54:57]
	v_mfma_f32_16x16x32_bf16 v[50:53], v[160:163], v[192:195], v[50:53]
	v_mfma_f32_16x16x32_bf16 v[38:41], v[144:147], v[200:203], v[38:41]
	v_mfma_f32_16x16x32_bf16 v[34:37], v[160:163], v[200:203], v[34:37]
	v_mfma_f32_16x16x32_bf16 v[22:25], v[144:147], v[208:211], v[22:25]
	v_mfma_f32_16x16x32_bf16 v[18:21], v[160:163], v[208:211], v[18:21]
	v_mfma_f32_16x16x32_bf16 v[46:49], v[164:167], v[180:183], v[46:49]
	v_mfma_f32_16x16x32_bf16 v[42:45], v[172:175], v[180:183], v[42:45]
	v_mfma_f32_16x16x32_bf16 v[30:33], v[164:167], v[188:191], v[30:33]
	v_mfma_f32_16x16x32_bf16 v[26:29], v[172:175], v[188:191], v[26:29]
	v_mfma_f32_16x16x32_bf16 v[14:17], v[164:167], v[196:199], v[14:17]
	v_mfma_f32_16x16x32_bf16 v[10:13], v[172:175], v[196:199], v[10:13]
	v_mfma_f32_16x16x32_bf16 v[6:9], v[164:167], v[204:207], v[6:9]
	v_mfma_f32_16x16x32_bf16 v[2:5], v[172:175], v[204:207], v[2:5]
	v_mfma_f32_16x16x32_bf16 v[46:49], v[168:171], v[184:187], v[46:49]
	v_mfma_f32_16x16x32_bf16 v[42:45], v[176:179], v[184:187], v[42:45]
	v_mfma_f32_16x16x32_bf16 v[30:33], v[168:171], v[192:195], v[30:33]
	v_mfma_f32_16x16x32_bf16 v[26:29], v[176:179], v[192:195], v[26:29]
	v_mfma_f32_16x16x32_bf16 v[14:17], v[168:171], v[200:203], v[14:17]
	v_mfma_f32_16x16x32_bf16 v[10:13], v[176:179], v[200:203], v[10:13]
	v_mfma_f32_16x16x32_bf16 v[6:9], v[168:171], v[208:211], v[6:9]
	v_mfma_f32_16x16x32_bf16 v[2:5], v[176:179], v[208:211], v[2:5]
	s_setprio 0
	s_barrier
	v_add_u32_e32 v160, s97, v137
	v_add_u32_e32 v176, s83, v137
	ds_read_b128 v[140:143], v160
	ds_read_b128 v[144:147], v160 offset:1024
	ds_read_b128 v[156:159], v160 offset:2048
	ds_read_b128 v[160:163], v160 offset:3072
	ds_read_b128 v[164:167], v176
	ds_read_b128 v[168:171], v176 offset:1024
	ds_read_b128 v[172:175], v176 offset:2048
	ds_read_b128 v[176:179], v176 offset:3072
	s_mov_b32 m0, s44
	v_lshl_add_u64 v[216:217], s[26:27], 0, v[134:135]
	ds_read_b128 v[180:183], v139 offset:32768
	ds_read_b128 v[184:187], v139 offset:33792
	ds_read_b128 v[188:191], v139 offset:34816
	ds_read_b128 v[192:195], v139 offset:35840
	ds_read_b128 v[196:199], v139 offset:36864
	ds_read_b128 v[200:203], v139 offset:37888
	ds_read_b128 v[204:207], v139 offset:38912
	ds_read_b128 v[208:211], v139 offset:39936
	global_load_lds_dwordx4 v[216:217], off
	s_mov_b32 m0, s45
	v_lshl_add_u64 v[216:217], s[26:27], 0, v[132:133]
	global_load_lds_dwordx4 v[216:217], off
	s_waitcnt vmcnt(8)
	s_waitcnt lgkmcnt(0)
	s_barrier
	s_setprio 1
	v_mfma_f32_16x16x32_bf16 v[126:129], v[140:143], v[180:183], v[126:129]
	v_mfma_f32_16x16x32_bf16 v[122:125], v[156:159], v[180:183], v[122:125]
	v_mfma_f32_16x16x32_bf16 v[118:121], v[140:143], v[188:191], v[118:121]
	v_mfma_f32_16x16x32_bf16 v[114:117], v[156:159], v[188:191], v[114:117]
	v_mfma_f32_16x16x32_bf16 v[102:105], v[140:143], v[196:199], v[102:105]
	v_mfma_f32_16x16x32_bf16 v[98:101], v[156:159], v[196:199], v[98:101]
	v_mfma_f32_16x16x32_bf16 v[86:89], v[140:143], v[204:207], v[86:89]
	v_mfma_f32_16x16x32_bf16 v[82:85], v[156:159], v[204:207], v[82:85]
	v_mfma_f32_16x16x32_bf16 v[126:129], v[144:147], v[184:187], v[126:129]
	v_mfma_f32_16x16x32_bf16 v[122:125], v[160:163], v[184:187], v[122:125]
	v_mfma_f32_16x16x32_bf16 v[118:121], v[144:147], v[192:195], v[118:121]
	v_mfma_f32_16x16x32_bf16 v[114:117], v[160:163], v[192:195], v[114:117]
	v_mfma_f32_16x16x32_bf16 v[102:105], v[144:147], v[200:203], v[102:105]
	v_mfma_f32_16x16x32_bf16 v[98:101], v[160:163], v[200:203], v[98:101]
	v_mfma_f32_16x16x32_bf16 v[86:89], v[144:147], v[208:211], v[86:89]
	v_mfma_f32_16x16x32_bf16 v[82:85], v[160:163], v[208:211], v[82:85]
	v_mfma_f32_16x16x32_bf16 v[110:113], v[164:167], v[180:183], v[110:113]
	v_mfma_f32_16x16x32_bf16 v[106:109], v[172:175], v[180:183], v[106:109]
	v_mfma_f32_16x16x32_bf16 v[94:97], v[164:167], v[188:191], v[94:97]
	v_mfma_f32_16x16x32_bf16 v[90:93], v[172:175], v[188:191], v[90:93]
	v_mfma_f32_16x16x32_bf16 v[78:81], v[164:167], v[196:199], v[78:81]
	v_mfma_f32_16x16x32_bf16 v[74:77], v[172:175], v[196:199], v[74:77]
	v_mfma_f32_16x16x32_bf16 v[70:73], v[164:167], v[204:207], v[70:73]
	v_mfma_f32_16x16x32_bf16 v[66:69], v[172:175], v[204:207], v[66:69]
	v_mfma_f32_16x16x32_bf16 v[110:113], v[168:171], v[184:187], v[110:113]
	v_mfma_f32_16x16x32_bf16 v[106:109], v[176:179], v[184:187], v[106:109]
	v_mfma_f32_16x16x32_bf16 v[94:97], v[168:171], v[192:195], v[94:97]
	v_mfma_f32_16x16x32_bf16 v[90:93], v[176:179], v[192:195], v[90:93]
	v_mfma_f32_16x16x32_bf16 v[78:81], v[168:171], v[200:203], v[78:81]
	v_mfma_f32_16x16x32_bf16 v[74:77], v[176:179], v[200:203], v[74:77]
	v_mfma_f32_16x16x32_bf16 v[70:73], v[168:171], v[208:211], v[70:73]
	v_mfma_f32_16x16x32_bf16 v[66:69], v[176:179], v[208:211], v[66:69]
	s_setprio 0
	s_barrier
	s_mov_b32 m0, s53
	v_lshl_add_u64 v[148:149], v[148:149], 0, s[70:71]
	ds_read_b128 v[180:183], v139 offset:49152
	ds_read_b128 v[184:187], v139 offset:50176
	ds_read_b128 v[188:191], v139 offset:51200
	ds_read_b128 v[192:195], v139 offset:52224
	ds_read_b128 v[196:199], v139 offset:53248
	ds_read_b128 v[200:203], v139 offset:54272
	ds_read_b128 v[204:207], v139 offset:55296
	ds_read_b128 v[208:211], v139 offset:56320
	global_load_lds_dwordx4 v[148:149], off
	s_mov_b32 m0, s9
	v_lshl_add_u64 v[148:149], v[150:151], 0, s[70:71]
	global_load_lds_dwordx4 v[148:149], off
	s_mov_b32 m0, s96
	v_lshl_add_u64 v[148:149], s[38:39], 0, v[0:1]
	global_load_lds_dwordx4 v[148:149], off
	s_mov_b32 m0, s92
	v_lshl_add_u64 v[148:149], s[38:39], 0, v[130:131]
	global_load_lds_dwordx4 v[148:149], off
	s_mov_b32 m0, s46
	v_lshl_add_u64 v[148:149], v[212:213], 0, s[70:71]
	global_load_lds_dwordx4 v[148:149], off
	s_mov_b32 m0, s47
	v_lshl_add_u64 v[148:149], v[214:215], 0, s[70:71]
	global_load_lds_dwordx4 v[148:149], off
	s_waitcnt vmcnt(8)
	s_waitcnt lgkmcnt(0)
	s_barrier
	s_setprio 1
	v_mfma_f32_16x16x32_bf16 v[62:65], v[140:143], v[180:183], v[62:65]
	v_mfma_f32_16x16x32_bf16 v[58:61], v[156:159], v[180:183], v[58:61]
	v_mfma_f32_16x16x32_bf16 v[54:57], v[140:143], v[188:191], v[54:57]
	v_mfma_f32_16x16x32_bf16 v[50:53], v[156:159], v[188:191], v[50:53]
	v_mfma_f32_16x16x32_bf16 v[38:41], v[140:143], v[196:199], v[38:41]
	v_mfma_f32_16x16x32_bf16 v[34:37], v[156:159], v[196:199], v[34:37]
	v_mfma_f32_16x16x32_bf16 v[22:25], v[140:143], v[204:207], v[22:25]
	v_mfma_f32_16x16x32_bf16 v[18:21], v[156:159], v[204:207], v[18:21]
	v_mfma_f32_16x16x32_bf16 v[62:65], v[144:147], v[184:187], v[62:65]
	v_mfma_f32_16x16x32_bf16 v[58:61], v[160:163], v[184:187], v[58:61]
	v_mfma_f32_16x16x32_bf16 v[54:57], v[144:147], v[192:195], v[54:57]
	v_mfma_f32_16x16x32_bf16 v[50:53], v[160:163], v[192:195], v[50:53]
	v_mfma_f32_16x16x32_bf16 v[38:41], v[144:147], v[200:203], v[38:41]
	v_mfma_f32_16x16x32_bf16 v[34:37], v[160:163], v[200:203], v[34:37]
	v_mfma_f32_16x16x32_bf16 v[22:25], v[144:147], v[208:211], v[22:25]
	v_mfma_f32_16x16x32_bf16 v[18:21], v[160:163], v[208:211], v[18:21]
	v_mfma_f32_16x16x32_bf16 v[46:49], v[164:167], v[180:183], v[46:49]
	v_mfma_f32_16x16x32_bf16 v[42:45], v[172:175], v[180:183], v[42:45]
	v_mfma_f32_16x16x32_bf16 v[30:33], v[164:167], v[188:191], v[30:33]
	v_mfma_f32_16x16x32_bf16 v[26:29], v[172:175], v[188:191], v[26:29]
	v_mfma_f32_16x16x32_bf16 v[14:17], v[164:167], v[196:199], v[14:17]
	v_mfma_f32_16x16x32_bf16 v[10:13], v[172:175], v[196:199], v[10:13]
	v_mfma_f32_16x16x32_bf16 v[6:9], v[164:167], v[204:207], v[6:9]
	v_mfma_f32_16x16x32_bf16 v[2:5], v[172:175], v[204:207], v[2:5]
	v_mfma_f32_16x16x32_bf16 v[46:49], v[168:171], v[184:187], v[46:49]
	v_mfma_f32_16x16x32_bf16 v[42:45], v[176:179], v[184:187], v[42:45]
	v_mfma_f32_16x16x32_bf16 v[30:33], v[168:171], v[192:195], v[30:33]
	v_mfma_f32_16x16x32_bf16 v[26:29], v[176:179], v[192:195], v[26:29]
	v_mfma_f32_16x16x32_bf16 v[14:17], v[168:171], v[200:203], v[14:17]
	v_mfma_f32_16x16x32_bf16 v[10:13], v[176:179], v[200:203], v[10:13]
	v_mfma_f32_16x16x32_bf16 v[6:9], v[168:171], v[208:211], v[6:9]
	v_mfma_f32_16x16x32_bf16 v[2:5], v[176:179], v[208:211], v[2:5]
	s_setprio 0
	s_barrier
	s_movk_i32 s9, 0x100
	s_andn2_b64 vcc, exec, s[4:5]
	s_mov_b64 s[38:39], -1
	s_mov_b64 s[4:5], 0
	s_cbranch_vccz .LBB0_376
	s_and_b64 vcc, exec, s[14:15]
	s_cbranch_vccz .LBB0_379
	s_barrier

.LBB0_393:
	s_ashr_i32 s19, s18, 31
	s_lshl_b64 s[24:25], s[18:19], 16
	s_add_u32 s24, s29, s24
	s_addc_u32 s25, s38, s25
	s_and_b64 s[4:5], s[4:5], exec
	s_cselect_b32 s5, s25, s27
	s_cselect_b32 s4, s24, s26
	s_add_i32 s19, 0, 0x10000
	s_add_i32 s48, 0, 0x14000
	v_add_u32_e32 v14, s19, v137
	v_add_u32_e32 v30, s48, v137
	.p2align 6
	ds_read_b128 v[2:5], v14
	ds_read_b128 v[6:9], v14 offset:1024
	ds_read_b128 v[10:13], v14 offset:2048
	ds_read_b128 v[14:17], v14 offset:3072
	ds_read_b128 v[18:21], v30
	ds_read_b128 v[22:25], v30 offset:1024
	ds_read_b128 v[26:29], v30 offset:2048
	ds_read_b128 v[30:33], v30 offset:3072
	s_add_u32 s26, s36, 0x58080
	s_addc_u32 s27, s37, 0
	v_lshl_add_u64 v[66:67], s[26:27], 0, v[134:135]
	s_add_i32 m0, s40, 0xc000
	ds_read_b128 v[34:37], v139
	ds_read_b128 v[38:41], v139 offset:1024
	ds_read_b128 v[42:45], v139 offset:2048
	ds_read_b128 v[46:49], v139 offset:3072
	ds_read_b128 v[50:53], v139 offset:4096
	ds_read_b128 v[54:57], v139 offset:5120
	ds_read_b128 v[58:61], v139 offset:6144
	ds_read_b128 v[62:65], v139 offset:7168
	global_load_lds_dwordx4 v[66:67], off
	s_add_i32 m0, s40, 0xe000
	v_lshl_add_u64 v[66:67], s[26:27], 0, v[132:133]
	global_load_lds_dwordx4 v[66:67], off
	s_waitcnt vmcnt(8)
	s_waitcnt lgkmcnt(0)
	s_barrier
	s_setprio 1
	v_mfma_f32_16x16x32_bf16 v[66:69], v[2:5], v[34:37], 0
	v_mfma_f32_16x16x32_bf16 v[70:73], v[10:13], v[34:37], 0
	v_mfma_f32_16x16x32_bf16 v[74:77], v[2:5], v[42:45], 0
	v_mfma_f32_16x16x32_bf16 v[78:81], v[10:13], v[42:45], 0
	v_mfma_f32_16x16x32_bf16 v[82:85], v[2:5], v[50:53], 0
	v_mfma_f32_16x16x32_bf16 v[86:89], v[10:13], v[50:53], 0
	v_mfma_f32_16x16x32_bf16 v[90:93], v[2:5], v[58:61], 0
	v_mfma_f32_16x16x32_bf16 v[94:97], v[10:13], v[58:61], 0
	v_mfma_f32_16x16x32_bf16 v[66:69], v[6:9], v[38:41], v[66:69]
	v_mfma_f32_16x16x32_bf16 v[70:73], v[14:17], v[38:41], v[70:73]
	v_mfma_f32_16x16x32_bf16 v[74:77], v[6:9], v[46:49], v[74:77]
	v_mfma_f32_16x16x32_bf16 v[78:81], v[14:17], v[46:49], v[78:81]
	v_mfma_f32_16x16x32_bf16 v[82:85], v[6:9], v[54:57], v[82:85]
	v_mfma_f32_16x16x32_bf16 v[86:89], v[14:17], v[54:57], v[86:89]
	v_mfma_f32_16x16x32_bf16 v[90:93], v[6:9], v[62:65], v[90:93]
	v_mfma_f32_16x16x32_bf16 v[94:97], v[14:17], v[62:65], v[94:97]
	v_mfma_f32_16x16x32_bf16 v[98:101], v[18:21], v[34:37], 0
	v_mfma_f32_16x16x32_bf16 v[34:37], v[26:29], v[34:37], 0
	v_mfma_f32_16x16x32_bf16 v[98:101], v[22:25], v[38:41], v[98:101]
	v_mfma_f32_16x16x32_bf16 v[34:37], v[30:33], v[38:41], v[34:37]
	v_mfma_f32_16x16x32_bf16 v[38:41], v[18:21], v[42:45], 0
	v_mfma_f32_16x16x32_bf16 v[42:45], v[26:29], v[42:45], 0
	v_mfma_f32_16x16x32_bf16 v[102:105], v[30:33], v[46:49], v[42:45]
	v_mfma_f32_16x16x32_bf16 v[42:45], v[18:21], v[50:53], 0
	v_mfma_f32_16x16x32_bf16 v[114:117], v[22:25], v[54:57], v[42:45]
	v_mfma_f32_16x16x32_bf16 v[42:45], v[26:29], v[50:53], 0
	v_mfma_f32_16x16x32_bf16 v[50:53], v[30:33], v[54:57], v[42:45]
	v_mfma_f32_16x16x32_bf16 v[42:45], v[18:21], v[58:61], 0
	v_mfma_f32_16x16x32_bf16 v[54:57], v[22:25], v[62:65], v[42:45]
	v_mfma_f32_16x16x32_bf16 v[42:45], v[26:29], v[58:61], 0
	v_mfma_f32_16x16x32_bf16 v[38:41], v[22:25], v[46:49], v[38:41]
	v_mfma_f32_16x16x32_bf16 v[58:61], v[30:33], v[62:65], v[42:45]
	s_setprio 0
	s_barrier
	s_add_i32 s19, s19, s39
	v_lshl_add_u64 v[148:149], s[4:5], 0, v[0:1]
	s_mov_b32 m0, s19
	s_nop 0
	ds_read_b128 v[42:45], v139 offset:16384
	ds_read_b128 v[46:49], v139 offset:17408
	ds_read_b128 v[62:65], v139 offset:18432
	ds_read_b128 v[106:109], v139 offset:19456
	ds_read_b128 v[110:113], v139 offset:20480
	ds_read_b128 v[118:121], v139 offset:21504
	ds_read_b128 v[122:125], v139 offset:22528
	ds_read_b128 v[126:129], v139 offset:23552
	global_load_lds_dwordx4 v[148:149], off
	s_add_i32 m0, s19, 0x2000
	s_add_u32 s26, s4, 0x8000
	v_lshl_add_u64 v[150:151], s[4:5], 0, v[130:131]
	s_addc_u32 s27, s5, 0
	s_add_i32 s19, s48, s39
	global_load_lds_dwordx4 v[150:151], off
	v_lshl_add_u64 v[140:141], s[26:27], 0, v[0:1]
	s_mov_b32 m0, s19
	v_lshl_add_u64 v[252:253], s[22:23], 0, v[134:135]
	global_load_lds_dwordx4 v[140:141], off
	v_lshl_add_u64 v[140:141], s[26:27], 0, v[130:131]
	s_add_i32 m0, s19, 0x2000
	v_lshl_add_u64 v[242:243], s[22:23], 0, v[132:133]
	global_load_lds_dwordx4 v[140:141], off
	s_mov_b32 m0, s40
	s_nop 0
	global_load_lds_dwordx4 v[252:253], off
	s_mov_b32 m0, s41
	s_nop 0
	global_load_lds_dwordx4 v[242:243], off
	s_waitcnt vmcnt(8)
	s_waitcnt lgkmcnt(0)
	s_barrier
	s_setprio 1
	v_mfma_f32_16x16x32_bf16 v[140:143], v[2:5], v[42:45], 0
	v_mfma_f32_16x16x32_bf16 v[156:159], v[2:5], v[62:65], 0
	v_mfma_f32_16x16x32_bf16 v[164:167], v[2:5], v[110:113], 0
	v_mfma_f32_16x16x32_bf16 v[2:5], v[2:5], v[122:125], 0
	v_mfma_f32_16x16x32_bf16 v[140:143], v[6:9], v[46:49], v[140:143]
	v_mfma_f32_16x16x32_bf16 v[156:159], v[6:9], v[106:109], v[156:159]
	v_mfma_f32_16x16x32_bf16 v[164:167], v[6:9], v[118:121], v[164:167]
	v_mfma_f32_16x16x32_bf16 v[2:5], v[6:9], v[126:129], v[2:5]
	v_mfma_f32_16x16x32_bf16 v[6:9], v[10:13], v[122:125], 0
	v_mfma_f32_16x16x32_bf16 v[144:147], v[10:13], v[42:45], 0
	v_mfma_f32_16x16x32_bf16 v[160:163], v[10:13], v[62:65], 0
	v_mfma_f32_16x16x32_bf16 v[168:171], v[10:13], v[110:113], 0
	v_mfma_f32_16x16x32_bf16 v[6:9], v[14:17], v[126:129], v[6:9]
	v_mfma_f32_16x16x32_bf16 v[144:147], v[14:17], v[46:49], v[144:147]
	v_mfma_f32_16x16x32_bf16 v[160:163], v[14:17], v[106:109], v[160:163]
	v_mfma_f32_16x16x32_bf16 v[168:171], v[14:17], v[118:121], v[168:171]
	v_mfma_f32_16x16x32_bf16 v[10:13], v[18:21], v[42:45], 0
	v_mfma_f32_16x16x32_bf16 v[172:175], v[22:25], v[46:49], v[10:13]
	v_mfma_f32_16x16x32_bf16 v[10:13], v[26:29], v[42:45], 0
	v_mfma_f32_16x16x32_bf16 v[176:179], v[30:33], v[46:49], v[10:13]
	v_mfma_f32_16x16x32_bf16 v[10:13], v[18:21], v[62:65], 0
	v_mfma_f32_16x16x32_bf16 v[180:183], v[22:25], v[106:109], v[10:13]
	v_mfma_f32_16x16x32_bf16 v[10:13], v[26:29], v[62:65], 0
	v_mfma_f32_16x16x32_bf16 v[184:187], v[30:33], v[106:109], v[10:13]
	v_mfma_f32_16x16x32_bf16 v[10:13], v[18:21], v[110:113], 0
	v_mfma_f32_16x16x32_bf16 v[188:191], v[22:25], v[118:121], v[10:13]
	v_mfma_f32_16x16x32_bf16 v[10:13], v[26:29], v[110:113], 0
	v_mfma_f32_16x16x32_bf16 v[192:195], v[30:33], v[118:121], v[10:13]
	v_mfma_f32_16x16x32_bf16 v[10:13], v[18:21], v[122:125], 0
	v_mfma_f32_16x16x32_bf16 v[18:21], v[22:25], v[126:129], v[10:13]
	v_mfma_f32_16x16x32_bf16 v[10:13], v[26:29], v[122:125], 0
	v_mfma_f32_16x16x32_bf16 v[22:25], v[30:33], v[126:129], v[10:13]
	s_setprio 0
	s_barrier
	s_add_i32 s19, 0, 0x18000
	s_nop 3
	v_add_u32_e32 v10, s19, v137
	s_add_i32 s36, 0, 0x1c000
	ds_read_b128 v[118:121], v10
	ds_read_b128 v[196:199], v10 offset:1024
	ds_read_b128 v[200:203], v10 offset:2048
	ds_read_b128 v[204:207], v10 offset:3072
	v_add_u32_e32 v10, s36, v137
	ds_read_b128 v[208:211], v10
	ds_read_b128 v[212:215], v10 offset:1024
	ds_read_b128 v[216:219], v10 offset:2048
	ds_read_b128 v[220:223], v10 offset:3072
	s_add_u32 s26, s22, 0x58000
	s_addc_u32 s27, s23, 0
	s_mov_b32 m0, s42
	v_lshl_add_u64 v[10:11], s[26:27], 0, v[134:135]
	ds_read_b128 v[26:29], v139 offset:32768
	ds_read_b128 v[30:33], v139 offset:33792
	ds_read_b128 v[62:65], v139 offset:34816
	ds_read_b128 v[224:227], v139 offset:35840
	ds_read_b128 v[228:231], v139 offset:36864
	ds_read_b128 v[232:235], v139 offset:37888
	ds_read_b128 v[236:239], v139 offset:38912
	ds_read_b128 v[248:251], v139 offset:39936
	global_load_lds_dwordx4 v[10:11], off
	s_mov_b32 m0, s43
	v_lshl_add_u64 v[10:11], s[26:27], 0, v[132:133]
	global_load_lds_dwordx4 v[10:11], off
	s_waitcnt vmcnt(8)
	s_waitcnt lgkmcnt(0)
	s_barrier
	s_setprio 1
	v_mfma_f32_16x16x32_bf16 v[10:13], v[118:121], v[26:29], v[66:69]
	v_mfma_f32_16x16x32_bf16 v[106:109], v[196:199], v[30:33], v[10:13]
	v_mfma_f32_16x16x32_bf16 v[10:13], v[200:203], v[26:29], v[70:73]
	v_mfma_f32_16x16x32_bf16 v[110:113], v[204:207], v[30:33], v[10:13]
	v_mfma_f32_16x16x32_bf16 v[10:13], v[118:121], v[62:65], v[74:77]
	v_mfma_f32_16x16x32_bf16 v[74:77], v[196:199], v[224:227], v[10:13]
	v_mfma_f32_16x16x32_bf16 v[10:13], v[200:203], v[62:65], v[78:81]
	v_mfma_f32_16x16x32_bf16 v[78:81], v[204:207], v[224:227], v[10:13]
	v_mfma_f32_16x16x32_bf16 v[10:13], v[118:121], v[228:231], v[82:85]
	v_mfma_f32_16x16x32_bf16 v[42:45], v[196:199], v[232:235], v[10:13]
	v_mfma_f32_16x16x32_bf16 v[10:13], v[200:203], v[228:231], v[86:89]
	v_mfma_f32_16x16x32_bf16 v[46:49], v[204:207], v[232:235], v[10:13]
	v_mfma_f32_16x16x32_bf16 v[10:13], v[118:121], v[236:239], v[90:93]
	v_mfma_f32_16x16x32_bf16 v[14:17], v[200:203], v[236:239], v[94:97]
	v_mfma_f32_16x16x32_bf16 v[10:13], v[196:199], v[248:251], v[10:13]
	v_mfma_f32_16x16x32_bf16 v[14:17], v[204:207], v[248:251], v[14:17]
	v_mfma_f32_16x16x32_bf16 v[66:69], v[208:211], v[26:29], v[98:101]
	v_mfma_f32_16x16x32_bf16 v[26:29], v[216:219], v[26:29], v[34:37]
	v_mfma_f32_16x16x32_bf16 v[126:129], v[220:223], v[30:33], v[26:29]
	v_mfma_f32_16x16x32_bf16 v[26:29], v[208:211], v[62:65], v[38:41]
	v_mfma_f32_16x16x32_bf16 v[98:101], v[212:215], v[224:227], v[26:29]
	v_mfma_f32_16x16x32_bf16 v[26:29], v[216:219], v[62:65], v[102:105]
	v_mfma_f32_16x16x32_bf16 v[102:105], v[220:223], v[224:227], v[26:29]
	v_mfma_f32_16x16x32_bf16 v[26:29], v[208:211], v[228:231], v[114:117]
	v_mfma_f32_16x16x32_bf16 v[122:125], v[212:215], v[30:33], v[66:69]
	v_mfma_f32_16x16x32_bf16 v[66:69], v[212:215], v[232:235], v[26:29]
	v_mfma_f32_16x16x32_bf16 v[26:29], v[216:219], v[228:231], v[50:53]
	v_mfma_f32_16x16x32_bf16 v[70:73], v[220:223], v[232:235], v[26:29]
	v_mfma_f32_16x16x32_bf16 v[26:29], v[208:211], v[236:239], v[54:57]
	v_mfma_f32_16x16x32_bf16 v[34:37], v[212:215], v[248:251], v[26:29]
	v_mfma_f32_16x16x32_bf16 v[26:29], v[216:219], v[236:239], v[58:61]
	v_mfma_f32_16x16x32_bf16 v[38:41], v[220:223], v[248:251], v[26:29]
	s_setprio 0
	s_barrier
	s_add_i32 s19, s19, s39
	s_nop 3
	v_lshl_add_u64 v[26:27], v[148:149], 0, s[70:71]
	s_mov_b32 m0, s19
	ds_read_b128 v[50:53], v139 offset:49152
	ds_read_b128 v[54:57], v139 offset:50176
	ds_read_b128 v[86:89], v139 offset:51200
	ds_read_b128 v[224:227], v139 offset:52224
	ds_read_b128 v[228:231], v139 offset:53248
	ds_read_b128 v[232:235], v139 offset:54272
	ds_read_b128 v[236:239], v139 offset:55296
	ds_read_b128 v[248:251], v139 offset:56320
	global_load_lds_dwordx4 v[26:27], off
	s_add_i32 m0, s19, 0x2000
	s_add_u32 s4, s4, 0x8080
	v_lshl_add_u64 v[26:27], v[150:151], 0, s[70:71]
	s_addc_u32 s5, s5, 0
	s_add_i32 s19, s36, s39
	global_load_lds_dwordx4 v[26:27], off
	s_mov_b32 m0, s19
	v_lshl_add_u64 v[26:27], s[4:5], 0, v[0:1]
	global_load_lds_dwordx4 v[26:27], off
	s_add_i32 m0, s19, 0x2000
	v_lshl_add_u64 v[26:27], s[4:5], 0, v[130:131]
	global_load_lds_dwordx4 v[26:27], off
	s_mov_b32 m0, s44
	v_lshl_add_u64 v[26:27], v[252:253], 0, s[70:71]
	global_load_lds_dwordx4 v[26:27], off
	s_mov_b32 m0, s45
	v_lshl_add_u64 v[26:27], v[242:243], 0, s[70:71]
	global_load_lds_dwordx4 v[26:27], off
	s_waitcnt vmcnt(8)
	s_waitcnt lgkmcnt(0)
	s_barrier
	s_setprio 1
	v_mfma_f32_16x16x32_bf16 v[26:29], v[118:121], v[50:53], v[140:143]
	v_mfma_f32_16x16x32_bf16 v[90:93], v[196:199], v[54:57], v[26:29]
	v_mfma_f32_16x16x32_bf16 v[26:29], v[200:203], v[50:53], v[144:147]
	v_mfma_f32_16x16x32_bf16 v[94:97], v[204:207], v[54:57], v[26:29]
	v_mfma_f32_16x16x32_bf16 v[26:29], v[118:121], v[86:89], v[156:159]
	v_mfma_f32_16x16x32_bf16 v[58:61], v[196:199], v[224:227], v[26:29]
	v_mfma_f32_16x16x32_bf16 v[26:29], v[200:203], v[86:89], v[160:163]
	v_mfma_f32_16x16x32_bf16 v[62:65], v[204:207], v[224:227], v[26:29]
	v_mfma_f32_16x16x32_bf16 v[26:29], v[118:121], v[228:231], v[164:167]
	v_mfma_f32_16x16x32_bf16 v[30:33], v[200:203], v[228:231], v[168:171]
	v_mfma_f32_16x16x32_bf16 v[2:5], v[118:121], v[236:239], v[2:5]
	v_mfma_f32_16x16x32_bf16 v[6:9], v[200:203], v[236:239], v[6:9]
	v_mfma_f32_16x16x32_bf16 v[26:29], v[196:199], v[232:235], v[26:29]
	v_mfma_f32_16x16x32_bf16 v[30:33], v[204:207], v[232:235], v[30:33]
	v_mfma_f32_16x16x32_bf16 v[2:5], v[196:199], v[248:251], v[2:5]
	v_mfma_f32_16x16x32_bf16 v[6:9], v[204:207], v[248:251], v[6:9]
	v_mfma_f32_16x16x32_bf16 v[82:85], v[208:211], v[50:53], v[172:175]
	v_mfma_f32_16x16x32_bf16 v[50:53], v[216:219], v[50:53], v[176:179]
	v_mfma_f32_16x16x32_bf16 v[118:121], v[220:223], v[54:57], v[50:53]
	v_mfma_f32_16x16x32_bf16 v[50:53], v[208:211], v[86:89], v[180:183]
	v_mfma_f32_16x16x32_bf16 v[114:117], v[212:215], v[54:57], v[82:85]
	v_mfma_f32_16x16x32_bf16 v[82:85], v[212:215], v[224:227], v[50:53]
	v_mfma_f32_16x16x32_bf16 v[50:53], v[216:219], v[86:89], v[184:187]
	v_mfma_f32_16x16x32_bf16 v[86:89], v[220:223], v[224:227], v[50:53]
	v_mfma_f32_16x16x32_bf16 v[50:53], v[208:211], v[228:231], v[188:191]
	v_mfma_f32_16x16x32_bf16 v[54:57], v[216:219], v[228:231], v[192:195]
	v_mfma_f32_16x16x32_bf16 v[18:21], v[208:211], v[236:239], v[18:21]
	v_mfma_f32_16x16x32_bf16 v[22:25], v[216:219], v[236:239], v[22:25]
	v_mfma_f32_16x16x32_bf16 v[50:53], v[212:215], v[232:235], v[50:53]
	v_mfma_f32_16x16x32_bf16 v[54:57], v[220:223], v[232:235], v[54:57]
	v_mfma_f32_16x16x32_bf16 v[18:21], v[212:215], v[248:251], v[18:21]
	v_mfma_f32_16x16x32_bf16 v[22:25], v[220:223], v[248:251], v[22:25]
	s_setprio 0
	s_barrier
	s_andn2_b64 vcc, exec, s[14:15]
	s_cbranch_vccnz .LBB0_395
	s_barrier

.LBB0_701:
	s_add_i32 s75, s26, 2
	s_add_u32 s9, s60, 0xfffc0080
	s_addc_u32 s27, s61, -1
	s_add_i32 s78, 0, 0x10000
	s_cmp_eq_u32 s19, s26
	s_cselect_b32 s73, s23, s27
	s_cselect_b32 s72, s22, s9
	s_cselect_b32 s27, s25, s29
	s_cselect_b32 s26, s24, s28
	s_add_i32 s9, 0, 0x14000
	s_waitcnt vmcnt(0)
	v_add_u32_e32 v142, s78, v177
	v_add_u32_e32 v148, s9, v177
	ds_read_b128 v[130:133], v142
	ds_read_b128 v[134:137], v142 offset:1024
	ds_read_b128 v[138:141], v142 offset:2048
	ds_read_b128 v[142:145], v142 offset:3072
	ds_read_b128 v[164:167], v148
	ds_read_b128 v[168:171], v148 offset:1024
	ds_read_b128 v[172:175], v148 offset:2048
	ds_read_b128 v[180:183], v148 offset:3072
	v_lshl_add_u64 v[148:149], s[60:61], 0, v[160:161]
	s_add_i32 m0, s37, 0xc000
	ds_read_b128 v[184:187], v179
	ds_read_b128 v[188:191], v179 offset:1024
	ds_read_b128 v[192:195], v179 offset:2048
	ds_read_b128 v[196:199], v179 offset:3072
	ds_read_b128 v[200:203], v179 offset:4096
	ds_read_b128 v[204:207], v179 offset:5120
	ds_read_b128 v[208:211], v179 offset:6144
	ds_read_b128 v[212:215], v179 offset:7168
	global_load_lds_dwordx4 v[148:149], off
	s_add_i32 m0, s37, 0xe000
	v_lshl_add_u64 v[148:149], s[60:61], 0, v[162:163]
	global_load_lds_dwordx4 v[148:149], off
	s_waitcnt vmcnt(8)
	s_waitcnt lgkmcnt(0)
	s_barrier
	s_setprio 1
	v_mfma_f32_16x16x32_bf16 v[126:129], v[130:133], v[184:187], v[126:129]
	v_mfma_f32_16x16x32_bf16 v[122:125], v[138:141], v[184:187], v[122:125]
	v_mfma_f32_16x16x32_bf16 v[110:113], v[130:133], v[192:195], v[110:113]
	v_mfma_f32_16x16x32_bf16 v[106:109], v[138:141], v[192:195], v[106:109]
	v_mfma_f32_16x16x32_bf16 v[94:97], v[130:133], v[200:203], v[94:97]
	v_mfma_f32_16x16x32_bf16 v[90:93], v[138:141], v[200:203], v[90:93]
	v_mfma_f32_16x16x32_bf16 v[78:81], v[130:133], v[208:211], v[78:81]
	v_mfma_f32_16x16x32_bf16 v[74:77], v[138:141], v[208:211], v[74:77]
	v_mfma_f32_16x16x32_bf16 v[126:129], v[134:137], v[188:191], v[126:129]
	v_mfma_f32_16x16x32_bf16 v[122:125], v[142:145], v[188:191], v[122:125]
	v_mfma_f32_16x16x32_bf16 v[110:113], v[134:137], v[196:199], v[110:113]
	v_mfma_f32_16x16x32_bf16 v[106:109], v[142:145], v[196:199], v[106:109]
	v_mfma_f32_16x16x32_bf16 v[94:97], v[134:137], v[204:207], v[94:97]
	v_mfma_f32_16x16x32_bf16 v[90:93], v[142:145], v[204:207], v[90:93]
	v_mfma_f32_16x16x32_bf16 v[78:81], v[134:137], v[212:215], v[78:81]
	v_mfma_f32_16x16x32_bf16 v[74:77], v[142:145], v[212:215], v[74:77]
	v_mfma_f32_16x16x32_bf16 v[118:121], v[164:167], v[184:187], v[118:121]
	v_mfma_f32_16x16x32_bf16 v[114:117], v[172:175], v[184:187], v[114:117]
	v_mfma_f32_16x16x32_bf16 v[102:105], v[164:167], v[192:195], v[102:105]
	v_mfma_f32_16x16x32_bf16 v[98:101], v[172:175], v[192:195], v[98:101]
	v_mfma_f32_16x16x32_bf16 v[86:89], v[164:167], v[200:203], v[86:89]
	v_mfma_f32_16x16x32_bf16 v[82:85], v[172:175], v[200:203], v[82:85]
	v_mfma_f32_16x16x32_bf16 v[70:73], v[164:167], v[208:211], v[70:73]
	v_mfma_f32_16x16x32_bf16 v[66:69], v[172:175], v[208:211], v[66:69]
	v_mfma_f32_16x16x32_bf16 v[118:121], v[168:171], v[188:191], v[118:121]
	v_mfma_f32_16x16x32_bf16 v[114:117], v[180:183], v[188:191], v[114:117]
	v_mfma_f32_16x16x32_bf16 v[102:105], v[168:171], v[196:199], v[102:105]
	v_mfma_f32_16x16x32_bf16 v[98:101], v[180:183], v[196:199], v[98:101]
	v_mfma_f32_16x16x32_bf16 v[86:89], v[168:171], v[204:207], v[86:89]
	v_mfma_f32_16x16x32_bf16 v[82:85], v[180:183], v[204:207], v[82:85]
	v_mfma_f32_16x16x32_bf16 v[70:73], v[168:171], v[212:215], v[70:73]
	v_mfma_f32_16x16x32_bf16 v[66:69], v[180:183], v[212:215], v[66:69]
	s_setprio 0
	s_barrier
	s_add_i32 s78, s78, s41
	v_lshl_add_u64 v[148:149], s[26:27], 0, v[0:1]
	s_mov_b32 m0, s78
	ds_read_b128 v[184:187], v179 offset:16384
	ds_read_b128 v[188:191], v179 offset:17408
	ds_read_b128 v[192:195], v179 offset:18432
	ds_read_b128 v[196:199], v179 offset:19456
	ds_read_b128 v[200:203], v179 offset:20480
	ds_read_b128 v[204:207], v179 offset:21504
	ds_read_b128 v[208:211], v179 offset:22528
	ds_read_b128 v[212:215], v179 offset:23552
	global_load_lds_dwordx4 v[148:149], off
	s_add_i32 m0, s78, 0x2000
	s_add_u32 s78, s26, 0x40000
	v_lshl_add_u64 v[150:151], s[26:27], 0, v[158:159]
	s_addc_u32 s79, s27, 0
	s_add_i32 s9, s9, s41
	global_load_lds_dwordx4 v[150:151], off
	v_lshl_add_u64 v[216:217], s[78:79], 0, v[0:1]
	s_mov_b32 m0, s9
	v_lshl_add_u64 v[218:219], s[72:73], 0, v[156:157]
	global_load_lds_dwordx4 v[216:217], off
	s_add_i32 m0, s9, 0x2000
	v_lshl_add_u64 v[216:217], s[78:79], 0, v[158:159]
	global_load_lds_dwordx4 v[216:217], off
	s_mov_b32 m0, s37
	v_lshl_add_u64 v[216:217], s[72:73], 0, v[146:147]
	global_load_lds_dwordx4 v[216:217], off
	s_mov_b32 m0, s39
	s_nop 0
	global_load_lds_dwordx4 v[218:219], off
	s_waitcnt vmcnt(8)
	s_waitcnt lgkmcnt(0)
	s_barrier
	s_setprio 1
	v_mfma_f32_16x16x32_bf16 v[62:65], v[130:133], v[184:187], v[62:65]
	v_mfma_f32_16x16x32_bf16 v[58:61], v[138:141], v[184:187], v[58:61]
	v_mfma_f32_16x16x32_bf16 v[46:49], v[130:133], v[192:195], v[46:49]
	v_mfma_f32_16x16x32_bf16 v[42:45], v[138:141], v[192:195], v[42:45]
	v_mfma_f32_16x16x32_bf16 v[30:33], v[130:133], v[200:203], v[30:33]
	v_mfma_f32_16x16x32_bf16 v[26:29], v[138:141], v[200:203], v[26:29]
	v_mfma_f32_16x16x32_bf16 v[14:17], v[130:133], v[208:211], v[14:17]
	v_mfma_f32_16x16x32_bf16 v[10:13], v[138:141], v[208:211], v[10:13]
	v_mfma_f32_16x16x32_bf16 v[62:65], v[134:137], v[188:191], v[62:65]
	v_mfma_f32_16x16x32_bf16 v[58:61], v[142:145], v[188:191], v[58:61]
	v_mfma_f32_16x16x32_bf16 v[46:49], v[134:137], v[196:199], v[46:49]
	v_mfma_f32_16x16x32_bf16 v[42:45], v[142:145], v[196:199], v[42:45]
	v_mfma_f32_16x16x32_bf16 v[30:33], v[134:137], v[204:207], v[30:33]
	v_mfma_f32_16x16x32_bf16 v[26:29], v[142:145], v[204:207], v[26:29]
	v_mfma_f32_16x16x32_bf16 v[14:17], v[134:137], v[212:215], v[14:17]
	v_mfma_f32_16x16x32_bf16 v[10:13], v[142:145], v[212:215], v[10:13]
	v_mfma_f32_16x16x32_bf16 v[54:57], v[164:167], v[184:187], v[54:57]
	v_mfma_f32_16x16x32_bf16 v[50:53], v[172:175], v[184:187], v[50:53]
	v_mfma_f32_16x16x32_bf16 v[38:41], v[164:167], v[192:195], v[38:41]
	v_mfma_f32_16x16x32_bf16 v[34:37], v[172:175], v[192:195], v[34:37]
	v_mfma_f32_16x16x32_bf16 v[22:25], v[164:167], v[200:203], v[22:25]
	v_mfma_f32_16x16x32_bf16 v[18:21], v[172:175], v[200:203], v[18:21]
	v_mfma_f32_16x16x32_bf16 v[6:9], v[164:167], v[208:211], v[6:9]
	v_mfma_f32_16x16x32_bf16 v[2:5], v[172:175], v[208:211], v[2:5]
	v_mfma_f32_16x16x32_bf16 v[54:57], v[168:171], v[188:191], v[54:57]
	v_mfma_f32_16x16x32_bf16 v[50:53], v[180:183], v[188:191], v[50:53]
	v_mfma_f32_16x16x32_bf16 v[38:41], v[168:171], v[196:199], v[38:41]
	v_mfma_f32_16x16x32_bf16 v[34:37], v[180:183], v[196:199], v[34:37]
	v_mfma_f32_16x16x32_bf16 v[22:25], v[168:171], v[204:207], v[22:25]
	v_mfma_f32_16x16x32_bf16 v[18:21], v[180:183], v[204:207], v[18:21]
	v_mfma_f32_16x16x32_bf16 v[6:9], v[168:171], v[212:215], v[6:9]
	v_mfma_f32_16x16x32_bf16 v[2:5], v[180:183], v[212:215], v[2:5]
	s_setprio 0
	s_barrier
	s_add_i32 s9, 0, 0x18000
	s_add_i32 s78, 0, 0x1c000
	v_add_u32_e32 v142, s9, v177
	v_add_u32_e32 v180, s78, v177
	ds_read_b128 v[130:133], v142
	ds_read_b128 v[134:137], v142 offset:1024
	ds_read_b128 v[138:141], v142 offset:2048
	ds_read_b128 v[142:145], v142 offset:3072
	ds_read_b128 v[164:167], v180
	ds_read_b128 v[168:171], v180 offset:1024
	ds_read_b128 v[172:175], v180 offset:2048
	ds_read_b128 v[180:183], v180 offset:3072
	s_add_u32 s72, s72, 0x40000
	s_addc_u32 s73, s73, 0
	s_mov_b32 m0, s44
	v_lshl_add_u64 v[220:221], s[72:73], 0, v[146:147]
	ds_read_b128 v[184:187], v179 offset:32768
	ds_read_b128 v[188:191], v179 offset:33792
	ds_read_b128 v[192:195], v179 offset:34816
	ds_read_b128 v[196:199], v179 offset:35840
	ds_read_b128 v[200:203], v179 offset:36864
	ds_read_b128 v[204:207], v179 offset:37888
	ds_read_b128 v[208:211], v179 offset:38912
	ds_read_b128 v[212:215], v179 offset:39936
	global_load_lds_dwordx4 v[220:221], off
	s_mov_b32 m0, s45
	v_lshl_add_u64 v[220:221], s[72:73], 0, v[156:157]
	global_load_lds_dwordx4 v[220:221], off
	s_waitcnt vmcnt(8)
	s_waitcnt lgkmcnt(0)
	s_barrier
	s_setprio 1
	v_mfma_f32_16x16x32_bf16 v[126:129], v[130:133], v[184:187], v[126:129]
	v_mfma_f32_16x16x32_bf16 v[122:125], v[138:141], v[184:187], v[122:125]
	v_mfma_f32_16x16x32_bf16 v[110:113], v[130:133], v[192:195], v[110:113]
	v_mfma_f32_16x16x32_bf16 v[106:109], v[138:141], v[192:195], v[106:109]
	v_mfma_f32_16x16x32_bf16 v[94:97], v[130:133], v[200:203], v[94:97]
	v_mfma_f32_16x16x32_bf16 v[90:93], v[138:141], v[200:203], v[90:93]
	v_mfma_f32_16x16x32_bf16 v[78:81], v[130:133], v[208:211], v[78:81]
	v_mfma_f32_16x16x32_bf16 v[74:77], v[138:141], v[208:211], v[74:77]
	v_mfma_f32_16x16x32_bf16 v[126:129], v[134:137], v[188:191], v[126:129]
	v_mfma_f32_16x16x32_bf16 v[122:125], v[142:145], v[188:191], v[122:125]
	v_mfma_f32_16x16x32_bf16 v[110:113], v[134:137], v[196:199], v[110:113]
	v_mfma_f32_16x16x32_bf16 v[106:109], v[142:145], v[196:199], v[106:109]
	v_mfma_f32_16x16x32_bf16 v[94:97], v[134:137], v[204:207], v[94:97]
	v_mfma_f32_16x16x32_bf16 v[90:93], v[142:145], v[204:207], v[90:93]
	v_mfma_f32_16x16x32_bf16 v[78:81], v[134:137], v[212:215], v[78:81]
	v_mfma_f32_16x16x32_bf16 v[74:77], v[142:145], v[212:215], v[74:77]
	v_mfma_f32_16x16x32_bf16 v[118:121], v[164:167], v[184:187], v[118:121]
	v_mfma_f32_16x16x32_bf16 v[114:117], v[172:175], v[184:187], v[114:117]
	v_mfma_f32_16x16x32_bf16 v[102:105], v[164:167], v[192:195], v[102:105]
	v_mfma_f32_16x16x32_bf16 v[98:101], v[172:175], v[192:195], v[98:101]
	v_mfma_f32_16x16x32_bf16 v[86:89], v[164:167], v[200:203], v[86:89]
	v_mfma_f32_16x16x32_bf16 v[82:85], v[172:175], v[200:203], v[82:85]
	v_mfma_f32_16x16x32_bf16 v[70:73], v[164:167], v[208:211], v[70:73]
	v_mfma_f32_16x16x32_bf16 v[66:69], v[172:175], v[208:211], v[66:69]
	v_mfma_f32_16x16x32_bf16 v[118:121], v[168:171], v[188:191], v[118:121]
	v_mfma_f32_16x16x32_bf16 v[114:117], v[180:183], v[188:191], v[114:117]
	v_mfma_f32_16x16x32_bf16 v[102:105], v[168:171], v[196:199], v[102:105]
	v_mfma_f32_16x16x32_bf16 v[98:101], v[180:183], v[196:199], v[98:101]
	v_mfma_f32_16x16x32_bf16 v[86:89], v[168:171], v[204:207], v[86:89]
	v_mfma_f32_16x16x32_bf16 v[82:85], v[180:183], v[204:207], v[82:85]
	v_mfma_f32_16x16x32_bf16 v[70:73], v[168:171], v[212:215], v[70:73]
	v_mfma_f32_16x16x32_bf16 v[66:69], v[180:183], v[212:215], v[66:69]
	s_setprio 0
	s_barrier
	s_add_i32 s9, s9, s41
	v_lshl_add_u64 v[148:149], v[148:149], 0, s[70:71]
	s_mov_b32 m0, s9
	ds_read_b128 v[184:187], v179 offset:49152
	ds_read_b128 v[188:191], v179 offset:50176
	ds_read_b128 v[192:195], v179 offset:51200
	ds_read_b128 v[196:199], v179 offset:52224
	ds_read_b128 v[200:203], v179 offset:53248
	ds_read_b128 v[204:207], v179 offset:54272
	ds_read_b128 v[208:211], v179 offset:55296
	ds_read_b128 v[212:215], v179 offset:56320
	global_load_lds_dwordx4 v[148:149], off
	s_add_i32 m0, s9, 0x2000
	s_add_u32 s26, s26, 0x40080
	v_lshl_add_u64 v[148:149], v[150:151], 0, s[70:71]
	s_addc_u32 s27, s27, 0
	s_add_i32 s9, s78, s41
	global_load_lds_dwordx4 v[148:149], off
	s_mov_b32 m0, s9
	v_lshl_add_u64 v[148:149], s[26:27], 0, v[0:1]
	global_load_lds_dwordx4 v[148:149], off
	s_add_i32 m0, s9, 0x2000
	v_lshl_add_u64 v[148:149], s[26:27], 0, v[158:159]
	global_load_lds_dwordx4 v[148:149], off
	s_mov_b32 m0, s50
	v_lshl_add_u64 v[148:149], v[216:217], 0, s[70:71]
	global_load_lds_dwordx4 v[148:149], off
	s_mov_b32 m0, s51
	v_lshl_add_u64 v[148:149], v[218:219], 0, s[70:71]
	global_load_lds_dwordx4 v[148:149], off
	s_waitcnt vmcnt(8)
	s_waitcnt lgkmcnt(0)
	s_barrier
	s_setprio 1
	v_mfma_f32_16x16x32_bf16 v[62:65], v[130:133], v[184:187], v[62:65]
	v_mfma_f32_16x16x32_bf16 v[58:61], v[138:141], v[184:187], v[58:61]
	v_mfma_f32_16x16x32_bf16 v[46:49], v[130:133], v[192:195], v[46:49]
	v_mfma_f32_16x16x32_bf16 v[42:45], v[138:141], v[192:195], v[42:45]
	v_mfma_f32_16x16x32_bf16 v[30:33], v[130:133], v[200:203], v[30:33]
	v_mfma_f32_16x16x32_bf16 v[26:29], v[138:141], v[200:203], v[26:29]
	v_mfma_f32_16x16x32_bf16 v[14:17], v[130:133], v[208:211], v[14:17]
	v_mfma_f32_16x16x32_bf16 v[10:13], v[138:141], v[208:211], v[10:13]
	v_mfma_f32_16x16x32_bf16 v[62:65], v[134:137], v[188:191], v[62:65]
	v_mfma_f32_16x16x32_bf16 v[58:61], v[142:145], v[188:191], v[58:61]
	v_mfma_f32_16x16x32_bf16 v[46:49], v[134:137], v[196:199], v[46:49]
	v_mfma_f32_16x16x32_bf16 v[42:45], v[142:145], v[196:199], v[42:45]
	v_mfma_f32_16x16x32_bf16 v[30:33], v[134:137], v[204:207], v[30:33]
	v_mfma_f32_16x16x32_bf16 v[26:29], v[142:145], v[204:207], v[26:29]
	v_mfma_f32_16x16x32_bf16 v[14:17], v[134:137], v[212:215], v[14:17]
	v_mfma_f32_16x16x32_bf16 v[10:13], v[142:145], v[212:215], v[10:13]
	v_mfma_f32_16x16x32_bf16 v[54:57], v[164:167], v[184:187], v[54:57]
	v_mfma_f32_16x16x32_bf16 v[50:53], v[172:175], v[184:187], v[50:53]
	v_mfma_f32_16x16x32_bf16 v[38:41], v[164:167], v[192:195], v[38:41]
	v_mfma_f32_16x16x32_bf16 v[34:37], v[172:175], v[192:195], v[34:37]
	v_mfma_f32_16x16x32_bf16 v[22:25], v[164:167], v[200:203], v[22:25]
	v_mfma_f32_16x16x32_bf16 v[18:21], v[172:175], v[200:203], v[18:21]
	v_mfma_f32_16x16x32_bf16 v[6:9], v[164:167], v[208:211], v[6:9]
	v_mfma_f32_16x16x32_bf16 v[2:5], v[172:175], v[208:211], v[2:5]
	v_mfma_f32_16x16x32_bf16 v[54:57], v[168:171], v[188:191], v[54:57]
	v_mfma_f32_16x16x32_bf16 v[50:53], v[180:183], v[188:191], v[50:53]
	v_mfma_f32_16x16x32_bf16 v[38:41], v[168:171], v[196:199], v[38:41]
	v_mfma_f32_16x16x32_bf16 v[34:37], v[180:183], v[196:199], v[34:37]
	v_mfma_f32_16x16x32_bf16 v[22:25], v[168:171], v[204:207], v[22:25]
	v_mfma_f32_16x16x32_bf16 v[18:21], v[180:183], v[204:207], v[18:21]
	v_mfma_f32_16x16x32_bf16 v[6:9], v[168:171], v[212:215], v[6:9]
	v_mfma_f32_16x16x32_bf16 v[2:5], v[180:183], v[212:215], v[2:5]
	s_setprio 0
	s_barrier
	s_add_u32 s60, s60, 0x100
	s_addc_u32 s61, s61, 0
	s_add_u32 s28, s28, 0x100
	s_addc_u32 s29, s29, 0
	s_cmp_ge_u32 s75, s17
	s_mov_b32 s26, s75
	s_cbranch_scc0 .LBB0_701
	s_and_b64 vcc, exec, s[14:15]
	s_cbranch_vccz .LBB0_704

.LBB0_783:
	v_lshlrev_b64 v[38:39], 1, v[38:39]
	v_lshl_add_u64 v[46:47], s[36:37], 0, v[38:39]
	v_lshl_add_u64 v[40:41], s[38:39], 0, v[38:39]
	v_lshl_add_u64 v[42:43], s[60:61], 0, v[38:39]
	v_lshl_add_u64 v[44:45], s[74:75], 0, v[38:39]
	global_load_dwordx2 v[134:135], v[46:47], off
	global_load_dwordx2 v[136:137], v[40:41], off
	global_load_dwordx2 v[138:139], v[42:43], off
	global_load_dwordx2 v[140:141], v[44:45], off
	global_load_dwordx2 v[142:143], v[46:47], off offset:512
	global_load_dwordx2 v[144:145], v[40:41], off offset:512
	global_load_dwordx2 v[146:147], v[42:43], off offset:512
	global_load_dwordx2 v[148:149], v[44:45], off offset:512
	global_load_dwordx2 v[150:151], v[46:47], off offset:1024
	global_load_dwordx2 v[156:157], v[40:41], off offset:1024
	global_load_dwordx2 v[158:159], v[42:43], off offset:1024
	global_load_dwordx2 v[160:161], v[44:45], off offset:1024
	global_load_dwordx2 v[162:163], v[46:47], off offset:1536
	global_load_dwordx2 v[164:165], v[40:41], off offset:1536
	global_load_dwordx2 v[166:167], v[42:43], off offset:1536
	global_load_dwordx2 v[168:169], v[44:45], off offset:1536
	v_lshl_add_u64 v[38:39], s[14:15], 0, v[38:39]
	s_waitcnt vmcnt(15)
	v_cvt_f32_f16_e32 v64, v134
	v_cvt_f32_f16_sdwa v65, v134 dst_sel:DWORD dst_unused:UNUSED_PAD src0_sel:WORD_1
	v_cvt_f32_f16_e32 v56, v135
	v_cvt_f32_f16_sdwa v57, v135 dst_sel:DWORD dst_unused:UNUSED_PAD src0_sel:WORD_1
	s_waitcnt vmcnt(14)
	v_cvt_f32_f16_e32 v66, v136
	v_cvt_f32_f16_sdwa v67, v136 dst_sel:DWORD dst_unused:UNUSED_PAD src0_sel:WORD_1
	v_cvt_f32_f16_e32 v58, v137
	v_cvt_f32_f16_sdwa v59, v137 dst_sel:DWORD dst_unused:UNUSED_PAD src0_sel:WORD_1
	s_waitcnt vmcnt(13)
	v_cvt_f32_f16_e32 v68, v138
	v_cvt_f32_f16_sdwa v69, v138 dst_sel:DWORD dst_unused:UNUSED_PAD src0_sel:WORD_1
	v_cvt_f32_f16_e32 v60, v139
	v_cvt_f32_f16_sdwa v61, v139 dst_sel:DWORD dst_unused:UNUSED_PAD src0_sel:WORD_1
	s_waitcnt vmcnt(12)
	v_cvt_f32_f16_e32 v70, v140
	v_cvt_f32_f16_sdwa v71, v140 dst_sel:DWORD dst_unused:UNUSED_PAD src0_sel:WORD_1
	v_cvt_f32_f16_e32 v62, v141
	v_cvt_f32_f16_sdwa v63, v141 dst_sel:DWORD dst_unused:UNUSED_PAD src0_sel:WORD_1
	v_pk_add_f32 v[64:65], v[64:65], v[66:67]
	v_pk_add_f32 v[56:57], v[56:57], v[58:59]
	v_pk_add_f32 v[58:59], v[68:69], v[70:71]
	v_pk_add_f32 v[60:61], v[60:61], v[62:63]
	v_pk_add_f32 v[58:59], v[64:65], v[58:59]
	v_pk_add_f32 v[56:57], v[56:57], v[60:61]
	v_pk_add_f32 v[30:31], v[30:31], v[58:59]
	v_pk_add_f32 v[32:33], v[32:33], v[56:57]
	v_cvt_pk_f16_f32 v56, v30, v31
	v_cvt_pk_f16_f32 v57, v32, v33
	global_store_dwordx2 v[38:39], v[56:57], off
	s_waitcnt vmcnt(12)
	v_cvt_f32_f16_e32 v64, v142
	v_cvt_f32_f16_sdwa v65, v142 dst_sel:DWORD dst_unused:UNUSED_PAD src0_sel:WORD_1
	v_cvt_f32_f16_e32 v56, v143
	v_cvt_f32_f16_sdwa v57, v143 dst_sel:DWORD dst_unused:UNUSED_PAD src0_sel:WORD_1
	s_waitcnt vmcnt(11)
	v_cvt_f32_f16_e32 v66, v144
	v_cvt_f32_f16_sdwa v67, v144 dst_sel:DWORD dst_unused:UNUSED_PAD src0_sel:WORD_1
	v_cvt_f32_f16_e32 v58, v145
	v_cvt_f32_f16_sdwa v59, v145 dst_sel:DWORD dst_unused:UNUSED_PAD src0_sel:WORD_1
	s_waitcnt vmcnt(10)
	v_cvt_f32_f16_e32 v68, v146
	v_cvt_f32_f16_sdwa v69, v146 dst_sel:DWORD dst_unused:UNUSED_PAD src0_sel:WORD_1
	v_cvt_f32_f16_e32 v60, v147
	v_cvt_f32_f16_sdwa v61, v147 dst_sel:DWORD dst_unused:UNUSED_PAD src0_sel:WORD_1
	s_waitcnt vmcnt(9)
	v_cvt_f32_f16_e32 v70, v148
	v_cvt_f32_f16_sdwa v71, v148 dst_sel:DWORD dst_unused:UNUSED_PAD src0_sel:WORD_1
	v_cvt_f32_f16_e32 v62, v149
	v_cvt_f32_f16_sdwa v63, v149 dst_sel:DWORD dst_unused:UNUSED_PAD src0_sel:WORD_1
	v_pk_add_f32 v[64:65], v[64:65], v[66:67]
	v_pk_add_f32 v[56:57], v[56:57], v[58:59]
	v_pk_add_f32 v[58:59], v[68:69], v[70:71]
	v_pk_add_f32 v[60:61], v[60:61], v[62:63]
	v_pk_add_f32 v[58:59], v[64:65], v[58:59]
	v_pk_add_f32 v[56:57], v[56:57], v[60:61]
	v_pk_add_f32 v[26:27], v[26:27], v[58:59]
	v_pk_add_f32 v[28:29], v[28:29], v[56:57]
	v_cvt_pk_f16_f32 v56, v26, v27
	v_cvt_pk_f16_f32 v57, v28, v29
	global_store_dwordx2 v[38:39], v[56:57], off offset:512
	s_waitcnt vmcnt(9)
	v_cvt_f32_f16_e32 v64, v150
	v_cvt_f32_f16_sdwa v65, v150 dst_sel:DWORD dst_unused:UNUSED_PAD src0_sel:WORD_1
	v_cvt_f32_f16_e32 v56, v151
	v_cvt_f32_f16_sdwa v57, v151 dst_sel:DWORD dst_unused:UNUSED_PAD src0_sel:WORD_1
	s_waitcnt vmcnt(8)
	v_cvt_f32_f16_e32 v66, v156
	v_cvt_f32_f16_sdwa v67, v156 dst_sel:DWORD dst_unused:UNUSED_PAD src0_sel:WORD_1
	v_cvt_f32_f16_e32 v58, v157
	v_cvt_f32_f16_sdwa v59, v157 dst_sel:DWORD dst_unused:UNUSED_PAD src0_sel:WORD_1
	s_waitcnt vmcnt(7)
	v_cvt_f32_f16_e32 v68, v158
	v_cvt_f32_f16_sdwa v69, v158 dst_sel:DWORD dst_unused:UNUSED_PAD src0_sel:WORD_1
	v_cvt_f32_f16_e32 v60, v159
	v_cvt_f32_f16_sdwa v61, v159 dst_sel:DWORD dst_unused:UNUSED_PAD src0_sel:WORD_1
	s_waitcnt vmcnt(6)
	v_cvt_f32_f16_e32 v70, v160
	v_cvt_f32_f16_sdwa v71, v160 dst_sel:DWORD dst_unused:UNUSED_PAD src0_sel:WORD_1
	v_cvt_f32_f16_e32 v62, v161
	v_cvt_f32_f16_sdwa v63, v161 dst_sel:DWORD dst_unused:UNUSED_PAD src0_sel:WORD_1
	v_pk_add_f32 v[64:65], v[64:65], v[66:67]
	v_pk_add_f32 v[56:57], v[56:57], v[58:59]
	v_pk_add_f32 v[58:59], v[68:69], v[70:71]
	v_pk_add_f32 v[60:61], v[60:61], v[62:63]
	v_pk_add_f32 v[58:59], v[64:65], v[58:59]
	v_pk_add_f32 v[56:57], v[56:57], v[60:61]
	v_pk_add_f32 v[22:23], v[22:23], v[58:59]
	v_pk_add_f32 v[24:25], v[24:25], v[56:57]
	v_cvt_pk_f16_f32 v56, v22, v23
	v_cvt_pk_f16_f32 v57, v24, v25
	global_store_dwordx2 v[38:39], v[56:57], off offset:1024
	s_waitcnt vmcnt(6)
	v_cvt_f32_f16_e32 v64, v162
	v_cvt_f32_f16_sdwa v65, v162 dst_sel:DWORD dst_unused:UNUSED_PAD src0_sel:WORD_1
	v_cvt_f32_f16_e32 v56, v163
	v_cvt_f32_f16_sdwa v57, v163 dst_sel:DWORD dst_unused:UNUSED_PAD src0_sel:WORD_1
	s_waitcnt vmcnt(5)
	v_cvt_f32_f16_e32 v66, v164
	v_cvt_f32_f16_sdwa v67, v164 dst_sel:DWORD dst_unused:UNUSED_PAD src0_sel:WORD_1
	v_cvt_f32_f16_e32 v58, v165
	v_cvt_f32_f16_sdwa v59, v165 dst_sel:DWORD dst_unused:UNUSED_PAD src0_sel:WORD_1
	s_waitcnt vmcnt(4)
	v_cvt_f32_f16_e32 v68, v166
	v_cvt_f32_f16_sdwa v69, v166 dst_sel:DWORD dst_unused:UNUSED_PAD src0_sel:WORD_1
	v_cvt_f32_f16_e32 v60, v167
	v_cvt_f32_f16_sdwa v61, v167 dst_sel:DWORD dst_unused:UNUSED_PAD src0_sel:WORD_1
	s_waitcnt vmcnt(3)
	v_cvt_f32_f16_e32 v70, v168
	v_cvt_f32_f16_sdwa v71, v168 dst_sel:DWORD dst_unused:UNUSED_PAD src0_sel:WORD_1
	v_cvt_f32_f16_e32 v62, v169
	v_cvt_f32_f16_sdwa v63, v169 dst_sel:DWORD dst_unused:UNUSED_PAD src0_sel:WORD_1
	v_pk_add_f32 v[64:65], v[64:65], v[66:67]
	v_pk_add_f32 v[56:57], v[56:57], v[58:59]
	v_pk_add_f32 v[58:59], v[68:69], v[70:71]
	v_pk_add_f32 v[60:61], v[60:61], v[62:63]
	v_pk_add_f32 v[58:59], v[64:65], v[58:59]
	v_pk_add_f32 v[56:57], v[56:57], v[60:61]
	v_pk_add_f32 v[18:19], v[18:19], v[58:59]
	v_pk_add_f32 v[20:21], v[20:21], v[56:57]
	v_cvt_pk_f16_f32 v56, v18, v19
	v_cvt_pk_f16_f32 v57, v20, v21
	global_store_dwordx2 v[38:39], v[56:57], off offset:1536
	s_branch .LBB0_777

.LBB0_846:
	s_add_u32 s9, s96, 0xfffc0080
	s_addc_u32 s38, s97, -1
	s_add_i32 s78, 0, 0x10000
	s_cmp_eq_u32 s75, 12
	s_cselect_b32 vcc_hi, s25, s38
	s_cselect_b32 vcc_lo, s28, s9
	v_add_u32_e32 v148, s78, v145
	s_cselect_b32 s39, s23, s61
	s_cselect_b32 s38, s29, s53
	s_add_i32 s9, 0, 0x14000
	ds_read_b128 v[140:143], v148
	ds_read_b128 v[156:159], v148 offset:1024
	ds_read_b128 v[160:163], v148 offset:2048
	ds_read_b128 v[164:167], v148 offset:3072
	v_add_u32_e32 v148, s9, v145
	ds_read_b128 v[168:171], v148
	ds_read_b128 v[172:175], v148 offset:1024
	ds_read_b128 v[176:179], v148 offset:2048
	ds_read_b128 v[180:183], v148 offset:3072
	v_lshl_add_u64 v[148:149], s[96:97], 0, v[136:137]
	s_add_i32 m0, s46, 0xc000
	ds_read_b128 v[184:187], v147
	ds_read_b128 v[188:191], v147 offset:1024
	ds_read_b128 v[192:195], v147 offset:2048
	ds_read_b128 v[196:199], v147 offset:3072
	ds_read_b128 v[200:203], v147 offset:4096
	ds_read_b128 v[204:207], v147 offset:5120
	ds_read_b128 v[208:211], v147 offset:6144
	ds_read_b128 v[212:215], v147 offset:7168
	global_load_lds_dwordx4 v[148:149], off
	s_add_i32 m0, s46, 0xe000
	v_lshl_add_u64 v[148:149], s[96:97], 0, v[138:139]
	global_load_lds_dwordx4 v[148:149], off
	s_waitcnt vmcnt(8)
	s_waitcnt lgkmcnt(0)
	s_barrier
	s_setprio 1
	v_mfma_f32_16x16x32_bf16 v[126:129], v[140:143], v[184:187], v[126:129]
	v_mfma_f32_16x16x32_bf16 v[118:121], v[160:163], v[184:187], v[118:121]
	v_mfma_f32_16x16x32_bf16 v[110:113], v[140:143], v[192:195], v[110:113]
	v_mfma_f32_16x16x32_bf16 v[102:105], v[160:163], v[192:195], v[102:105]
	v_mfma_f32_16x16x32_bf16 v[94:97], v[140:143], v[200:203], v[94:97]
	v_mfma_f32_16x16x32_bf16 v[86:89], v[160:163], v[200:203], v[86:89]
	v_mfma_f32_16x16x32_bf16 v[78:81], v[140:143], v[208:211], v[78:81]
	v_mfma_f32_16x16x32_bf16 v[70:73], v[160:163], v[208:211], v[70:73]
	v_mfma_f32_16x16x32_bf16 v[126:129], v[156:159], v[188:191], v[126:129]
	v_mfma_f32_16x16x32_bf16 v[118:121], v[164:167], v[188:191], v[118:121]
	v_mfma_f32_16x16x32_bf16 v[110:113], v[156:159], v[196:199], v[110:113]
	v_mfma_f32_16x16x32_bf16 v[102:105], v[164:167], v[196:199], v[102:105]
	v_mfma_f32_16x16x32_bf16 v[94:97], v[156:159], v[204:207], v[94:97]
	v_mfma_f32_16x16x32_bf16 v[86:89], v[164:167], v[204:207], v[86:89]
	v_mfma_f32_16x16x32_bf16 v[78:81], v[156:159], v[212:215], v[78:81]
	v_mfma_f32_16x16x32_bf16 v[70:73], v[164:167], v[212:215], v[70:73]
	v_mfma_f32_16x16x32_bf16 v[122:125], v[168:171], v[184:187], v[122:125]
	v_mfma_f32_16x16x32_bf16 v[114:117], v[176:179], v[184:187], v[114:117]
	v_mfma_f32_16x16x32_bf16 v[106:109], v[168:171], v[192:195], v[106:109]
	v_mfma_f32_16x16x32_bf16 v[98:101], v[176:179], v[192:195], v[98:101]
	v_mfma_f32_16x16x32_bf16 v[90:93], v[168:171], v[200:203], v[90:93]
	v_mfma_f32_16x16x32_bf16 v[82:85], v[176:179], v[200:203], v[82:85]
	v_mfma_f32_16x16x32_bf16 v[74:77], v[168:171], v[208:211], v[74:77]
	v_mfma_f32_16x16x32_bf16 v[66:69], v[176:179], v[208:211], v[66:69]
	v_mfma_f32_16x16x32_bf16 v[122:125], v[172:175], v[188:191], v[122:125]
	v_mfma_f32_16x16x32_bf16 v[114:117], v[180:183], v[188:191], v[114:117]
	v_mfma_f32_16x16x32_bf16 v[106:109], v[172:175], v[196:199], v[106:109]
	v_mfma_f32_16x16x32_bf16 v[98:101], v[180:183], v[196:199], v[98:101]
	v_mfma_f32_16x16x32_bf16 v[90:93], v[172:175], v[204:207], v[90:93]
	v_mfma_f32_16x16x32_bf16 v[82:85], v[180:183], v[204:207], v[82:85]
	v_mfma_f32_16x16x32_bf16 v[74:77], v[172:175], v[212:215], v[74:77]
	v_mfma_f32_16x16x32_bf16 v[66:69], v[180:183], v[212:215], v[66:69]
	s_setprio 0
	s_barrier
	s_add_i32 s78, s78, s45
	v_lshl_add_u64 v[148:149], s[38:39], 0, v[0:1]
	s_mov_b32 m0, s78
	ds_read_b128 v[184:187], v147 offset:16384
	ds_read_b128 v[188:191], v147 offset:17408
	ds_read_b128 v[192:195], v147 offset:18432
	ds_read_b128 v[196:199], v147 offset:19456
	ds_read_b128 v[200:203], v147 offset:20480
	ds_read_b128 v[204:207], v147 offset:21504
	ds_read_b128 v[208:211], v147 offset:22528
	ds_read_b128 v[212:215], v147 offset:23552
	global_load_lds_dwordx4 v[148:149], off
	s_add_i32 m0, s78, 0x2000
	s_add_u32 s78, s38, 0x40000
	v_lshl_add_u64 v[150:151], s[38:39], 0, v[134:135]
	s_addc_u32 s79, s39, 0
	s_add_i32 s9, s9, s45
	global_load_lds_dwordx4 v[150:151], off
	v_lshl_add_u64 v[216:217], s[78:79], 0, v[0:1]
	s_mov_b32 m0, s9
	v_lshl_add_u64 v[218:219], vcc, 0, v[132:133]
	global_load_lds_dwordx4 v[216:217], off
	s_add_i32 m0, s9, 0x2000
	v_lshl_add_u64 v[216:217], s[78:79], 0, v[134:135]
	global_load_lds_dwordx4 v[216:217], off
	s_mov_b32 m0, s46
	v_lshl_add_u64 v[216:217], vcc, 0, v[130:131]
	global_load_lds_dwordx4 v[216:217], off
	s_mov_b32 m0, s47
	s_nop 0
	global_load_lds_dwordx4 v[218:219], off
	s_waitcnt vmcnt(8)
	s_waitcnt lgkmcnt(0)
	s_barrier
	s_setprio 1
	v_mfma_f32_16x16x32_bf16 v[62:65], v[140:143], v[184:187], v[62:65]
	v_mfma_f32_16x16x32_bf16 v[54:57], v[160:163], v[184:187], v[54:57]
	v_mfma_f32_16x16x32_bf16 v[46:49], v[140:143], v[192:195], v[46:49]
	v_mfma_f32_16x16x32_bf16 v[38:41], v[160:163], v[192:195], v[38:41]
	v_mfma_f32_16x16x32_bf16 v[30:33], v[140:143], v[200:203], v[30:33]
	v_mfma_f32_16x16x32_bf16 v[22:25], v[160:163], v[200:203], v[22:25]
	v_mfma_f32_16x16x32_bf16 v[14:17], v[140:143], v[208:211], v[14:17]
	v_mfma_f32_16x16x32_bf16 v[6:9], v[160:163], v[208:211], v[6:9]
	v_mfma_f32_16x16x32_bf16 v[62:65], v[156:159], v[188:191], v[62:65]
	v_mfma_f32_16x16x32_bf16 v[54:57], v[164:167], v[188:191], v[54:57]
	v_mfma_f32_16x16x32_bf16 v[46:49], v[156:159], v[196:199], v[46:49]
	v_mfma_f32_16x16x32_bf16 v[38:41], v[164:167], v[196:199], v[38:41]
	v_mfma_f32_16x16x32_bf16 v[30:33], v[156:159], v[204:207], v[30:33]
	v_mfma_f32_16x16x32_bf16 v[22:25], v[164:167], v[204:207], v[22:25]
	v_mfma_f32_16x16x32_bf16 v[14:17], v[156:159], v[212:215], v[14:17]
	v_mfma_f32_16x16x32_bf16 v[6:9], v[164:167], v[212:215], v[6:9]
	v_mfma_f32_16x16x32_bf16 v[58:61], v[168:171], v[184:187], v[58:61]
	v_mfma_f32_16x16x32_bf16 v[50:53], v[176:179], v[184:187], v[50:53]
	v_mfma_f32_16x16x32_bf16 v[42:45], v[168:171], v[192:195], v[42:45]
	v_mfma_f32_16x16x32_bf16 v[34:37], v[176:179], v[192:195], v[34:37]
	v_mfma_f32_16x16x32_bf16 v[26:29], v[168:171], v[200:203], v[26:29]
	v_mfma_f32_16x16x32_bf16 v[18:21], v[176:179], v[200:203], v[18:21]
	v_mfma_f32_16x16x32_bf16 v[10:13], v[168:171], v[208:211], v[10:13]
	v_mfma_f32_16x16x32_bf16 v[2:5], v[176:179], v[208:211], v[2:5]
	v_mfma_f32_16x16x32_bf16 v[58:61], v[172:175], v[188:191], v[58:61]
	v_mfma_f32_16x16x32_bf16 v[50:53], v[180:183], v[188:191], v[50:53]
	v_mfma_f32_16x16x32_bf16 v[42:45], v[172:175], v[196:199], v[42:45]
	v_mfma_f32_16x16x32_bf16 v[34:37], v[180:183], v[196:199], v[34:37]
	v_mfma_f32_16x16x32_bf16 v[26:29], v[172:175], v[204:207], v[26:29]
	v_mfma_f32_16x16x32_bf16 v[18:21], v[180:183], v[204:207], v[18:21]
	v_mfma_f32_16x16x32_bf16 v[10:13], v[172:175], v[212:215], v[10:13]
	v_mfma_f32_16x16x32_bf16 v[2:5], v[180:183], v[212:215], v[2:5]
	s_setprio 0
	s_barrier
	s_add_i32 s9, 0, 0x18000
	s_add_i32 s83, 0, 0x1c000
	v_add_u32_e32 v164, s9, v145
	v_add_u32_e32 v180, s83, v145
	ds_read_b128 v[140:143], v164
	ds_read_b128 v[156:159], v164 offset:1024
	ds_read_b128 v[160:163], v164 offset:2048
	ds_read_b128 v[164:167], v164 offset:3072
	ds_read_b128 v[168:171], v180
	ds_read_b128 v[172:175], v180 offset:1024
	ds_read_b128 v[176:179], v180 offset:2048
	ds_read_b128 v[180:183], v180 offset:3072
	s_add_u32 s78, vcc_lo, 0x40000
	s_addc_u32 s79, vcc_hi, 0
	s_mov_b32 m0, s48
	v_lshl_add_u64 v[220:221], s[78:79], 0, v[130:131]
	ds_read_b128 v[184:187], v147 offset:32768
	ds_read_b128 v[188:191], v147 offset:33792
	ds_read_b128 v[192:195], v147 offset:34816
	ds_read_b128 v[196:199], v147 offset:35840
	ds_read_b128 v[200:203], v147 offset:36864
	ds_read_b128 v[204:207], v147 offset:37888
	ds_read_b128 v[208:211], v147 offset:38912
	ds_read_b128 v[212:215], v147 offset:39936
	global_load_lds_dwordx4 v[220:221], off
	s_mov_b32 m0, s49
	v_lshl_add_u64 v[220:221], s[78:79], 0, v[132:133]
	global_load_lds_dwordx4 v[220:221], off
	s_waitcnt vmcnt(8)
	s_waitcnt lgkmcnt(0)
	s_barrier
	s_setprio 1
	v_mfma_f32_16x16x32_bf16 v[126:129], v[140:143], v[184:187], v[126:129]
	v_mfma_f32_16x16x32_bf16 v[118:121], v[160:163], v[184:187], v[118:121]
	v_mfma_f32_16x16x32_bf16 v[110:113], v[140:143], v[192:195], v[110:113]
	v_mfma_f32_16x16x32_bf16 v[102:105], v[160:163], v[192:195], v[102:105]
	v_mfma_f32_16x16x32_bf16 v[94:97], v[140:143], v[200:203], v[94:97]
	v_mfma_f32_16x16x32_bf16 v[86:89], v[160:163], v[200:203], v[86:89]
	v_mfma_f32_16x16x32_bf16 v[78:81], v[140:143], v[208:211], v[78:81]
	v_mfma_f32_16x16x32_bf16 v[70:73], v[160:163], v[208:211], v[70:73]
	v_mfma_f32_16x16x32_bf16 v[126:129], v[156:159], v[188:191], v[126:129]
	v_mfma_f32_16x16x32_bf16 v[118:121], v[164:167], v[188:191], v[118:121]
	v_mfma_f32_16x16x32_bf16 v[110:113], v[156:159], v[196:199], v[110:113]
	v_mfma_f32_16x16x32_bf16 v[102:105], v[164:167], v[196:199], v[102:105]
	v_mfma_f32_16x16x32_bf16 v[94:97], v[156:159], v[204:207], v[94:97]
	v_mfma_f32_16x16x32_bf16 v[86:89], v[164:167], v[204:207], v[86:89]
	v_mfma_f32_16x16x32_bf16 v[78:81], v[156:159], v[212:215], v[78:81]
	v_mfma_f32_16x16x32_bf16 v[70:73], v[164:167], v[212:215], v[70:73]
	v_mfma_f32_16x16x32_bf16 v[122:125], v[168:171], v[184:187], v[122:125]
	v_mfma_f32_16x16x32_bf16 v[114:117], v[176:179], v[184:187], v[114:117]
	v_mfma_f32_16x16x32_bf16 v[106:109], v[168:171], v[192:195], v[106:109]
	v_mfma_f32_16x16x32_bf16 v[98:101], v[176:179], v[192:195], v[98:101]
	v_mfma_f32_16x16x32_bf16 v[90:93], v[168:171], v[200:203], v[90:93]
	v_mfma_f32_16x16x32_bf16 v[82:85], v[176:179], v[200:203], v[82:85]
	v_mfma_f32_16x16x32_bf16 v[74:77], v[168:171], v[208:211], v[74:77]
	v_mfma_f32_16x16x32_bf16 v[66:69], v[176:179], v[208:211], v[66:69]
	v_mfma_f32_16x16x32_bf16 v[122:125], v[172:175], v[188:191], v[122:125]
	v_mfma_f32_16x16x32_bf16 v[114:117], v[180:183], v[188:191], v[114:117]
	v_mfma_f32_16x16x32_bf16 v[106:109], v[172:175], v[196:199], v[106:109]
	v_mfma_f32_16x16x32_bf16 v[98:101], v[180:183], v[196:199], v[98:101]
	v_mfma_f32_16x16x32_bf16 v[90:93], v[172:175], v[204:207], v[90:93]
	v_mfma_f32_16x16x32_bf16 v[82:85], v[180:183], v[204:207], v[82:85]
	v_mfma_f32_16x16x32_bf16 v[74:77], v[172:175], v[212:215], v[74:77]
	v_mfma_f32_16x16x32_bf16 v[66:69], v[180:183], v[212:215], v[66:69]
	s_setprio 0
	s_barrier
	s_add_i32 s9, s9, s45
	v_lshl_add_u64 v[148:149], v[148:149], 0, s[70:71]
	s_mov_b32 m0, s9
	ds_read_b128 v[184:187], v147 offset:49152
	ds_read_b128 v[188:191], v147 offset:50176
	ds_read_b128 v[192:195], v147 offset:51200
	ds_read_b128 v[196:199], v147 offset:52224
	ds_read_b128 v[200:203], v147 offset:53248
	ds_read_b128 v[204:207], v147 offset:54272
	ds_read_b128 v[208:211], v147 offset:55296
	ds_read_b128 v[212:215], v147 offset:56320
	global_load_lds_dwordx4 v[148:149], off
	s_add_i32 m0, s9, 0x2000
	s_add_u32 s38, s38, 0x40080
	v_lshl_add_u64 v[148:149], v[150:151], 0, s[70:71]
	s_addc_u32 s39, s39, 0
	s_add_i32 s9, s83, s45
	global_load_lds_dwordx4 v[148:149], off
	s_mov_b32 m0, s9
	v_lshl_add_u64 v[148:149], s[38:39], 0, v[0:1]
	global_load_lds_dwordx4 v[148:149], off
	s_add_i32 m0, s9, 0x2000
	v_lshl_add_u64 v[148:149], s[38:39], 0, v[134:135]
	global_load_lds_dwordx4 v[148:149], off
	s_mov_b32 m0, s50
	v_lshl_add_u64 v[148:149], v[216:217], 0, s[70:71]
	global_load_lds_dwordx4 v[148:149], off
	s_mov_b32 m0, s51
	v_lshl_add_u64 v[148:149], v[218:219], 0, s[70:71]
	global_load_lds_dwordx4 v[148:149], off
	s_waitcnt vmcnt(8)
	s_waitcnt lgkmcnt(0)
	s_barrier
	s_setprio 1
	v_mfma_f32_16x16x32_bf16 v[62:65], v[140:143], v[184:187], v[62:65]
	v_mfma_f32_16x16x32_bf16 v[54:57], v[160:163], v[184:187], v[54:57]
	v_mfma_f32_16x16x32_bf16 v[46:49], v[140:143], v[192:195], v[46:49]
	v_mfma_f32_16x16x32_bf16 v[38:41], v[160:163], v[192:195], v[38:41]
	v_mfma_f32_16x16x32_bf16 v[30:33], v[140:143], v[200:203], v[30:33]
	v_mfma_f32_16x16x32_bf16 v[22:25], v[160:163], v[200:203], v[22:25]
	v_mfma_f32_16x16x32_bf16 v[14:17], v[140:143], v[208:211], v[14:17]
	v_mfma_f32_16x16x32_bf16 v[6:9], v[160:163], v[208:211], v[6:9]
	v_mfma_f32_16x16x32_bf16 v[62:65], v[156:159], v[188:191], v[62:65]
	v_mfma_f32_16x16x32_bf16 v[54:57], v[164:167], v[188:191], v[54:57]
	v_mfma_f32_16x16x32_bf16 v[46:49], v[156:159], v[196:199], v[46:49]
	v_mfma_f32_16x16x32_bf16 v[38:41], v[164:167], v[196:199], v[38:41]
	v_mfma_f32_16x16x32_bf16 v[30:33], v[156:159], v[204:207], v[30:33]
	v_mfma_f32_16x16x32_bf16 v[22:25], v[164:167], v[204:207], v[22:25]
	v_mfma_f32_16x16x32_bf16 v[14:17], v[156:159], v[212:215], v[14:17]
	v_mfma_f32_16x16x32_bf16 v[6:9], v[164:167], v[212:215], v[6:9]
	v_mfma_f32_16x16x32_bf16 v[58:61], v[168:171], v[184:187], v[58:61]
	v_mfma_f32_16x16x32_bf16 v[50:53], v[176:179], v[184:187], v[50:53]
	v_mfma_f32_16x16x32_bf16 v[42:45], v[168:171], v[192:195], v[42:45]
	v_mfma_f32_16x16x32_bf16 v[34:37], v[176:179], v[192:195], v[34:37]
	v_mfma_f32_16x16x32_bf16 v[26:29], v[168:171], v[200:203], v[26:29]
	v_mfma_f32_16x16x32_bf16 v[18:21], v[176:179], v[200:203], v[18:21]
	v_mfma_f32_16x16x32_bf16 v[10:13], v[168:171], v[208:211], v[10:13]
	v_mfma_f32_16x16x32_bf16 v[2:5], v[176:179], v[208:211], v[2:5]
	v_mfma_f32_16x16x32_bf16 v[58:61], v[172:175], v[188:191], v[58:61]
	v_mfma_f32_16x16x32_bf16 v[50:53], v[180:183], v[188:191], v[50:53]
	v_mfma_f32_16x16x32_bf16 v[42:45], v[172:175], v[196:199], v[42:45]
	v_mfma_f32_16x16x32_bf16 v[34:37], v[180:183], v[196:199], v[34:37]
	v_mfma_f32_16x16x32_bf16 v[26:29], v[172:175], v[204:207], v[26:29]
	v_mfma_f32_16x16x32_bf16 v[18:21], v[180:183], v[204:207], v[18:21]
	v_mfma_f32_16x16x32_bf16 v[10:13], v[172:175], v[212:215], v[10:13]
	v_mfma_f32_16x16x32_bf16 v[2:5], v[180:183], v[212:215], v[2:5]
	s_setprio 0
	s_barrier
	s_add_i32 s75, s75, 2
	s_add_u32 s96, s96, 0x100
	s_addc_u32 s97, s97, 0
	s_add_u32 s53, s53, 0x100
	s_addc_u32 s61, s61, 0
	s_cmp_gt_u32 s75, 13
	s_cbranch_scc0 .LBB0_846
	s_and_b64 vcc, exec, s[14:15]
	s_cbranch_vccz .LBB0_849
	s_barrier

.LBB0_950:
	s_add_i32 s9, s26, 2
	s_add_u32 s60, s38, 0x100
	s_addc_u32 s61, s39, 0
	s_add_i32 s78, 0, 0x10000
	s_cmp_eq_u32 s29, s26
	s_cselect_b32 s73, s25, s61
	s_cselect_b32 s72, s24, s60
	s_cselect_b32 s27, s37, vcc_hi
	s_cselect_b32 s26, s36, vcc_lo
	s_add_i32 s79, 0, 0x14000
	v_add_u32_e32 v156, s78, v177
	v_add_u32_e32 v172, s79, v177
	ds_read_b128 v[140:143], v156
	ds_read_b128 v[144:147], v156 offset:1024
	ds_read_b128 v[148:151], v156 offset:2048
	ds_read_b128 v[156:159], v156 offset:3072
	ds_read_b128 v[160:163], v172
	ds_read_b128 v[164:167], v172 offset:1024
	ds_read_b128 v[168:171], v172 offset:2048
	ds_read_b128 v[172:175], v172 offset:3072
	v_lshl_add_u64 v[212:213], s[38:39], 0, v[136:137]
	s_add_i32 m0, s50, 0xc000
	ds_read_b128 v[180:183], v179
	ds_read_b128 v[184:187], v179 offset:1024
	ds_read_b128 v[188:191], v179 offset:2048
	ds_read_b128 v[192:195], v179 offset:3072
	ds_read_b128 v[196:199], v179 offset:4096
	ds_read_b128 v[200:203], v179 offset:5120
	ds_read_b128 v[204:207], v179 offset:6144
	ds_read_b128 v[208:211], v179 offset:7168
	global_load_lds_dwordx4 v[212:213], off
	s_add_i32 m0, s50, 0xe000
	v_lshl_add_u64 v[212:213], s[38:39], 0, v[138:139]
	global_load_lds_dwordx4 v[212:213], off
	s_waitcnt vmcnt(8)
	s_waitcnt lgkmcnt(0)
	s_barrier
	s_setprio 1
	v_mfma_f32_16x16x32_bf16 v[126:129], v[140:143], v[180:183], v[126:129]
	v_mfma_f32_16x16x32_bf16 v[122:125], v[148:151], v[180:183], v[122:125]
	v_mfma_f32_16x16x32_bf16 v[110:113], v[140:143], v[188:191], v[110:113]
	v_mfma_f32_16x16x32_bf16 v[106:109], v[148:151], v[188:191], v[106:109]
	v_mfma_f32_16x16x32_bf16 v[94:97], v[140:143], v[196:199], v[94:97]
	v_mfma_f32_16x16x32_bf16 v[90:93], v[148:151], v[196:199], v[90:93]
	v_mfma_f32_16x16x32_bf16 v[78:81], v[140:143], v[204:207], v[78:81]
	v_mfma_f32_16x16x32_bf16 v[74:77], v[148:151], v[204:207], v[74:77]
	v_mfma_f32_16x16x32_bf16 v[126:129], v[144:147], v[184:187], v[126:129]
	v_mfma_f32_16x16x32_bf16 v[122:125], v[156:159], v[184:187], v[122:125]
	v_mfma_f32_16x16x32_bf16 v[110:113], v[144:147], v[192:195], v[110:113]
	v_mfma_f32_16x16x32_bf16 v[106:109], v[156:159], v[192:195], v[106:109]
	v_mfma_f32_16x16x32_bf16 v[94:97], v[144:147], v[200:203], v[94:97]
	v_mfma_f32_16x16x32_bf16 v[90:93], v[156:159], v[200:203], v[90:93]
	v_mfma_f32_16x16x32_bf16 v[78:81], v[144:147], v[208:211], v[78:81]
	v_mfma_f32_16x16x32_bf16 v[74:77], v[156:159], v[208:211], v[74:77]
	v_mfma_f32_16x16x32_bf16 v[118:121], v[160:163], v[180:183], v[118:121]
	v_mfma_f32_16x16x32_bf16 v[114:117], v[168:171], v[180:183], v[114:117]
	v_mfma_f32_16x16x32_bf16 v[102:105], v[160:163], v[188:191], v[102:105]
	v_mfma_f32_16x16x32_bf16 v[98:101], v[168:171], v[188:191], v[98:101]
	v_mfma_f32_16x16x32_bf16 v[86:89], v[160:163], v[196:199], v[86:89]
	v_mfma_f32_16x16x32_bf16 v[82:85], v[168:171], v[196:199], v[82:85]
	v_mfma_f32_16x16x32_bf16 v[70:73], v[160:163], v[204:207], v[70:73]
	v_mfma_f32_16x16x32_bf16 v[66:69], v[168:171], v[204:207], v[66:69]
	v_mfma_f32_16x16x32_bf16 v[118:121], v[164:167], v[184:187], v[118:121]
	v_mfma_f32_16x16x32_bf16 v[114:117], v[172:175], v[184:187], v[114:117]
	v_mfma_f32_16x16x32_bf16 v[102:105], v[164:167], v[192:195], v[102:105]
	v_mfma_f32_16x16x32_bf16 v[98:101], v[172:175], v[192:195], v[98:101]
	v_mfma_f32_16x16x32_bf16 v[86:89], v[164:167], v[200:203], v[86:89]
	v_mfma_f32_16x16x32_bf16 v[82:85], v[172:175], v[200:203], v[82:85]
	v_mfma_f32_16x16x32_bf16 v[70:73], v[164:167], v[208:211], v[70:73]
	v_mfma_f32_16x16x32_bf16 v[66:69], v[172:175], v[208:211], v[66:69]
	s_setprio 0
	s_barrier
	s_add_i32 s38, s78, s49
	v_lshl_add_u64 v[212:213], s[26:27], 0, v[0:1]
	s_mov_b32 m0, s38
	ds_read_b128 v[180:183], v179 offset:16384
	ds_read_b128 v[184:187], v179 offset:17408
	ds_read_b128 v[188:191], v179 offset:18432
	ds_read_b128 v[192:195], v179 offset:19456
	ds_read_b128 v[196:199], v179 offset:20480
	ds_read_b128 v[200:203], v179 offset:21504
	ds_read_b128 v[204:207], v179 offset:22528
	ds_read_b128 v[208:211], v179 offset:23552
	global_load_lds_dwordx4 v[212:213], off
	s_add_i32 m0, s38, 0x2000
	s_add_u32 s38, s26, 0xb0000
	v_lshl_add_u64 v[214:215], s[26:27], 0, v[134:135]
	s_addc_u32 s39, s27, 0
	s_add_i32 s78, s79, s49
	global_load_lds_dwordx4 v[214:215], off
	v_lshl_add_u64 v[216:217], s[38:39], 0, v[0:1]
	s_mov_b32 m0, s78
	v_lshl_add_u64 v[218:219], s[72:73], 0, v[132:133]
	global_load_lds_dwordx4 v[216:217], off
	s_add_i32 m0, s78, 0x2000
	v_lshl_add_u64 v[216:217], s[38:39], 0, v[134:135]
	global_load_lds_dwordx4 v[216:217], off
	s_mov_b32 m0, s50
	v_lshl_add_u64 v[216:217], s[72:73], 0, v[130:131]
	global_load_lds_dwordx4 v[216:217], off
	s_mov_b32 m0, s51
	s_nop 0
	global_load_lds_dwordx4 v[218:219], off
	s_waitcnt vmcnt(8)
	s_waitcnt lgkmcnt(0)
	s_barrier
	s_setprio 1
	v_mfma_f32_16x16x32_bf16 v[62:65], v[140:143], v[180:183], v[62:65]
	v_mfma_f32_16x16x32_bf16 v[58:61], v[148:151], v[180:183], v[58:61]
	v_mfma_f32_16x16x32_bf16 v[46:49], v[140:143], v[188:191], v[46:49]
	v_mfma_f32_16x16x32_bf16 v[42:45], v[148:151], v[188:191], v[42:45]
	v_mfma_f32_16x16x32_bf16 v[30:33], v[140:143], v[196:199], v[30:33]
	v_mfma_f32_16x16x32_bf16 v[26:29], v[148:151], v[196:199], v[26:29]
	v_mfma_f32_16x16x32_bf16 v[14:17], v[140:143], v[204:207], v[14:17]
	v_mfma_f32_16x16x32_bf16 v[10:13], v[148:151], v[204:207], v[10:13]
	v_mfma_f32_16x16x32_bf16 v[62:65], v[144:147], v[184:187], v[62:65]
	v_mfma_f32_16x16x32_bf16 v[58:61], v[156:159], v[184:187], v[58:61]
	v_mfma_f32_16x16x32_bf16 v[46:49], v[144:147], v[192:195], v[46:49]
	v_mfma_f32_16x16x32_bf16 v[42:45], v[156:159], v[192:195], v[42:45]
	v_mfma_f32_16x16x32_bf16 v[30:33], v[144:147], v[200:203], v[30:33]
	v_mfma_f32_16x16x32_bf16 v[26:29], v[156:159], v[200:203], v[26:29]
	v_mfma_f32_16x16x32_bf16 v[14:17], v[144:147], v[208:211], v[14:17]
	v_mfma_f32_16x16x32_bf16 v[10:13], v[156:159], v[208:211], v[10:13]
	v_mfma_f32_16x16x32_bf16 v[54:57], v[160:163], v[180:183], v[54:57]
	v_mfma_f32_16x16x32_bf16 v[50:53], v[168:171], v[180:183], v[50:53]
	v_mfma_f32_16x16x32_bf16 v[38:41], v[160:163], v[188:191], v[38:41]
	v_mfma_f32_16x16x32_bf16 v[34:37], v[168:171], v[188:191], v[34:37]
	v_mfma_f32_16x16x32_bf16 v[22:25], v[160:163], v[196:199], v[22:25]
	v_mfma_f32_16x16x32_bf16 v[18:21], v[168:171], v[196:199], v[18:21]
	v_mfma_f32_16x16x32_bf16 v[6:9], v[160:163], v[204:207], v[6:9]
	v_mfma_f32_16x16x32_bf16 v[2:5], v[168:171], v[204:207], v[2:5]
	v_mfma_f32_16x16x32_bf16 v[54:57], v[164:167], v[184:187], v[54:57]
	v_mfma_f32_16x16x32_bf16 v[50:53], v[172:175], v[184:187], v[50:53]
	v_mfma_f32_16x16x32_bf16 v[38:41], v[164:167], v[192:195], v[38:41]
	v_mfma_f32_16x16x32_bf16 v[34:37], v[172:175], v[192:195], v[34:37]
	v_mfma_f32_16x16x32_bf16 v[22:25], v[164:167], v[200:203], v[22:25]
	v_mfma_f32_16x16x32_bf16 v[18:21], v[172:175], v[200:203], v[18:21]
	v_mfma_f32_16x16x32_bf16 v[6:9], v[164:167], v[208:211], v[6:9]
	v_mfma_f32_16x16x32_bf16 v[2:5], v[172:175], v[208:211], v[2:5]
	s_setprio 0
	s_barrier
	s_add_i32 s78, 0, 0x18000
	s_add_i32 s79, 0, 0x1c000
	v_add_u32_e32 v156, s78, v177
	v_add_u32_e32 v172, s79, v177
	ds_read_b128 v[140:143], v156
	ds_read_b128 v[144:147], v156 offset:1024
	ds_read_b128 v[148:151], v156 offset:2048
	ds_read_b128 v[156:159], v156 offset:3072
	ds_read_b128 v[160:163], v172
	ds_read_b128 v[164:167], v172 offset:1024
	ds_read_b128 v[168:171], v172 offset:2048
	ds_read_b128 v[172:175], v172 offset:3072
	s_add_u32 s38, s72, 0xb0000
	s_addc_u32 s39, s73, 0
	s_mov_b32 m0, s52
	v_lshl_add_u64 v[220:221], s[38:39], 0, v[130:131]
	ds_read_b128 v[180:183], v179 offset:32768
	ds_read_b128 v[184:187], v179 offset:33792
	ds_read_b128 v[188:191], v179 offset:34816
	ds_read_b128 v[192:195], v179 offset:35840
	ds_read_b128 v[196:199], v179 offset:36864
	ds_read_b128 v[200:203], v179 offset:37888
	ds_read_b128 v[204:207], v179 offset:38912
	ds_read_b128 v[208:211], v179 offset:39936
	global_load_lds_dwordx4 v[220:221], off
	s_mov_b32 m0, s53
	v_lshl_add_u64 v[220:221], s[38:39], 0, v[132:133]
	global_load_lds_dwordx4 v[220:221], off
	s_waitcnt vmcnt(8)
	s_waitcnt lgkmcnt(0)
	s_barrier
	s_setprio 1
	v_mfma_f32_16x16x32_bf16 v[126:129], v[140:143], v[180:183], v[126:129]
	v_mfma_f32_16x16x32_bf16 v[122:125], v[148:151], v[180:183], v[122:125]
	v_mfma_f32_16x16x32_bf16 v[110:113], v[140:143], v[188:191], v[110:113]
	v_mfma_f32_16x16x32_bf16 v[106:109], v[148:151], v[188:191], v[106:109]
	v_mfma_f32_16x16x32_bf16 v[94:97], v[140:143], v[196:199], v[94:97]
	v_mfma_f32_16x16x32_bf16 v[90:93], v[148:151], v[196:199], v[90:93]
	v_mfma_f32_16x16x32_bf16 v[78:81], v[140:143], v[204:207], v[78:81]
	v_mfma_f32_16x16x32_bf16 v[74:77], v[148:151], v[204:207], v[74:77]
	v_mfma_f32_16x16x32_bf16 v[126:129], v[144:147], v[184:187], v[126:129]
	v_mfma_f32_16x16x32_bf16 v[122:125], v[156:159], v[184:187], v[122:125]
	v_mfma_f32_16x16x32_bf16 v[110:113], v[144:147], v[192:195], v[110:113]
	v_mfma_f32_16x16x32_bf16 v[106:109], v[156:159], v[192:195], v[106:109]
	v_mfma_f32_16x16x32_bf16 v[94:97], v[144:147], v[200:203], v[94:97]
	v_mfma_f32_16x16x32_bf16 v[90:93], v[156:159], v[200:203], v[90:93]
	v_mfma_f32_16x16x32_bf16 v[78:81], v[144:147], v[208:211], v[78:81]
	v_mfma_f32_16x16x32_bf16 v[74:77], v[156:159], v[208:211], v[74:77]
	v_mfma_f32_16x16x32_bf16 v[118:121], v[160:163], v[180:183], v[118:121]
	v_mfma_f32_16x16x32_bf16 v[114:117], v[168:171], v[180:183], v[114:117]
	v_mfma_f32_16x16x32_bf16 v[102:105], v[160:163], v[188:191], v[102:105]
	v_mfma_f32_16x16x32_bf16 v[98:101], v[168:171], v[188:191], v[98:101]
	v_mfma_f32_16x16x32_bf16 v[86:89], v[160:163], v[196:199], v[86:89]
	v_mfma_f32_16x16x32_bf16 v[82:85], v[168:171], v[196:199], v[82:85]
	v_mfma_f32_16x16x32_bf16 v[70:73], v[160:163], v[204:207], v[70:73]
	v_mfma_f32_16x16x32_bf16 v[66:69], v[168:171], v[204:207], v[66:69]
	v_mfma_f32_16x16x32_bf16 v[118:121], v[164:167], v[184:187], v[118:121]
	v_mfma_f32_16x16x32_bf16 v[114:117], v[172:175], v[184:187], v[114:117]
	v_mfma_f32_16x16x32_bf16 v[102:105], v[164:167], v[192:195], v[102:105]
	v_mfma_f32_16x16x32_bf16 v[98:101], v[172:175], v[192:195], v[98:101]
	v_mfma_f32_16x16x32_bf16 v[86:89], v[164:167], v[200:203], v[86:89]
	v_mfma_f32_16x16x32_bf16 v[82:85], v[172:175], v[200:203], v[82:85]
	v_mfma_f32_16x16x32_bf16 v[70:73], v[164:167], v[208:211], v[70:73]
	v_mfma_f32_16x16x32_bf16 v[66:69], v[172:175], v[208:211], v[66:69]
	s_setprio 0
	s_barrier
	s_add_i32 s38, s78, s49
	v_lshl_add_u64 v[212:213], v[212:213], 0, s[70:71]
	s_mov_b32 m0, s38
	ds_read_b128 v[180:183], v179 offset:49152
	ds_read_b128 v[184:187], v179 offset:50176
	ds_read_b128 v[188:191], v179 offset:51200
	ds_read_b128 v[192:195], v179 offset:52224
	ds_read_b128 v[196:199], v179 offset:53248
	ds_read_b128 v[200:203], v179 offset:54272
	ds_read_b128 v[204:207], v179 offset:55296
	ds_read_b128 v[208:211], v179 offset:56320
	global_load_lds_dwordx4 v[212:213], off
	s_add_i32 m0, s38, 0x2000
	s_add_u32 s26, s26, 0xb0080
	v_lshl_add_u64 v[212:213], v[214:215], 0, s[70:71]
	s_addc_u32 s27, s27, 0
	s_add_i32 s38, s79, s49
	global_load_lds_dwordx4 v[212:213], off
	s_mov_b32 m0, s38
	v_lshl_add_u64 v[212:213], s[26:27], 0, v[0:1]
	global_load_lds_dwordx4 v[212:213], off
	s_add_i32 m0, s38, 0x2000
	v_lshl_add_u64 v[212:213], s[26:27], 0, v[134:135]
	global_load_lds_dwordx4 v[212:213], off
	s_mov_b32 m0, s74
	v_lshl_add_u64 v[212:213], v[216:217], 0, s[70:71]
	global_load_lds_dwordx4 v[212:213], off
	s_mov_b32 m0, s75
	v_lshl_add_u64 v[212:213], v[218:219], 0, s[70:71]
	global_load_lds_dwordx4 v[212:213], off
	s_waitcnt vmcnt(8)
	s_waitcnt lgkmcnt(0)
	s_barrier
	s_setprio 1
	v_mfma_f32_16x16x32_bf16 v[62:65], v[140:143], v[180:183], v[62:65]
	v_mfma_f32_16x16x32_bf16 v[58:61], v[148:151], v[180:183], v[58:61]
	v_mfma_f32_16x16x32_bf16 v[46:49], v[140:143], v[188:191], v[46:49]
	v_mfma_f32_16x16x32_bf16 v[42:45], v[148:151], v[188:191], v[42:45]
	v_mfma_f32_16x16x32_bf16 v[30:33], v[140:143], v[196:199], v[30:33]
	v_mfma_f32_16x16x32_bf16 v[26:29], v[148:151], v[196:199], v[26:29]
	v_mfma_f32_16x16x32_bf16 v[14:17], v[140:143], v[204:207], v[14:17]
	v_mfma_f32_16x16x32_bf16 v[10:13], v[148:151], v[204:207], v[10:13]
	v_mfma_f32_16x16x32_bf16 v[62:65], v[144:147], v[184:187], v[62:65]
	v_mfma_f32_16x16x32_bf16 v[58:61], v[156:159], v[184:187], v[58:61]
	v_mfma_f32_16x16x32_bf16 v[46:49], v[144:147], v[192:195], v[46:49]
	v_mfma_f32_16x16x32_bf16 v[42:45], v[156:159], v[192:195], v[42:45]
	v_mfma_f32_16x16x32_bf16 v[30:33], v[144:147], v[200:203], v[30:33]
	v_mfma_f32_16x16x32_bf16 v[26:29], v[156:159], v[200:203], v[26:29]
	v_mfma_f32_16x16x32_bf16 v[14:17], v[144:147], v[208:211], v[14:17]
	v_mfma_f32_16x16x32_bf16 v[10:13], v[156:159], v[208:211], v[10:13]
	v_mfma_f32_16x16x32_bf16 v[54:57], v[160:163], v[180:183], v[54:57]
	v_mfma_f32_16x16x32_bf16 v[50:53], v[168:171], v[180:183], v[50:53]
	v_mfma_f32_16x16x32_bf16 v[38:41], v[160:163], v[188:191], v[38:41]
	v_mfma_f32_16x16x32_bf16 v[34:37], v[168:171], v[188:191], v[34:37]
	v_mfma_f32_16x16x32_bf16 v[22:25], v[160:163], v[196:199], v[22:25]
	v_mfma_f32_16x16x32_bf16 v[18:21], v[168:171], v[196:199], v[18:21]
	v_mfma_f32_16x16x32_bf16 v[6:9], v[160:163], v[204:207], v[6:9]
	v_mfma_f32_16x16x32_bf16 v[2:5], v[168:171], v[204:207], v[2:5]
	v_mfma_f32_16x16x32_bf16 v[54:57], v[164:167], v[184:187], v[54:57]
	v_mfma_f32_16x16x32_bf16 v[50:53], v[172:175], v[184:187], v[50:53]
	v_mfma_f32_16x16x32_bf16 v[38:41], v[164:167], v[192:195], v[38:41]
	v_mfma_f32_16x16x32_bf16 v[34:37], v[172:175], v[192:195], v[34:37]
	v_mfma_f32_16x16x32_bf16 v[22:25], v[164:167], v[200:203], v[22:25]
	v_mfma_f32_16x16x32_bf16 v[18:21], v[172:175], v[200:203], v[18:21]
	v_mfma_f32_16x16x32_bf16 v[6:9], v[164:167], v[208:211], v[6:9]
	v_mfma_f32_16x16x32_bf16 v[2:5], v[172:175], v[208:211], v[2:5]
	s_setprio 0
	s_barrier
	s_add_u32 vcc_lo, vcc_lo, 0x100
	s_addc_u32 vcc_hi, vcc_hi, 0
	s_cmp_ge_u32 s9, s28
	s_mov_b64 s[38:39], s[60:61]
	s_mov_b32 s26, s9
	s_cbranch_scc0 .LBB0_950
	s_and_b64 vcc, exec, s[22:23]
	s_cbranch_vccz .LBB0_953

.LBB0_1000:
	s_add_i32 s9, s26, 2
	s_add_u32 s60, s38, 0x100
	s_addc_u32 s61, s39, 0
	s_add_i32 s78, 0, 0x10000
	s_cmp_eq_u32 s29, s26
	s_cselect_b32 s73, s25, s61
	s_cselect_b32 s72, s24, s60
	v_add_u32_e32 v148, s78, v251
	s_cselect_b32 s27, s37, vcc_hi
	s_cselect_b32 s26, s36, vcc_lo
	s_add_i32 s79, 0, 0x14000
	ds_read_b128 v[140:143], v148
	ds_read_b128 v[144:147], v148 offset:1024
	ds_read_b128 v[156:159], v148 offset:2048
	ds_read_b128 v[160:163], v148 offset:3072
	v_add_u32_e32 v148, s79, v251
	ds_read_b128 v[164:167], v148
	ds_read_b128 v[168:171], v148 offset:1024
	ds_read_b128 v[172:175], v148 offset:2048
	ds_read_b128 v[176:179], v148 offset:3072
	v_lshl_add_u64 v[148:149], s[38:39], 0, v[136:137]
	s_add_i32 m0, s50, 0xc000
	ds_read_b128 v[180:183], v253
	ds_read_b128 v[184:187], v253 offset:1024
	ds_read_b128 v[188:191], v253 offset:2048
	ds_read_b128 v[192:195], v253 offset:3072
	ds_read_b128 v[196:199], v253 offset:4096
	ds_read_b128 v[200:203], v253 offset:5120
	ds_read_b128 v[204:207], v253 offset:6144
	ds_read_b128 v[208:211], v253 offset:7168
	global_load_lds_dwordx4 v[148:149], off
	s_add_i32 m0, s50, 0xe000
	v_lshl_add_u64 v[148:149], s[38:39], 0, v[138:139]
	global_load_lds_dwordx4 v[148:149], off
	s_waitcnt vmcnt(8)
	s_waitcnt lgkmcnt(0)
	s_barrier
	s_setprio 1
	v_mfma_f32_16x16x32_bf16 v[126:129], v[140:143], v[180:183], v[126:129]
	v_mfma_f32_16x16x32_bf16 v[122:125], v[156:159], v[180:183], v[122:125]
	v_mfma_f32_16x16x32_bf16 v[110:113], v[140:143], v[188:191], v[110:113]
	v_mfma_f32_16x16x32_bf16 v[106:109], v[156:159], v[188:191], v[106:109]
	v_mfma_f32_16x16x32_bf16 v[94:97], v[140:143], v[196:199], v[94:97]
	v_mfma_f32_16x16x32_bf16 v[90:93], v[156:159], v[196:199], v[90:93]
	v_mfma_f32_16x16x32_bf16 v[78:81], v[140:143], v[204:207], v[78:81]
	v_mfma_f32_16x16x32_bf16 v[74:77], v[156:159], v[204:207], v[74:77]
	v_mfma_f32_16x16x32_bf16 v[126:129], v[144:147], v[184:187], v[126:129]
	v_mfma_f32_16x16x32_bf16 v[122:125], v[160:163], v[184:187], v[122:125]
	v_mfma_f32_16x16x32_bf16 v[110:113], v[144:147], v[192:195], v[110:113]
	v_mfma_f32_16x16x32_bf16 v[106:109], v[160:163], v[192:195], v[106:109]
	v_mfma_f32_16x16x32_bf16 v[94:97], v[144:147], v[200:203], v[94:97]
	v_mfma_f32_16x16x32_bf16 v[90:93], v[160:163], v[200:203], v[90:93]
	v_mfma_f32_16x16x32_bf16 v[78:81], v[144:147], v[208:211], v[78:81]
	v_mfma_f32_16x16x32_bf16 v[74:77], v[160:163], v[208:211], v[74:77]
	v_mfma_f32_16x16x32_bf16 v[118:121], v[164:167], v[180:183], v[118:121]
	v_mfma_f32_16x16x32_bf16 v[114:117], v[172:175], v[180:183], v[114:117]
	v_mfma_f32_16x16x32_bf16 v[102:105], v[164:167], v[188:191], v[102:105]
	v_mfma_f32_16x16x32_bf16 v[98:101], v[172:175], v[188:191], v[98:101]
	v_mfma_f32_16x16x32_bf16 v[86:89], v[164:167], v[196:199], v[86:89]
	v_mfma_f32_16x16x32_bf16 v[82:85], v[172:175], v[196:199], v[82:85]
	v_mfma_f32_16x16x32_bf16 v[70:73], v[164:167], v[204:207], v[70:73]
	v_mfma_f32_16x16x32_bf16 v[66:69], v[172:175], v[204:207], v[66:69]
	v_mfma_f32_16x16x32_bf16 v[118:121], v[168:171], v[184:187], v[118:121]
	v_mfma_f32_16x16x32_bf16 v[114:117], v[176:179], v[184:187], v[114:117]
	v_mfma_f32_16x16x32_bf16 v[102:105], v[168:171], v[192:195], v[102:105]
	v_mfma_f32_16x16x32_bf16 v[98:101], v[176:179], v[192:195], v[98:101]
	v_mfma_f32_16x16x32_bf16 v[86:89], v[168:171], v[200:203], v[86:89]
	v_mfma_f32_16x16x32_bf16 v[82:85], v[176:179], v[200:203], v[82:85]
	v_mfma_f32_16x16x32_bf16 v[70:73], v[168:171], v[208:211], v[70:73]
	v_mfma_f32_16x16x32_bf16 v[66:69], v[176:179], v[208:211], v[66:69]
	s_setprio 0
	s_barrier
	s_add_i32 s38, s78, s49
	v_lshl_add_u64 v[148:149], s[26:27], 0, v[0:1]
	s_mov_b32 m0, s38
	ds_read_b128 v[180:183], v253 offset:16384
	ds_read_b128 v[184:187], v253 offset:17408
	ds_read_b128 v[188:191], v253 offset:18432
	ds_read_b128 v[192:195], v253 offset:19456
	ds_read_b128 v[196:199], v253 offset:20480
	ds_read_b128 v[200:203], v253 offset:21504
	ds_read_b128 v[204:207], v253 offset:22528
	ds_read_b128 v[208:211], v253 offset:23552
	global_load_lds_dwordx4 v[148:149], off
	s_add_i32 m0, s38, 0x2000
	s_add_u32 s38, s26, 0xb0000
	v_lshl_add_u64 v[150:151], s[26:27], 0, v[134:135]
	s_addc_u32 s39, s27, 0
	s_add_i32 s78, s79, s49
	global_load_lds_dwordx4 v[150:151], off
	v_lshl_add_u64 v[212:213], s[38:39], 0, v[0:1]
	s_mov_b32 m0, s78
	v_lshl_add_u64 v[214:215], s[72:73], 0, v[132:133]
	global_load_lds_dwordx4 v[212:213], off
	s_add_i32 m0, s78, 0x2000
	v_lshl_add_u64 v[212:213], s[38:39], 0, v[134:135]
	global_load_lds_dwordx4 v[212:213], off
	s_mov_b32 m0, s50
	v_lshl_add_u64 v[212:213], s[72:73], 0, v[130:131]
	global_load_lds_dwordx4 v[212:213], off
	s_mov_b32 m0, s51
	s_nop 0
	global_load_lds_dwordx4 v[214:215], off
	s_waitcnt vmcnt(8)
	s_waitcnt lgkmcnt(0)
	s_barrier
	s_setprio 1
	v_mfma_f32_16x16x32_bf16 v[62:65], v[140:143], v[180:183], v[62:65]
	v_mfma_f32_16x16x32_bf16 v[58:61], v[156:159], v[180:183], v[58:61]
	v_mfma_f32_16x16x32_bf16 v[46:49], v[140:143], v[188:191], v[46:49]
	v_mfma_f32_16x16x32_bf16 v[42:45], v[156:159], v[188:191], v[42:45]
	v_mfma_f32_16x16x32_bf16 v[30:33], v[140:143], v[196:199], v[30:33]
	v_mfma_f32_16x16x32_bf16 v[26:29], v[156:159], v[196:199], v[26:29]
	v_mfma_f32_16x16x32_bf16 v[14:17], v[140:143], v[204:207], v[14:17]
	v_mfma_f32_16x16x32_bf16 v[10:13], v[156:159], v[204:207], v[10:13]
	v_mfma_f32_16x16x32_bf16 v[62:65], v[144:147], v[184:187], v[62:65]
	v_mfma_f32_16x16x32_bf16 v[58:61], v[160:163], v[184:187], v[58:61]
	v_mfma_f32_16x16x32_bf16 v[46:49], v[144:147], v[192:195], v[46:49]
	v_mfma_f32_16x16x32_bf16 v[42:45], v[160:163], v[192:195], v[42:45]
	v_mfma_f32_16x16x32_bf16 v[30:33], v[144:147], v[200:203], v[30:33]
	v_mfma_f32_16x16x32_bf16 v[26:29], v[160:163], v[200:203], v[26:29]
	v_mfma_f32_16x16x32_bf16 v[14:17], v[144:147], v[208:211], v[14:17]
	v_mfma_f32_16x16x32_bf16 v[10:13], v[160:163], v[208:211], v[10:13]
	v_mfma_f32_16x16x32_bf16 v[54:57], v[164:167], v[180:183], v[54:57]
	v_mfma_f32_16x16x32_bf16 v[50:53], v[172:175], v[180:183], v[50:53]
	v_mfma_f32_16x16x32_bf16 v[38:41], v[164:167], v[188:191], v[38:41]
	v_mfma_f32_16x16x32_bf16 v[34:37], v[172:175], v[188:191], v[34:37]
	v_mfma_f32_16x16x32_bf16 v[22:25], v[164:167], v[196:199], v[22:25]
	v_mfma_f32_16x16x32_bf16 v[18:21], v[172:175], v[196:199], v[18:21]
	v_mfma_f32_16x16x32_bf16 v[6:9], v[164:167], v[204:207], v[6:9]
	v_mfma_f32_16x16x32_bf16 v[2:5], v[172:175], v[204:207], v[2:5]
	v_mfma_f32_16x16x32_bf16 v[54:57], v[168:171], v[184:187], v[54:57]
	v_mfma_f32_16x16x32_bf16 v[50:53], v[176:179], v[184:187], v[50:53]
	v_mfma_f32_16x16x32_bf16 v[38:41], v[168:171], v[192:195], v[38:41]
	v_mfma_f32_16x16x32_bf16 v[34:37], v[176:179], v[192:195], v[34:37]
	v_mfma_f32_16x16x32_bf16 v[22:25], v[168:171], v[200:203], v[22:25]
	v_mfma_f32_16x16x32_bf16 v[18:21], v[176:179], v[200:203], v[18:21]
	v_mfma_f32_16x16x32_bf16 v[6:9], v[168:171], v[208:211], v[6:9]
	v_mfma_f32_16x16x32_bf16 v[2:5], v[176:179], v[208:211], v[2:5]
	s_setprio 0
	s_barrier
	s_add_i32 s78, 0, 0x18000
	s_add_i32 s79, 0, 0x1c000
	v_add_u32_e32 v160, s78, v251
	v_add_u32_e32 v176, s79, v251
	ds_read_b128 v[140:143], v160
	ds_read_b128 v[144:147], v160 offset:1024
	ds_read_b128 v[156:159], v160 offset:2048
	ds_read_b128 v[160:163], v160 offset:3072
	ds_read_b128 v[164:167], v176
	ds_read_b128 v[168:171], v176 offset:1024
	ds_read_b128 v[172:175], v176 offset:2048
	ds_read_b128 v[176:179], v176 offset:3072
	s_add_u32 s38, s72, 0xb0000
	s_addc_u32 s39, s73, 0
	s_mov_b32 m0, s52
	v_lshl_add_u64 v[216:217], s[38:39], 0, v[130:131]
	ds_read_b128 v[180:183], v253 offset:32768
	ds_read_b128 v[184:187], v253 offset:33792
	ds_read_b128 v[188:191], v253 offset:34816
	ds_read_b128 v[192:195], v253 offset:35840
	ds_read_b128 v[196:199], v253 offset:36864
	ds_read_b128 v[200:203], v253 offset:37888
	ds_read_b128 v[204:207], v253 offset:38912
	ds_read_b128 v[208:211], v253 offset:39936
	global_load_lds_dwordx4 v[216:217], off
	s_mov_b32 m0, s53
	v_lshl_add_u64 v[216:217], s[38:39], 0, v[132:133]
	global_load_lds_dwordx4 v[216:217], off
	s_waitcnt vmcnt(8)
	s_waitcnt lgkmcnt(0)
	s_barrier
	s_setprio 1
	v_mfma_f32_16x16x32_bf16 v[126:129], v[140:143], v[180:183], v[126:129]
	v_mfma_f32_16x16x32_bf16 v[122:125], v[156:159], v[180:183], v[122:125]
	v_mfma_f32_16x16x32_bf16 v[110:113], v[140:143], v[188:191], v[110:113]
	v_mfma_f32_16x16x32_bf16 v[106:109], v[156:159], v[188:191], v[106:109]
	v_mfma_f32_16x16x32_bf16 v[94:97], v[140:143], v[196:199], v[94:97]
	v_mfma_f32_16x16x32_bf16 v[90:93], v[156:159], v[196:199], v[90:93]
	v_mfma_f32_16x16x32_bf16 v[78:81], v[140:143], v[204:207], v[78:81]
	v_mfma_f32_16x16x32_bf16 v[74:77], v[156:159], v[204:207], v[74:77]
	v_mfma_f32_16x16x32_bf16 v[126:129], v[144:147], v[184:187], v[126:129]
	v_mfma_f32_16x16x32_bf16 v[122:125], v[160:163], v[184:187], v[122:125]
	v_mfma_f32_16x16x32_bf16 v[110:113], v[144:147], v[192:195], v[110:113]
	v_mfma_f32_16x16x32_bf16 v[106:109], v[160:163], v[192:195], v[106:109]
	v_mfma_f32_16x16x32_bf16 v[94:97], v[144:147], v[200:203], v[94:97]
	v_mfma_f32_16x16x32_bf16 v[90:93], v[160:163], v[200:203], v[90:93]
	v_mfma_f32_16x16x32_bf16 v[78:81], v[144:147], v[208:211], v[78:81]
	v_mfma_f32_16x16x32_bf16 v[74:77], v[160:163], v[208:211], v[74:77]
	v_mfma_f32_16x16x32_bf16 v[118:121], v[164:167], v[180:183], v[118:121]
	v_mfma_f32_16x16x32_bf16 v[114:117], v[172:175], v[180:183], v[114:117]
	v_mfma_f32_16x16x32_bf16 v[102:105], v[164:167], v[188:191], v[102:105]
	v_mfma_f32_16x16x32_bf16 v[98:101], v[172:175], v[188:191], v[98:101]
	v_mfma_f32_16x16x32_bf16 v[86:89], v[164:167], v[196:199], v[86:89]
	v_mfma_f32_16x16x32_bf16 v[82:85], v[172:175], v[196:199], v[82:85]
	v_mfma_f32_16x16x32_bf16 v[70:73], v[164:167], v[204:207], v[70:73]
	v_mfma_f32_16x16x32_bf16 v[66:69], v[172:175], v[204:207], v[66:69]
	v_mfma_f32_16x16x32_bf16 v[118:121], v[168:171], v[184:187], v[118:121]
	v_mfma_f32_16x16x32_bf16 v[114:117], v[176:179], v[184:187], v[114:117]
	v_mfma_f32_16x16x32_bf16 v[102:105], v[168:171], v[192:195], v[102:105]
	v_mfma_f32_16x16x32_bf16 v[98:101], v[176:179], v[192:195], v[98:101]
	v_mfma_f32_16x16x32_bf16 v[86:89], v[168:171], v[200:203], v[86:89]
	v_mfma_f32_16x16x32_bf16 v[82:85], v[176:179], v[200:203], v[82:85]
	v_mfma_f32_16x16x32_bf16 v[70:73], v[168:171], v[208:211], v[70:73]
	v_mfma_f32_16x16x32_bf16 v[66:69], v[176:179], v[208:211], v[66:69]
	s_setprio 0
	s_barrier
	s_add_i32 s38, s78, s49
	v_lshl_add_u64 v[148:149], v[148:149], 0, s[70:71]
	s_mov_b32 m0, s38
	ds_read_b128 v[180:183], v253 offset:49152
	ds_read_b128 v[184:187], v253 offset:50176
	ds_read_b128 v[188:191], v253 offset:51200
	ds_read_b128 v[192:195], v253 offset:52224
	ds_read_b128 v[196:199], v253 offset:53248
	ds_read_b128 v[200:203], v253 offset:54272
	ds_read_b128 v[204:207], v253 offset:55296
	ds_read_b128 v[208:211], v253 offset:56320
	global_load_lds_dwordx4 v[148:149], off
	s_add_i32 m0, s38, 0x2000
	s_add_u32 s26, s26, 0xb0080
	v_lshl_add_u64 v[148:149], v[150:151], 0, s[70:71]
	s_addc_u32 s27, s27, 0
	s_add_i32 s38, s79, s49
	global_load_lds_dwordx4 v[148:149], off
	s_mov_b32 m0, s38
	v_lshl_add_u64 v[148:149], s[26:27], 0, v[0:1]
	global_load_lds_dwordx4 v[148:149], off
	s_add_i32 m0, s38, 0x2000
	v_lshl_add_u64 v[148:149], s[26:27], 0, v[134:135]
	global_load_lds_dwordx4 v[148:149], off
	s_mov_b32 m0, s74
	v_lshl_add_u64 v[148:149], v[212:213], 0, s[70:71]
	global_load_lds_dwordx4 v[148:149], off
	s_mov_b32 m0, s75
	v_lshl_add_u64 v[148:149], v[214:215], 0, s[70:71]
	global_load_lds_dwordx4 v[148:149], off
	s_waitcnt vmcnt(8)
	s_waitcnt lgkmcnt(0)
	s_barrier
	s_setprio 1
	v_mfma_f32_16x16x32_bf16 v[62:65], v[140:143], v[180:183], v[62:65]
	v_mfma_f32_16x16x32_bf16 v[58:61], v[156:159], v[180:183], v[58:61]
	v_mfma_f32_16x16x32_bf16 v[46:49], v[140:143], v[188:191], v[46:49]
	v_mfma_f32_16x16x32_bf16 v[42:45], v[156:159], v[188:191], v[42:45]
	v_mfma_f32_16x16x32_bf16 v[30:33], v[140:143], v[196:199], v[30:33]
	v_mfma_f32_16x16x32_bf16 v[26:29], v[156:159], v[196:199], v[26:29]
	v_mfma_f32_16x16x32_bf16 v[14:17], v[140:143], v[204:207], v[14:17]
	v_mfma_f32_16x16x32_bf16 v[10:13], v[156:159], v[204:207], v[10:13]
	v_mfma_f32_16x16x32_bf16 v[62:65], v[144:147], v[184:187], v[62:65]
	v_mfma_f32_16x16x32_bf16 v[58:61], v[160:163], v[184:187], v[58:61]
	v_mfma_f32_16x16x32_bf16 v[46:49], v[144:147], v[192:195], v[46:49]
	v_mfma_f32_16x16x32_bf16 v[42:45], v[160:163], v[192:195], v[42:45]
	v_mfma_f32_16x16x32_bf16 v[30:33], v[144:147], v[200:203], v[30:33]
	v_mfma_f32_16x16x32_bf16 v[26:29], v[160:163], v[200:203], v[26:29]
	v_mfma_f32_16x16x32_bf16 v[14:17], v[144:147], v[208:211], v[14:17]
	v_mfma_f32_16x16x32_bf16 v[10:13], v[160:163], v[208:211], v[10:13]
	v_mfma_f32_16x16x32_bf16 v[54:57], v[164:167], v[180:183], v[54:57]
	v_mfma_f32_16x16x32_bf16 v[50:53], v[172:175], v[180:183], v[50:53]
	v_mfma_f32_16x16x32_bf16 v[38:41], v[164:167], v[188:191], v[38:41]
	v_mfma_f32_16x16x32_bf16 v[34:37], v[172:175], v[188:191], v[34:37]
	v_mfma_f32_16x16x32_bf16 v[22:25], v[164:167], v[196:199], v[22:25]
	v_mfma_f32_16x16x32_bf16 v[18:21], v[172:175], v[196:199], v[18:21]
	v_mfma_f32_16x16x32_bf16 v[6:9], v[164:167], v[204:207], v[6:9]
	v_mfma_f32_16x16x32_bf16 v[2:5], v[172:175], v[204:207], v[2:5]
	v_mfma_f32_16x16x32_bf16 v[54:57], v[168:171], v[184:187], v[54:57]
	v_mfma_f32_16x16x32_bf16 v[50:53], v[176:179], v[184:187], v[50:53]
	v_mfma_f32_16x16x32_bf16 v[38:41], v[168:171], v[192:195], v[38:41]
	v_mfma_f32_16x16x32_bf16 v[34:37], v[176:179], v[192:195], v[34:37]
	v_mfma_f32_16x16x32_bf16 v[22:25], v[168:171], v[200:203], v[22:25]
	v_mfma_f32_16x16x32_bf16 v[18:21], v[176:179], v[200:203], v[18:21]
	v_mfma_f32_16x16x32_bf16 v[6:9], v[168:171], v[208:211], v[6:9]
	v_mfma_f32_16x16x32_bf16 v[2:5], v[176:179], v[208:211], v[2:5]
	s_setprio 0
	s_barrier
	s_add_u32 vcc_lo, vcc_lo, 0x100
	s_addc_u32 vcc_hi, vcc_hi, 0
	s_cmp_ge_u32 s9, s28
	s_mov_b64 s[38:39], s[60:61]
	s_mov_b32 s26, s9
	s_cbranch_scc0 .LBB0_1000
	s_and_b64 vcc, exec, s[22:23]
	s_cbranch_vccz .LBB0_1003

.LBB0_1054:
	s_add_i32 s96, s26, 2
	s_add_u32 s36, s24, 0x100
	s_addc_u32 s37, s25, 0
	s_add_i32 s9, 0, 0x10000
	s_cmp_eq_u32 s93, s26
	s_cselect_b32 s39, s15, s37
	s_cselect_b32 s38, s14, s36
	v_add_u32_e32 v148, s9, v177
	s_cselect_b32 s27, s23, s95
	s_cselect_b32 s26, s22, s94
	s_add_i32 s78, 0, 0x14000
	ds_read_b128 v[140:143], v148
	ds_read_b128 v[144:147], v148 offset:1024
	ds_read_b128 v[156:159], v148 offset:2048
	ds_read_b128 v[160:163], v148 offset:3072
	v_add_u32_e32 v148, s78, v177
	ds_read_b128 v[164:167], v148
	ds_read_b128 v[168:171], v148 offset:1024
	ds_read_b128 v[172:175], v148 offset:2048
	ds_read_b128 v[180:183], v148 offset:3072
	v_lshl_add_u64 v[148:149], s[24:25], 0, v[136:137]
	s_add_i32 m0, s29, 0xc000
	ds_read_b128 v[184:187], v179
	ds_read_b128 v[188:191], v179 offset:1024
	ds_read_b128 v[192:195], v179 offset:2048
	ds_read_b128 v[196:199], v179 offset:3072
	ds_read_b128 v[200:203], v179 offset:4096
	ds_read_b128 v[204:207], v179 offset:5120
	ds_read_b128 v[208:211], v179 offset:6144
	ds_read_b128 v[212:215], v179 offset:7168
	global_load_lds_dwordx4 v[148:149], off
	s_add_i32 m0, s29, 0xe000
	v_lshl_add_u64 v[148:149], s[24:25], 0, v[138:139]
	global_load_lds_dwordx4 v[148:149], off
	s_waitcnt vmcnt(8)
	s_waitcnt lgkmcnt(0)
	s_barrier
	s_setprio 1
	v_mfma_f32_16x16x32_bf16 v[126:129], v[140:143], v[184:187], v[126:129]
	v_mfma_f32_16x16x32_bf16 v[122:125], v[156:159], v[184:187], v[122:125]
	v_mfma_f32_16x16x32_bf16 v[110:113], v[140:143], v[192:195], v[110:113]
	v_mfma_f32_16x16x32_bf16 v[106:109], v[156:159], v[192:195], v[106:109]
	v_mfma_f32_16x16x32_bf16 v[94:97], v[140:143], v[200:203], v[94:97]
	v_mfma_f32_16x16x32_bf16 v[90:93], v[156:159], v[200:203], v[90:93]
	v_mfma_f32_16x16x32_bf16 v[78:81], v[140:143], v[208:211], v[78:81]
	v_mfma_f32_16x16x32_bf16 v[74:77], v[156:159], v[208:211], v[74:77]
	v_mfma_f32_16x16x32_bf16 v[126:129], v[144:147], v[188:191], v[126:129]
	v_mfma_f32_16x16x32_bf16 v[122:125], v[160:163], v[188:191], v[122:125]
	v_mfma_f32_16x16x32_bf16 v[110:113], v[144:147], v[196:199], v[110:113]
	v_mfma_f32_16x16x32_bf16 v[106:109], v[160:163], v[196:199], v[106:109]
	v_mfma_f32_16x16x32_bf16 v[94:97], v[144:147], v[204:207], v[94:97]
	v_mfma_f32_16x16x32_bf16 v[90:93], v[160:163], v[204:207], v[90:93]
	v_mfma_f32_16x16x32_bf16 v[78:81], v[144:147], v[212:215], v[78:81]
	v_mfma_f32_16x16x32_bf16 v[74:77], v[160:163], v[212:215], v[74:77]
	v_mfma_f32_16x16x32_bf16 v[118:121], v[164:167], v[184:187], v[118:121]
	v_mfma_f32_16x16x32_bf16 v[114:117], v[172:175], v[184:187], v[114:117]
	v_mfma_f32_16x16x32_bf16 v[102:105], v[164:167], v[192:195], v[102:105]
	v_mfma_f32_16x16x32_bf16 v[98:101], v[172:175], v[192:195], v[98:101]
	v_mfma_f32_16x16x32_bf16 v[86:89], v[164:167], v[200:203], v[86:89]
	v_mfma_f32_16x16x32_bf16 v[82:85], v[172:175], v[200:203], v[82:85]
	v_mfma_f32_16x16x32_bf16 v[70:73], v[164:167], v[208:211], v[70:73]
	v_mfma_f32_16x16x32_bf16 v[66:69], v[172:175], v[208:211], v[66:69]
	v_mfma_f32_16x16x32_bf16 v[118:121], v[168:171], v[188:191], v[118:121]
	v_mfma_f32_16x16x32_bf16 v[114:117], v[180:183], v[188:191], v[114:117]
	v_mfma_f32_16x16x32_bf16 v[102:105], v[168:171], v[196:199], v[102:105]
	v_mfma_f32_16x16x32_bf16 v[98:101], v[180:183], v[196:199], v[98:101]
	v_mfma_f32_16x16x32_bf16 v[86:89], v[168:171], v[204:207], v[86:89]
	v_mfma_f32_16x16x32_bf16 v[82:85], v[180:183], v[204:207], v[82:85]
	v_mfma_f32_16x16x32_bf16 v[70:73], v[168:171], v[212:215], v[70:73]
	v_mfma_f32_16x16x32_bf16 v[66:69], v[180:183], v[212:215], v[66:69]
	s_setprio 0
	s_barrier
	s_add_i32 s9, s9, s28
	v_lshl_add_u64 v[148:149], s[26:27], 0, v[0:1]
	s_mov_b32 m0, s9
	ds_read_b128 v[184:187], v179 offset:16384
	ds_read_b128 v[188:191], v179 offset:17408
	ds_read_b128 v[192:195], v179 offset:18432
	ds_read_b128 v[196:199], v179 offset:19456
	ds_read_b128 v[200:203], v179 offset:20480
	ds_read_b128 v[204:207], v179 offset:21504
	ds_read_b128 v[208:211], v179 offset:22528
	ds_read_b128 v[212:215], v179 offset:23552
	global_load_lds_dwordx4 v[148:149], off
	s_add_i32 m0, s9, 0x2000
	s_add_u32 s24, s26, 0xb0000
	v_lshl_add_u64 v[150:151], s[26:27], 0, v[134:135]
	s_addc_u32 s25, s27, 0
	s_add_i32 s9, s78, s28
	global_load_lds_dwordx4 v[150:151], off
	v_lshl_add_u64 v[216:217], s[24:25], 0, v[0:1]
	s_mov_b32 m0, s9
	v_lshl_add_u64 v[218:219], s[38:39], 0, v[132:133]
	global_load_lds_dwordx4 v[216:217], off
	s_add_i32 m0, s9, 0x2000
	v_lshl_add_u64 v[216:217], s[24:25], 0, v[134:135]
	global_load_lds_dwordx4 v[216:217], off
	s_mov_b32 m0, s29
	v_lshl_add_u64 v[216:217], s[38:39], 0, v[130:131]
	global_load_lds_dwordx4 v[216:217], off
	s_mov_b32 m0, s49
	s_nop 0
	global_load_lds_dwordx4 v[218:219], off
	s_waitcnt vmcnt(8)
	s_waitcnt lgkmcnt(0)
	s_barrier
	s_setprio 1
	v_mfma_f32_16x16x32_bf16 v[62:65], v[140:143], v[184:187], v[62:65]
	v_mfma_f32_16x16x32_bf16 v[58:61], v[156:159], v[184:187], v[58:61]
	v_mfma_f32_16x16x32_bf16 v[46:49], v[140:143], v[192:195], v[46:49]
	v_mfma_f32_16x16x32_bf16 v[42:45], v[156:159], v[192:195], v[42:45]
	v_mfma_f32_16x16x32_bf16 v[30:33], v[140:143], v[200:203], v[30:33]
	v_mfma_f32_16x16x32_bf16 v[26:29], v[156:159], v[200:203], v[26:29]
	v_mfma_f32_16x16x32_bf16 v[14:17], v[140:143], v[208:211], v[14:17]
	v_mfma_f32_16x16x32_bf16 v[10:13], v[156:159], v[208:211], v[10:13]
	v_mfma_f32_16x16x32_bf16 v[62:65], v[144:147], v[188:191], v[62:65]
	v_mfma_f32_16x16x32_bf16 v[58:61], v[160:163], v[188:191], v[58:61]
	v_mfma_f32_16x16x32_bf16 v[46:49], v[144:147], v[196:199], v[46:49]
	v_mfma_f32_16x16x32_bf16 v[42:45], v[160:163], v[196:199], v[42:45]
	v_mfma_f32_16x16x32_bf16 v[30:33], v[144:147], v[204:207], v[30:33]
	v_mfma_f32_16x16x32_bf16 v[26:29], v[160:163], v[204:207], v[26:29]
	v_mfma_f32_16x16x32_bf16 v[14:17], v[144:147], v[212:215], v[14:17]
	v_mfma_f32_16x16x32_bf16 v[10:13], v[160:163], v[212:215], v[10:13]
	v_mfma_f32_16x16x32_bf16 v[54:57], v[164:167], v[184:187], v[54:57]
	v_mfma_f32_16x16x32_bf16 v[50:53], v[172:175], v[184:187], v[50:53]
	v_mfma_f32_16x16x32_bf16 v[38:41], v[164:167], v[192:195], v[38:41]
	v_mfma_f32_16x16x32_bf16 v[34:37], v[172:175], v[192:195], v[34:37]
	v_mfma_f32_16x16x32_bf16 v[22:25], v[164:167], v[200:203], v[22:25]
	v_mfma_f32_16x16x32_bf16 v[18:21], v[172:175], v[200:203], v[18:21]
	v_mfma_f32_16x16x32_bf16 v[6:9], v[164:167], v[208:211], v[6:9]
	v_mfma_f32_16x16x32_bf16 v[2:5], v[172:175], v[208:211], v[2:5]
	v_mfma_f32_16x16x32_bf16 v[54:57], v[168:171], v[188:191], v[54:57]
	v_mfma_f32_16x16x32_bf16 v[50:53], v[180:183], v[188:191], v[50:53]
	v_mfma_f32_16x16x32_bf16 v[38:41], v[168:171], v[196:199], v[38:41]
	v_mfma_f32_16x16x32_bf16 v[34:37], v[180:183], v[196:199], v[34:37]
	v_mfma_f32_16x16x32_bf16 v[22:25], v[168:171], v[204:207], v[22:25]
	v_mfma_f32_16x16x32_bf16 v[18:21], v[180:183], v[204:207], v[18:21]
	v_mfma_f32_16x16x32_bf16 v[6:9], v[168:171], v[212:215], v[6:9]
	v_mfma_f32_16x16x32_bf16 v[2:5], v[180:183], v[212:215], v[2:5]
	s_setprio 0
	s_barrier
	s_add_i32 s9, 0, 0x18000
	s_add_i32 s78, 0, 0x1c000
	v_add_u32_e32 v160, s9, v177
	v_add_u32_e32 v180, s78, v177
	ds_read_b128 v[140:143], v160
	ds_read_b128 v[144:147], v160 offset:1024
	ds_read_b128 v[156:159], v160 offset:2048
	ds_read_b128 v[160:163], v160 offset:3072
	ds_read_b128 v[164:167], v180
	ds_read_b128 v[168:171], v180 offset:1024
	ds_read_b128 v[172:175], v180 offset:2048
	ds_read_b128 v[180:183], v180 offset:3072
	s_add_u32 s24, s38, 0xb0000
	s_addc_u32 s25, s39, 0
	s_mov_b32 m0, s50
	v_lshl_add_u64 v[220:221], s[24:25], 0, v[130:131]
	ds_read_b128 v[184:187], v179 offset:32768
	ds_read_b128 v[188:191], v179 offset:33792
	ds_read_b128 v[192:195], v179 offset:34816
	ds_read_b128 v[196:199], v179 offset:35840
	ds_read_b128 v[200:203], v179 offset:36864
	ds_read_b128 v[204:207], v179 offset:37888
	ds_read_b128 v[208:211], v179 offset:38912
	ds_read_b128 v[212:215], v179 offset:39936
	global_load_lds_dwordx4 v[220:221], off
	s_mov_b32 m0, s51
	v_lshl_add_u64 v[220:221], s[24:25], 0, v[132:133]
	global_load_lds_dwordx4 v[220:221], off
	s_waitcnt vmcnt(8)
	s_waitcnt lgkmcnt(0)
	s_barrier
	s_setprio 1
	v_mfma_f32_16x16x32_bf16 v[126:129], v[140:143], v[184:187], v[126:129]
	v_mfma_f32_16x16x32_bf16 v[122:125], v[156:159], v[184:187], v[122:125]
	v_mfma_f32_16x16x32_bf16 v[110:113], v[140:143], v[192:195], v[110:113]
	v_mfma_f32_16x16x32_bf16 v[106:109], v[156:159], v[192:195], v[106:109]
	v_mfma_f32_16x16x32_bf16 v[94:97], v[140:143], v[200:203], v[94:97]
	v_mfma_f32_16x16x32_bf16 v[90:93], v[156:159], v[200:203], v[90:93]
	v_mfma_f32_16x16x32_bf16 v[78:81], v[140:143], v[208:211], v[78:81]
	v_mfma_f32_16x16x32_bf16 v[74:77], v[156:159], v[208:211], v[74:77]
	v_mfma_f32_16x16x32_bf16 v[126:129], v[144:147], v[188:191], v[126:129]
	v_mfma_f32_16x16x32_bf16 v[122:125], v[160:163], v[188:191], v[122:125]
	v_mfma_f32_16x16x32_bf16 v[110:113], v[144:147], v[196:199], v[110:113]
	v_mfma_f32_16x16x32_bf16 v[106:109], v[160:163], v[196:199], v[106:109]
	v_mfma_f32_16x16x32_bf16 v[94:97], v[144:147], v[204:207], v[94:97]
	v_mfma_f32_16x16x32_bf16 v[90:93], v[160:163], v[204:207], v[90:93]
	v_mfma_f32_16x16x32_bf16 v[78:81], v[144:147], v[212:215], v[78:81]
	v_mfma_f32_16x16x32_bf16 v[74:77], v[160:163], v[212:215], v[74:77]
	v_mfma_f32_16x16x32_bf16 v[118:121], v[164:167], v[184:187], v[118:121]
	v_mfma_f32_16x16x32_bf16 v[114:117], v[172:175], v[184:187], v[114:117]
	v_mfma_f32_16x16x32_bf16 v[102:105], v[164:167], v[192:195], v[102:105]
	v_mfma_f32_16x16x32_bf16 v[98:101], v[172:175], v[192:195], v[98:101]
	v_mfma_f32_16x16x32_bf16 v[86:89], v[164:167], v[200:203], v[86:89]
	v_mfma_f32_16x16x32_bf16 v[82:85], v[172:175], v[200:203], v[82:85]
	v_mfma_f32_16x16x32_bf16 v[70:73], v[164:167], v[208:211], v[70:73]
	v_mfma_f32_16x16x32_bf16 v[66:69], v[172:175], v[208:211], v[66:69]
	v_mfma_f32_16x16x32_bf16 v[118:121], v[168:171], v[188:191], v[118:121]
	v_mfma_f32_16x16x32_bf16 v[114:117], v[180:183], v[188:191], v[114:117]
	v_mfma_f32_16x16x32_bf16 v[102:105], v[168:171], v[196:199], v[102:105]
	v_mfma_f32_16x16x32_bf16 v[98:101], v[180:183], v[196:199], v[98:101]
	v_mfma_f32_16x16x32_bf16 v[86:89], v[168:171], v[204:207], v[86:89]
	v_mfma_f32_16x16x32_bf16 v[82:85], v[180:183], v[204:207], v[82:85]
	v_mfma_f32_16x16x32_bf16 v[70:73], v[168:171], v[212:215], v[70:73]
	v_mfma_f32_16x16x32_bf16 v[66:69], v[180:183], v[212:215], v[66:69]
	s_setprio 0
	s_barrier
	s_add_i32 s9, s9, s28
	v_lshl_add_u64 v[148:149], v[148:149], 0, s[70:71]
	s_mov_b32 m0, s9
	ds_read_b128 v[184:187], v179 offset:49152
	ds_read_b128 v[188:191], v179 offset:50176
	ds_read_b128 v[192:195], v179 offset:51200
	ds_read_b128 v[196:199], v179 offset:52224
	ds_read_b128 v[200:203], v179 offset:53248
	ds_read_b128 v[204:207], v179 offset:54272
	ds_read_b128 v[208:211], v179 offset:55296
	ds_read_b128 v[212:215], v179 offset:56320
	global_load_lds_dwordx4 v[148:149], off
	s_add_i32 m0, s9, 0x2000
	s_add_u32 s24, s26, 0xb0080
	v_lshl_add_u64 v[148:149], v[150:151], 0, s[70:71]
	s_addc_u32 s25, s27, 0
	s_add_i32 s9, s78, s28
	global_load_lds_dwordx4 v[148:149], off
	s_mov_b32 m0, s9
	v_lshl_add_u64 v[148:149], s[24:25], 0, v[0:1]
	global_load_lds_dwordx4 v[148:149], off
	s_add_i32 m0, s9, 0x2000
	v_lshl_add_u64 v[148:149], s[24:25], 0, v[134:135]
	global_load_lds_dwordx4 v[148:149], off
	s_mov_b32 m0, s52
	v_lshl_add_u64 v[148:149], v[216:217], 0, s[70:71]
	global_load_lds_dwordx4 v[148:149], off
	s_mov_b32 m0, s53
	v_lshl_add_u64 v[148:149], v[218:219], 0, s[70:71]
	global_load_lds_dwordx4 v[148:149], off
	s_waitcnt vmcnt(8)
	s_waitcnt lgkmcnt(0)
	s_barrier
	s_setprio 1
	v_mfma_f32_16x16x32_bf16 v[62:65], v[140:143], v[184:187], v[62:65]
	v_mfma_f32_16x16x32_bf16 v[58:61], v[156:159], v[184:187], v[58:61]
	v_mfma_f32_16x16x32_bf16 v[46:49], v[140:143], v[192:195], v[46:49]
	v_mfma_f32_16x16x32_bf16 v[42:45], v[156:159], v[192:195], v[42:45]
	v_mfma_f32_16x16x32_bf16 v[30:33], v[140:143], v[200:203], v[30:33]
	v_mfma_f32_16x16x32_bf16 v[26:29], v[156:159], v[200:203], v[26:29]
	v_mfma_f32_16x16x32_bf16 v[14:17], v[140:143], v[208:211], v[14:17]
	v_mfma_f32_16x16x32_bf16 v[10:13], v[156:159], v[208:211], v[10:13]
	v_mfma_f32_16x16x32_bf16 v[62:65], v[144:147], v[188:191], v[62:65]
	v_mfma_f32_16x16x32_bf16 v[58:61], v[160:163], v[188:191], v[58:61]
	v_mfma_f32_16x16x32_bf16 v[46:49], v[144:147], v[196:199], v[46:49]
	v_mfma_f32_16x16x32_bf16 v[42:45], v[160:163], v[196:199], v[42:45]
	v_mfma_f32_16x16x32_bf16 v[30:33], v[144:147], v[204:207], v[30:33]
	v_mfma_f32_16x16x32_bf16 v[26:29], v[160:163], v[204:207], v[26:29]
	v_mfma_f32_16x16x32_bf16 v[14:17], v[144:147], v[212:215], v[14:17]
	v_mfma_f32_16x16x32_bf16 v[10:13], v[160:163], v[212:215], v[10:13]
	v_mfma_f32_16x16x32_bf16 v[54:57], v[164:167], v[184:187], v[54:57]
	v_mfma_f32_16x16x32_bf16 v[50:53], v[172:175], v[184:187], v[50:53]
	v_mfma_f32_16x16x32_bf16 v[38:41], v[164:167], v[192:195], v[38:41]
	v_mfma_f32_16x16x32_bf16 v[34:37], v[172:175], v[192:195], v[34:37]
	v_mfma_f32_16x16x32_bf16 v[22:25], v[164:167], v[200:203], v[22:25]
	v_mfma_f32_16x16x32_bf16 v[18:21], v[172:175], v[200:203], v[18:21]
	v_mfma_f32_16x16x32_bf16 v[6:9], v[164:167], v[208:211], v[6:9]
	v_mfma_f32_16x16x32_bf16 v[2:5], v[172:175], v[208:211], v[2:5]
	v_mfma_f32_16x16x32_bf16 v[54:57], v[168:171], v[188:191], v[54:57]
	v_mfma_f32_16x16x32_bf16 v[50:53], v[180:183], v[188:191], v[50:53]
	v_mfma_f32_16x16x32_bf16 v[38:41], v[168:171], v[196:199], v[38:41]
	v_mfma_f32_16x16x32_bf16 v[34:37], v[180:183], v[196:199], v[34:37]
	v_mfma_f32_16x16x32_bf16 v[22:25], v[168:171], v[204:207], v[22:25]
	v_mfma_f32_16x16x32_bf16 v[18:21], v[180:183], v[204:207], v[18:21]
	v_mfma_f32_16x16x32_bf16 v[6:9], v[168:171], v[212:215], v[6:9]
	v_mfma_f32_16x16x32_bf16 v[2:5], v[180:183], v[212:215], v[2:5]
	s_setprio 0
	s_barrier
	s_add_u32 s94, s94, 0x100
	s_addc_u32 s95, s95, 0
	s_cmp_ge_u32 s96, s92
	s_mov_b64 s[24:25], s[36:37]
	s_mov_b32 s26, s96
	s_cbranch_scc0 .LBB0_1054
	s_and_b64 vcc, exec, s[12:13]
	s_cbranch_vccz .LBB0_1057
